# K/V LDS-DMA issued at the very top of each attention step (right after the leading QK MFMA), +0.5 step prefetch distance; on top of v18
# speedup vs baseline: 1.0071x; 1.0026x over previous
.LBB0_863:
	v_mfma_f32_32x32x16_bf16 v[112:127], v[100:103], v[218:221], 0
	v_lshl_add_u32 v206, s89, 1, v168
	s_add_i32 s88, s87, s35
	v_lshl_add_u64 v[238:239], v[180:181], 0, s[54:55]
	s_mov_b32 s89, m0
	s_mov_b32 m0, s88
	s_nop 0
	global_load_lds_dwordx4 v[238:239], off
	s_mov_b32 m0, s89
	s_lshl_b32 s88, s86, 1
	v_lshl_add_u64 v[238:239], v[178:179], 0, s[54:55]
	s_add_i32 s88, s88, s16
	s_mov_b32 s89, m0
	s_mov_b32 m0, s88
	s_nop 0
	global_load_lds_dwordx4 v[238:239], off
	s_mov_b32 m0, s89
	v_lshl_add_u64 v[238:239], v[176:177], 0, s[54:55]
	s_addk_i32 s88, 0x2000
	s_mov_b32 s89, m0
	s_mov_b32 m0, s88
	s_nop 0
	global_load_lds_dwordx4 v[238:239], off
	s_mov_b32 m0, s89
	ds_read_b64_tr_b16 v[194:195], v206 offset:24576
	ds_read_b64_tr_b16 v[196:197], v206 offset:25088
	v_add_f32_e32 v108, v80, v81
	v_add_f32_e32 v108, v82, v108
	v_add_f32_e32 v108, v83, v108
	v_add_f32_e32 v108, v84, v108
	v_add_f32_e32 v108, v85, v108
	v_cvt_pk_bf16_f32 v156, v80, v81
	v_cvt_pk_bf16_f32 v157, v82, v83
	ds_read_b64_tr_b16 v[80:81], v206 offset:28672
	ds_read_b64_tr_b16 v[82:83], v206 offset:29184
	v_add_f32_e32 v104, v86, v108
	v_add_f32_e32 v104, v87, v104
	v_add_f32_e32 v104, v88, v104
	v_add_f32_e32 v144, v89, v104
	v_mfma_f32_32x32x16_bf16 v[96:111], v[96:99], v[218:221], 0
	v_cvt_pk_bf16_f32 v158, v84, v85
	v_cvt_pk_bf16_f32 v159, v86, v87
	ds_read_b64_tr_b16 v[84:85], v206 offset:25600
	ds_read_b64_tr_b16 v[86:87], v206 offset:26112
	v_add_f32_e32 v144, v90, v144
	v_add_f32_e32 v144, v91, v144
	v_add_f32_e32 v144, v92, v144
	v_add_f32_e32 v144, v93, v144
	v_cvt_pk_bf16_f32 v152, v88, v89
	v_cvt_pk_bf16_f32 v153, v90, v91
	v_mfma_f32_32x32x16_bf16 v[112:127], v[164:167], v[222:225], v[112:127]
	ds_read_b64_tr_b16 v[88:89], v206 offset:29696
	ds_read_b64_tr_b16 v[90:91], v206 offset:30208
	v_add_f32_e32 v144, v94, v144
	v_add_f32_e32 v144, v95, v144
	v_add_f32_e32 v144, v64, v144
	v_add_f32_e32 v144, v65, v144
	v_mfma_f32_32x32x16_bf16 v[96:111], v[160:163], v[222:225], v[96:111]
	v_cvt_pk_bf16_f32 v154, v92, v93
	v_cvt_pk_bf16_f32 v155, v94, v95
	ds_read_b64_tr_b16 v[92:93], v206 offset:26624
	ds_read_b64_tr_b16 v[94:95], v206 offset:27136
	v_add_f32_e32 v144, v66, v144
	v_add_f32_e32 v144, v67, v144
	v_add_f32_e32 v144, v68, v144
	v_add_f32_e32 v144, v69, v144
	v_cvt_pk_bf16_f32 v148, v64, v65
	v_cvt_pk_bf16_f32 v149, v66, v67
	v_mfma_f32_32x32x16_bf16 v[112:127], v[140:143], v[226:229], v[112:127]
	ds_read_b64_tr_b16 v[198:199], v206 offset:30720
	ds_read_b64_tr_b16 v[200:201], v206 offset:31232
	v_add_f32_e32 v140, v70, v144
	v_add_f32_e32 v140, v71, v140
	v_add_f32_e32 v140, v72, v140
	v_add_f32_e32 v140, v73, v140
	v_mfma_f32_32x32x16_bf16 v[96:111], v[136:139], v[226:229], v[96:111]
	v_cvt_pk_bf16_f32 v150, v68, v69
	v_cvt_pk_bf16_f32 v151, v70, v71
	ds_read_b64_tr_b16 v[202:203], v206 offset:27648
	ds_read_b64_tr_b16 v[204:205], v206 offset:28160
	v_add_f32_e32 v68, v74, v140
	v_add_f32_e32 v68, v75, v68
	v_add_f32_e32 v68, v76, v68
	v_add_f32_e32 v68, v77, v68
	v_cvt_pk_bf16_f32 v144, v72, v73
	v_cvt_pk_bf16_f32 v145, v74, v75
	v_mfma_f32_32x32x16_bf16 v[112:127], v[132:135], v[230:233], v[112:127]
	ds_read_b64_tr_b16 v[72:73], v206 offset:31744
	ds_read_b64_tr_b16 v[74:75], v206 offset:32256
	v_add_f32_e32 v68, v78, v68
	v_add_f32_e32 v68, v79, v68
	v_add_f32_e32 v68, 0, v68
	v_cvt_pk_bf16_f32 v146, v76, v77
	v_mfma_f32_32x32x16_bf16 v[96:111], v[128:131], v[230:233], v[96:111]
	v_cvt_pk_bf16_f32 v147, v78, v79
	v_add_f32_e32 v193, v193, v68
	s_waitcnt lgkmcnt(12)
	v_mfma_f32_32x32x16_bf16 v[48:63], v[156:159], v[194:197], v[48:63]
	ds_read_b64_tr_b16 v[76:77], v206 offset:32768
	ds_read_b64_tr_b16 v[78:79], v206 offset:33280
	v_exp_f32_e32 v112, v112
	v_exp_f32_e32 v113, v113
	v_mfma_f32_32x32x16_bf16 v[32:47], v[156:159], v[80:83], v[32:47]
	ds_read_b64_tr_b16 v[194:195], v206 offset:36864
	ds_read_b64_tr_b16 v[196:197], v206 offset:37376
	v_exp_f32_e32 v114, v114
	v_exp_f32_e32 v115, v115
	v_add_u32_e32 v242, s86, v234
	v_add_u32_e32 v243, s86, v235
	v_add_u32_e32 v244, s86, v236
	v_add_u32_e32 v245, s86, v237
	ds_read_b128 v[68:71], v242
	ds_read_b128 v[64:67], v242 offset:4096
	s_waitcnt lgkmcnt(14)
	v_mfma_f32_32x32x16_bf16 v[48:63], v[152:155], v[84:87], v[48:63]
	ds_read_b64_tr_b16 v[80:81], v206 offset:33792
	ds_read_b64_tr_b16 v[82:83], v206 offset:34304
	v_exp_f32_e32 v116, v116
	v_exp_f32_e32 v117, v117
	ds_read_b128 v[164:167], v243
	ds_read_b128 v[140:143], v243 offset:4096
	v_mfma_f32_32x32x16_bf16 v[32:47], v[152:155], v[88:91], v[32:47]
	ds_read_b64_tr_b16 v[84:85], v206 offset:37888
	ds_read_b64_tr_b16 v[86:87], v206 offset:38400
	v_exp_f32_e32 v118, v118
	v_exp_f32_e32 v119, v119
	ds_read_b128 v[160:163], v244
	ds_read_b128 v[132:135], v244 offset:4096
	s_waitcnt lgkmcnt(14)
	v_mfma_f32_32x32x16_bf16 v[48:63], v[148:151], v[92:95], v[48:63]
	ds_read_b64_tr_b16 v[88:89], v206 offset:34816
	ds_read_b64_tr_b16 v[90:91], v206 offset:35328
	v_exp_f32_e32 v120, v120
	v_exp_f32_e32 v121, v121
	ds_read_b128 v[136:139], v245
	ds_read_b128 v[128:131], v245 offset:4096
	v_mfma_f32_32x32x16_bf16 v[32:47], v[148:151], v[198:201], v[32:47]
	ds_read_b64_tr_b16 v[92:93], v206 offset:38912
	ds_read_b64_tr_b16 v[94:95], v206 offset:39424
	v_exp_f32_e32 v122, v122
	v_exp_f32_e32 v123, v123
	s_waitcnt lgkmcnt(14)
	v_mfma_f32_32x32x16_bf16 v[48:63], v[144:147], v[202:205], v[48:63]
	ds_read_b64_tr_b16 v[198:199], v206 offset:35840
	ds_read_b64_tr_b16 v[200:201], v206 offset:36352
	v_exp_f32_e32 v124, v124
	v_exp_f32_e32 v125, v125
	v_mfma_f32_32x32x16_bf16 v[32:47], v[144:147], v[72:75], v[32:47]
	ds_read_b64_tr_b16 v[202:203], v206 offset:39936
	ds_read_b64_tr_b16 v[204:205], v206 offset:40448
	v_exp_f32_e32 v126, v126
	v_exp_f32_e32 v127, v127
	s_waitcnt lgkmcnt(14)
	v_mfma_f32_32x32x16_bf16 v[16:31], v[156:159], v[76:79], v[16:31]
	v_exp_f32_e32 v96, v96
	v_exp_f32_e32 v97, v97
	v_mfma_f32_32x32x16_bf16 v[0:15], v[156:159], v[194:197], v[0:15]
	v_exp_f32_e32 v98, v98
	v_exp_f32_e32 v99, v99
	v_mfma_f32_32x32x16_bf16 v[16:31], v[152:155], v[80:83], v[16:31]
	v_exp_f32_e32 v100, v100
	v_exp_f32_e32 v101, v101
	s_waitcnt lgkmcnt(12)
	v_mfma_f32_32x32x16_bf16 v[0:15], v[152:155], v[84:87], v[0:15]
	v_exp_f32_e32 v102, v102
	v_exp_f32_e32 v103, v103
	s_waitcnt lgkmcnt(8)
	v_mfma_f32_32x32x16_bf16 v[16:31], v[148:151], v[88:91], v[16:31]
	v_exp_f32_e32 v104, v104
	v_exp_f32_e32 v105, v105
	s_waitcnt lgkmcnt(4)
	v_mfma_f32_32x32x16_bf16 v[0:15], v[148:151], v[92:95], v[0:15]
	v_exp_f32_e32 v106, v106
	v_exp_f32_e32 v107, v107
	s_waitcnt lgkmcnt(2)
	v_mfma_f32_32x32x16_bf16 v[16:31], v[144:147], v[198:201], v[16:31]
	v_exp_f32_e32 v108, v108
	v_exp_f32_e32 v109, v109
	s_waitcnt lgkmcnt(0)
	v_mfma_f32_32x32x16_bf16 v[0:15], v[144:147], v[202:205], v[0:15]
	v_exp_f32_e32 v110, v110
	v_exp_f32_e32 v111, v111
	s_waitcnt vmcnt(3) lgkmcnt(0)
	s_barrier
; #define WAIT_BAR(N) asm volatile("s_waitcnt vmcnt(" #N ") lgkmcnt(0)\n\ts_barrier":::"memory")
;   #define RESC() do{ if(!NOMAX&&resc){ asm volatile("s_waitcnt lgkmcnt(0)":::"memory"); \
;       _Pragma("unroll") for(int d_=0;d_<2*VM;++d_) _Pragma("unroll") for(int r=0;r<16;++r)o[d_][r]*=wsf[crow(r,hi)]; } }while(0)
;   #define ROT() do{sl_prev=sl_cur;sl_cur=sl_next;sl_next=(sl_next==(NSLOT-1)*SLOTB)?0:sl_next+SLOTB;}while(0)
; template<int THRL,int VM,bool NOMAX> __device__ __forceinline__ void attn_unit(const bf16*Qb,const bf16*__restrict__ Kh,const bf16*__restrict__ Vh,bf16*Ob,const int NT,const int sp,float*wscr,char*shm){
;     ...
;   int t=1;
;   for(;t+5<NT;t+=2){
;     STEP(pB0,pB1,pA0,pA1,t,true,true,true);     if constexpr(VM==2){WAIT_BAR(3);}else{WAIT_BAR(2);} RESC(); ROT();
;     STEP(pA0,pA1,pB0,pB1,t+1,true,true,true);   if constexpr(VM==2){WAIT_BAR(3);}else{WAIT_BAR(2);} RESC(); ROT();
	v_mfma_f32_32x32x16_bf16 v[80:95], v[68:71], v[218:221], 0
	s_add_i32 s88, s86, 0x2000
	s_cmpk_lg_i32 s86, 0x4000
	s_cselect_b32 s88, s88, 0
	v_lshl_add_u32 v206, s87, 1, v168
	s_add_i32 s87, s86, s35
	s_mov_b32 s89, m0
	s_mov_b32 m0, s87
	s_nop 0
	global_load_lds_dwordx4 v[180:181], off
	s_mov_b32 m0, s89
	s_lshl_b32 s87, s88, 1
	s_add_i32 s87, s87, s16
	s_mov_b32 s89, m0
	s_mov_b32 m0, s87
	s_nop 0
	global_load_lds_dwordx4 v[178:179], off
	s_mov_b32 m0, s89
	s_addk_i32 s87, 0x2000
	s_mov_b32 s89, m0
	s_mov_b32 m0, s87
	s_nop 0
	global_load_lds_dwordx4 v[176:177], off
	s_mov_b32 m0, s89
	ds_read_b64_tr_b16 v[194:195], v206 offset:24576
	ds_read_b64_tr_b16 v[196:197], v206 offset:25088
	v_add_f32_e32 v76, v112, v113
	v_add_f32_e32 v76, v114, v76
	v_add_f32_e32 v76, v115, v76
	v_add_f32_e32 v76, v116, v76
	v_add_f32_e32 v76, v117, v76
	v_cvt_pk_bf16_f32 v156, v112, v113
	v_cvt_pk_bf16_f32 v157, v114, v115
	ds_read_b64_tr_b16 v[112:113], v206 offset:28672
	ds_read_b64_tr_b16 v[114:115], v206 offset:29184
	v_add_f32_e32 v72, v118, v76
	v_add_f32_e32 v72, v119, v72
	v_add_f32_e32 v72, v120, v72
	v_add_f32_e32 v144, v121, v72
	v_mfma_f32_32x32x16_bf16 v[64:79], v[64:67], v[218:221], 0
	v_cvt_pk_bf16_f32 v158, v116, v117
	v_cvt_pk_bf16_f32 v159, v118, v119
	ds_read_b64_tr_b16 v[116:117], v206 offset:25600
	ds_read_b64_tr_b16 v[118:119], v206 offset:26112
	v_add_f32_e32 v144, v122, v144
	v_add_f32_e32 v144, v123, v144
	v_add_f32_e32 v144, v124, v144
	v_add_f32_e32 v144, v125, v144
	v_mfma_f32_32x32x16_bf16 v[80:95], v[164:167], v[222:225], v[80:95]
	v_cvt_pk_bf16_f32 v152, v120, v121
	v_cvt_pk_bf16_f32 v153, v122, v123
	ds_read_b64_tr_b16 v[120:121], v206 offset:29696
	ds_read_b64_tr_b16 v[122:123], v206 offset:30208
	v_add_f32_e32 v144, v126, v144
	v_add_f32_e32 v144, v127, v144
	v_add_f32_e32 v144, v96, v144
	v_add_f32_e32 v144, v97, v144
	v_mfma_f32_32x32x16_bf16 v[64:79], v[140:143], v[222:225], v[64:79]
	v_cvt_pk_bf16_f32 v154, v124, v125
	v_cvt_pk_bf16_f32 v155, v126, v127
	ds_read_b64_tr_b16 v[124:125], v206 offset:26624
	ds_read_b64_tr_b16 v[126:127], v206 offset:27136
	v_add_f32_e32 v144, v98, v144
	v_add_f32_e32 v144, v99, v144
	v_add_f32_e32 v144, v100, v144
	v_add_f32_e32 v144, v101, v144
	v_mfma_f32_32x32x16_bf16 v[80:95], v[160:163], v[226:229], v[80:95]
	v_cvt_pk_bf16_f32 v148, v96, v97
	v_cvt_pk_bf16_f32 v149, v98, v99
	ds_read_b64_tr_b16 v[198:199], v206 offset:30720
	ds_read_b64_tr_b16 v[200:201], v206 offset:31232
	v_add_f32_e32 v140, v102, v144
	v_add_f32_e32 v140, v103, v140
	v_add_f32_e32 v140, v104, v140
	v_add_f32_e32 v140, v105, v140
	v_mfma_f32_32x32x16_bf16 v[64:79], v[132:135], v[226:229], v[64:79]
	v_cvt_pk_bf16_f32 v150, v100, v101
	v_cvt_pk_bf16_f32 v151, v102, v103
	ds_read_b64_tr_b16 v[202:203], v206 offset:27648
	ds_read_b64_tr_b16 v[204:205], v206 offset:28160
	v_add_f32_e32 v100, v106, v140
	v_add_f32_e32 v100, v107, v100
	v_add_f32_e32 v100, v108, v100
	v_add_f32_e32 v100, v109, v100
	v_mfma_f32_32x32x16_bf16 v[80:95], v[136:139], v[230:233], v[80:95]
	v_cvt_pk_bf16_f32 v144, v104, v105
	v_cvt_pk_bf16_f32 v145, v106, v107
	ds_read_b64_tr_b16 v[104:105], v206 offset:31744
	ds_read_b64_tr_b16 v[106:107], v206 offset:32256
	v_add_f32_e32 v100, v110, v100
	v_add_f32_e32 v100, v111, v100
	v_add_f32_e32 v100, 0, v100
	v_cvt_pk_bf16_f32 v146, v108, v109
	v_mfma_f32_32x32x16_bf16 v[64:79], v[128:131], v[230:233], v[64:79]
	v_cvt_pk_bf16_f32 v147, v110, v111
	v_add_f32_e32 v193, v193, v100
	s_waitcnt lgkmcnt(12)
	v_mfma_f32_32x32x16_bf16 v[48:63], v[156:159], v[194:197], v[48:63]
	ds_read_b64_tr_b16 v[108:109], v206 offset:32768
	ds_read_b64_tr_b16 v[110:111], v206 offset:33280
	v_exp_f32_e32 v80, v80
	v_exp_f32_e32 v81, v81
	v_mfma_f32_32x32x16_bf16 v[32:47], v[156:159], v[112:115], v[32:47]
	ds_read_b64_tr_b16 v[194:195], v206 offset:36864
	ds_read_b64_tr_b16 v[196:197], v206 offset:37376
	v_exp_f32_e32 v82, v82
	v_exp_f32_e32 v83, v83
	v_add_u32_e32 v242, s88, v234
	v_add_u32_e32 v243, s88, v235
	v_add_u32_e32 v244, s88, v236
	v_add_u32_e32 v245, s88, v237
	ds_read_b128 v[100:103], v242
	ds_read_b128 v[96:99], v242 offset:4096
	s_waitcnt lgkmcnt(14)
	v_mfma_f32_32x32x16_bf16 v[48:63], v[152:155], v[116:119], v[48:63]
	ds_read_b64_tr_b16 v[112:113], v206 offset:33792
	ds_read_b64_tr_b16 v[114:115], v206 offset:34304
	v_exp_f32_e32 v84, v84
	v_exp_f32_e32 v85, v85
	ds_read_b128 v[164:167], v243
	ds_read_b128 v[160:163], v243 offset:4096
	v_mfma_f32_32x32x16_bf16 v[32:47], v[152:155], v[120:123], v[32:47]
	ds_read_b64_tr_b16 v[116:117], v206 offset:37888
	ds_read_b64_tr_b16 v[118:119], v206 offset:38400
	v_exp_f32_e32 v86, v86
	v_exp_f32_e32 v87, v87
	ds_read_b128 v[140:143], v244
	ds_read_b128 v[136:139], v244 offset:4096
	s_waitcnt lgkmcnt(14)
	v_mfma_f32_32x32x16_bf16 v[48:63], v[148:151], v[124:127], v[48:63]
	ds_read_b64_tr_b16 v[120:121], v206 offset:34816
	ds_read_b64_tr_b16 v[122:123], v206 offset:35328
	v_exp_f32_e32 v88, v88
	v_exp_f32_e32 v89, v89
	ds_read_b128 v[132:135], v245
	ds_read_b128 v[128:131], v245 offset:4096
	v_mfma_f32_32x32x16_bf16 v[32:47], v[148:151], v[198:201], v[32:47]
	ds_read_b64_tr_b16 v[124:125], v206 offset:38912
	ds_read_b64_tr_b16 v[126:127], v206 offset:39424
	v_exp_f32_e32 v90, v90
	v_exp_f32_e32 v91, v91
	s_waitcnt lgkmcnt(14)
	v_mfma_f32_32x32x16_bf16 v[48:63], v[144:147], v[202:205], v[48:63]
	ds_read_b64_tr_b16 v[198:199], v206 offset:35840
	ds_read_b64_tr_b16 v[200:201], v206 offset:36352
	v_exp_f32_e32 v92, v92
	v_exp_f32_e32 v93, v93
	v_mfma_f32_32x32x16_bf16 v[32:47], v[144:147], v[104:107], v[32:47]
	ds_read_b64_tr_b16 v[202:203], v206 offset:39936
	ds_read_b64_tr_b16 v[204:205], v206 offset:40448
	v_exp_f32_e32 v94, v94
	v_exp_f32_e32 v95, v95
	s_waitcnt lgkmcnt(14)
	v_mfma_f32_32x32x16_bf16 v[16:31], v[156:159], v[108:111], v[16:31]
	v_exp_f32_e32 v64, v64
	v_exp_f32_e32 v65, v65
	v_mfma_f32_32x32x16_bf16 v[0:15], v[156:159], v[194:197], v[0:15]
	v_exp_f32_e32 v66, v66
	v_exp_f32_e32 v67, v67
	v_mfma_f32_32x32x16_bf16 v[16:31], v[152:155], v[112:115], v[16:31]
	v_exp_f32_e32 v68, v68
	v_exp_f32_e32 v69, v69
	s_waitcnt lgkmcnt(12)
	v_mfma_f32_32x32x16_bf16 v[0:15], v[152:155], v[116:119], v[0:15]
	v_exp_f32_e32 v70, v70
	v_exp_f32_e32 v71, v71
	s_waitcnt lgkmcnt(8)
	v_mfma_f32_32x32x16_bf16 v[16:31], v[148:151], v[120:123], v[16:31]
	v_exp_f32_e32 v72, v72
	v_exp_f32_e32 v73, v73
	s_waitcnt lgkmcnt(4)
	v_mfma_f32_32x32x16_bf16 v[0:15], v[148:151], v[124:127], v[0:15]
	v_exp_f32_e32 v74, v74
	v_exp_f32_e32 v75, v75
	s_waitcnt lgkmcnt(2)
	v_mfma_f32_32x32x16_bf16 v[16:31], v[144:147], v[198:201], v[16:31]
	v_exp_f32_e32 v76, v76
	v_exp_f32_e32 v77, v77
	s_waitcnt lgkmcnt(0)
	v_mfma_f32_32x32x16_bf16 v[0:15], v[144:147], v[202:205], v[0:15]
	v_exp_f32_e32 v78, v78
	v_exp_f32_e32 v79, v79
	s_add_i32 s90, s88, 0x2000
	s_waitcnt vmcnt(3) lgkmcnt(0)
	s_barrier
; #define WAIT_BAR(N) asm volatile("s_waitcnt vmcnt(" #N ") lgkmcnt(0)\n\ts_barrier":::"memory")
;   #define RESC() do{ if(!NOMAX&&resc){ asm volatile("s_waitcnt lgkmcnt(0)":::"memory"); \
;       _Pragma("unroll") for(int d_=0;d_<2*VM;++d_) _Pragma("unroll") for(int r=0;r<16;++r)o[d_][r]*=wsf[crow(r,hi)]; } }while(0)
;   #define ROT() do{sl_prev=sl_cur;sl_cur=sl_next;sl_next=(sl_next==(NSLOT-1)*SLOTB)?0:sl_next+SLOTB;}while(0)
;   #define ENDW(tt) do{ if((tt)+3<NT){ if constexpr(VM==2){WAIT_BAR(3);}else{WAIT_BAR(2);} } else if((tt)+2<NT){ if constexpr(VM==2){WAIT_BAR(2);}else{WAIT_BAR(1);} } else {WAIT_BAR(0);} }while(0)
; template<int THRL,int VM,bool NOMAX> __device__ __forceinline__ void attn_unit(const bf16*Qb,const bf16*__restrict__ Kh,const bf16*__restrict__ Vh,bf16*Ob,const int NT,const int sp,float*wscr,char*shm){
;     ...
;   int t=1;
;   for(;t+5<NT;t+=2){
;     STEP(pB0,pB1,pA0,pA1,t,true,true,true);     if constexpr(VM==2){WAIT_BAR(3);}else{WAIT_BAR(2);} RESC(); ROT();
;     STEP(pA0,pA1,pB0,pB1,t+1,true,true,true);   if constexpr(VM==2){WAIT_BAR(3);}else{WAIT_BAR(2);} RESC(); ROT();
;   }
;     ...
;   for(;t+1<NT;t+=2){
;     STEP(pB0,pB1,pA0,pA1,t,(t+3<NT),(t+1<NT),(t+1<NT));       ENDW(t);   RESC(); ROT();
	s_cmpk_lg_i32 s88, 0x4000
	s_mov_b32 s89, s86
	s_cselect_b32 s86, s90, 0
	s_add_i32 s85, s85, 2
	v_lshl_add_u64 v[176:177], v[176:177], 0, s[56:57]
	v_lshl_add_u64 v[178:179], v[178:179], 0, s[56:57]
	v_lshl_add_u64 v[180:181], v[180:181], 0, s[56:57]
	s_mov_b32 s87, s88
	s_cmpk_lt_u32 s85, 0x79
	s_cbranch_scc1 .LBB0_863
	s_and_b32 s34, s34, 0x3fffffc0
	s_lshl_b32 s34, s34, 2
	s_add_i32 s34, s34, 0
	s_add_i32 s34, s34, 0x12000
	s_cmp_lg_u32 0, -1
	s_cselect_b32 s85, 0, 0
	s_add_i32 s86, s85, 0x6000
	v_add_u32_e32 v104, s86, v191
	v_add3_u32 v176, v104, v190, v192
	v_add_u32_e32 v177, 0x6000, v168
	ds_read_b64_tr_b16 v[178:179], v168 offset:57344
	ds_read_b64_tr_b16 v[180:181], v168 offset:57856
	v_add_f32_e32 v108, v80, v81
	ds_read_b128 v[104:107], v188
	v_add_f32_e32 v108, v82, v108
	v_add_f32_e32 v108, v83, v108
	v_add_f32_e32 v108, v84, v108
	v_add_f32_e32 v108, v85, v108
	v_cvt_pk_bf16_f32 v156, v80, v81
	v_cvt_pk_bf16_f32 v157, v82, v83
	s_waitcnt lgkmcnt(0)
	v_mfma_f32_32x32x16_bf16 v[112:127], v[100:103], v[104:107], 0
	ds_read_b64_tr_b16 v[80:81], v168 offset:61440
	ds_read_b64_tr_b16 v[82:83], v168 offset:61952
	ds_read_b128 v[100:103], v188
	v_add_f32_e32 v104, v86, v108
	v_add_f32_e32 v104, v87, v104
	v_add_f32_e32 v104, v88, v104
	v_add_f32_e32 v144, v89, v104
	v_cvt_pk_bf16_f32 v158, v84, v85
	v_cvt_pk_bf16_f32 v159, v86, v87
	s_waitcnt lgkmcnt(0)
	v_mfma_f32_32x32x16_bf16 v[96:111], v[96:99], v[100:103], 0
	ds_read_b64_tr_b16 v[84:85], v168 offset:58368
	ds_read_b64_tr_b16 v[86:87], v168 offset:58880
	ds_read_b128 v[194:197], v188 offset:1024
	v_add_f32_e32 v144, v90, v144
	v_add_f32_e32 v144, v91, v144
	v_add_f32_e32 v144, v92, v144
	v_add_f32_e32 v144, v93, v144
	v_cvt_pk_bf16_f32 v152, v88, v89
	v_cvt_pk_bf16_f32 v153, v90, v91
	s_waitcnt lgkmcnt(0)
	v_mfma_f32_32x32x16_bf16 v[112:127], v[164:167], v[194:197], v[112:127]
	ds_read_b64_tr_b16 v[88:89], v168 offset:62464
	ds_read_b64_tr_b16 v[90:91], v168 offset:62976
	ds_read_b128 v[164:167], v188 offset:1024
	v_add_f32_e32 v144, v94, v144
	v_add_f32_e32 v144, v95, v144
	v_add_f32_e32 v144, v64, v144
	v_add_f32_e32 v144, v65, v144
	v_cvt_pk_bf16_f32 v154, v92, v93
	v_cvt_pk_bf16_f32 v155, v94, v95
	s_waitcnt lgkmcnt(0)
	v_mfma_f32_32x32x16_bf16 v[96:111], v[160:163], v[164:167], v[96:111]
	ds_read_b64_tr_b16 v[194:195], v168 offset:59392
	ds_read_b64_tr_b16 v[196:197], v168 offset:59904
	ds_read_b128 v[92:95], v188 offset:2048
	v_add_f32_e32 v144, v66, v144
	v_add_f32_e32 v144, v67, v144
	v_add_f32_e32 v144, v68, v144
	v_add_f32_e32 v144, v69, v144
	v_cvt_pk_bf16_f32 v148, v64, v65
	v_cvt_pk_bf16_f32 v149, v66, v67
	s_waitcnt lgkmcnt(0)
	v_mfma_f32_32x32x16_bf16 v[112:127], v[140:143], v[92:95], v[112:127]
	ds_read_b64_tr_b16 v[140:141], v168 offset:63488
	ds_read_b64_tr_b16 v[142:143], v168 offset:64000
	ds_read_b128 v[64:67], v188 offset:2048
	v_add_f32_e32 v92, v70, v144
	v_add_f32_e32 v92, v71, v92
	v_add_f32_e32 v92, v72, v92
	v_add_f32_e32 v92, v73, v92
	v_cvt_pk_bf16_f32 v150, v68, v69
	v_cvt_pk_bf16_f32 v151, v70, v71
	s_waitcnt lgkmcnt(0)
	v_mfma_f32_32x32x16_bf16 v[96:111], v[136:139], v[64:67], v[96:111]
	ds_read_b64_tr_b16 v[136:137], v168 offset:60416
	ds_read_b64_tr_b16 v[138:139], v168 offset:60928
	ds_read_b128 v[64:67], v188 offset:3072
	v_add_f32_e32 v68, v74, v92
	v_add_f32_e32 v68, v75, v68
	v_add_f32_e32 v68, v76, v68
	v_add_f32_e32 v68, v77, v68
	v_cvt_pk_bf16_f32 v144, v72, v73
	v_cvt_pk_bf16_f32 v145, v74, v75
	s_waitcnt lgkmcnt(0)
	v_mfma_f32_32x32x16_bf16 v[112:127], v[132:135], v[64:67], v[112:127]
	ds_read_b64_tr_b16 v[72:73], v168 offset:64512
	ds_read_b64_tr_b16 v[74:75], v168 offset:65024
	ds_read_b128 v[64:67], v188 offset:3072
	v_add_f32_e32 v68, v78, v68
	v_add_f32_e32 v68, v79, v68
	v_add_f32_e32 v68, 0, v68
	v_cvt_pk_bf16_f32 v146, v76, v77
	v_cvt_pk_bf16_f32 v147, v78, v79
	s_waitcnt lgkmcnt(0)
	v_mfma_f32_32x32x16_bf16 v[96:111], v[128:131], v[64:67], v[96:111]
	v_lshl_add_u64 v[64:65], v[174:175], 0, s[58:59]
	s_mov_b32 s86, m0
	s_mov_b32 m0, s35
	s_nop 0
	global_load_lds_dwordx4 v[64:65], off
	s_mov_b32 m0, s86
	s_add_i32 s85, s85, s17
	v_lshl_add_u64 v[64:65], v[170:171], 0, s[60:61]
	s_add_i32 s17, s85, 0xa000
	s_mov_b32 s35, m0
	s_mov_b32 m0, s17
	s_nop 0
	global_load_lds_dwordx4 v[64:65], off
	s_mov_b32 m0, s35
	v_lshl_add_u64 v[64:65], v[172:173], 0, s[60:61]
	s_add_i32 s35, s17, 0x2000
	s_mov_b32 s86, m0
	s_mov_b32 m0, s35
	s_nop 0
	global_load_lds_dwordx4 v[64:65], off
	s_mov_b32 m0, s86
	v_add_f32_e32 v198, v193, v68
	v_mfma_f32_32x32x16_bf16 v[48:63], v[156:159], v[178:181], v[48:63]
	ds_read_b64_tr_b16 v[76:77], v177 offset:40960
	ds_read_b64_tr_b16 v[78:79], v177 offset:41472
	v_exp_f32_e32 v112, v112
	v_exp_f32_e32 v113, v113
	v_mfma_f32_32x32x16_bf16 v[32:47], v[156:159], v[80:83], v[32:47]
	ds_read_b64_tr_b16 v[128:129], v177 offset:45056
	ds_read_b64_tr_b16 v[130:131], v177 offset:45568
	v_exp_f32_e32 v114, v114
	v_exp_f32_e32 v115, v115
	ds_read_b128 v[68:71], v234 offset:8192
	ds_read_b128 v[64:67], v234 offset:12288
	v_mfma_f32_32x32x16_bf16 v[48:63], v[152:155], v[84:87], v[48:63]
	ds_read_b64_tr_b16 v[132:133], v177 offset:41984
	ds_read_b64_tr_b16 v[134:135], v177 offset:42496
	v_exp_f32_e32 v116, v116
	v_exp_f32_e32 v117, v117
	ds_read_b128 v[164:167], v235 offset:8192
	ds_read_b128 v[92:95], v235 offset:12288
	v_mfma_f32_32x32x16_bf16 v[32:47], v[152:155], v[88:91], v[32:47]
	ds_read_b64_tr_b16 v[178:179], v177 offset:46080
	ds_read_b64_tr_b16 v[180:181], v177 offset:46592
	v_exp_f32_e32 v118, v118
	v_exp_f32_e32 v119, v119
	ds_read_b128 v[160:163], v236 offset:8192
	ds_read_b128 v[84:87], v236 offset:12288
	v_mfma_f32_32x32x16_bf16 v[48:63], v[148:151], v[194:197], v[48:63]
	ds_read_b64_tr_b16 v[190:191], v177 offset:43008
	ds_read_b64_tr_b16 v[192:193], v177 offset:43520
	v_exp_f32_e32 v120, v120
	v_exp_f32_e32 v121, v121
	ds_read_b128 v[88:91], v237 offset:8192
	ds_read_b128 v[80:83], v237 offset:12288
	v_mfma_f32_32x32x16_bf16 v[32:47], v[148:151], v[140:143], v[32:47]
	ds_read_b64_tr_b16 v[194:195], v177 offset:47104
	ds_read_b64_tr_b16 v[196:197], v177 offset:47616
	v_exp_f32_e32 v122, v122
	v_exp_f32_e32 v123, v123
	v_mfma_f32_32x32x16_bf16 v[48:63], v[144:147], v[136:139], v[48:63]
	ds_read_b64_tr_b16 v[140:141], v177 offset:44032
	ds_read_b64_tr_b16 v[142:143], v177 offset:44544
	v_exp_f32_e32 v124, v124
	v_exp_f32_e32 v125, v125
	v_mfma_f32_32x32x16_bf16 v[32:47], v[144:147], v[72:75], v[32:47]
	ds_read_b64_tr_b16 v[136:137], v177 offset:48128
	ds_read_b64_tr_b16 v[138:139], v177 offset:48640
	v_exp_f32_e32 v126, v126
	v_exp_f32_e32 v127, v127
	s_waitcnt lgkmcnt(14)
;   #define RESC() do{ if(!NOMAX&&resc){ asm volatile("s_waitcnt lgkmcnt(0)":::"memory"); \
;       _Pragma("unroll") for(int d_=0;d_<2*VM;++d_) _Pragma("unroll") for(int r=0;r<16;++r)o[d_][r]*=wsf[crow(r,hi)]; } }while(0)
;   #define ROT() do{sl_prev=sl_cur;sl_cur=sl_next;sl_next=(sl_next==(NSLOT-1)*SLOTB)?0:sl_next+SLOTB;}while(0)
;   #define ENDW(tt) do{ if((tt)+3<NT){ if constexpr(VM==2){WAIT_BAR(3);}else{WAIT_BAR(2);} } else if((tt)+2<NT){ if constexpr(VM==2){WAIT_BAR(2);}else{WAIT_BAR(1);} } else {WAIT_BAR(0);} }while(0)
; template<int THRL,int VM,bool NOMAX> __device__ __forceinline__ void attn_unit(const bf16*Qb,const bf16*__restrict__ Kh,const bf16*__restrict__ Vh,bf16*Ob,const int NT,const int sp,float*wscr,char*shm){
;     ...
;   for(;t+1<NT;t+=2){
;     STEP(pB0,pB1,pA0,pA1,t,(t+3<NT),(t+1<NT),(t+1<NT));       ENDW(t);   RESC(); ROT();
	v_mfma_f32_32x32x16_bf16 v[16:31], v[156:159], v[76:79], v[16:31]
	v_exp_f32_e32 v96, v96
	v_exp_f32_e32 v97, v97
	v_mfma_f32_32x32x16_bf16 v[0:15], v[156:159], v[128:131], v[0:15]
	v_exp_f32_e32 v98, v98
	v_exp_f32_e32 v99, v99
	v_mfma_f32_32x32x16_bf16 v[16:31], v[152:155], v[132:135], v[16:31]
	v_exp_f32_e32 v100, v100
	v_exp_f32_e32 v101, v101
	s_waitcnt lgkmcnt(12)
	v_mfma_f32_32x32x16_bf16 v[0:15], v[152:155], v[178:181], v[0:15]
	v_exp_f32_e32 v102, v102
	v_exp_f32_e32 v103, v103
	s_waitcnt lgkmcnt(8)
	v_mfma_f32_32x32x16_bf16 v[16:31], v[148:151], v[190:193], v[16:31]
	v_exp_f32_e32 v104, v104
	v_exp_f32_e32 v105, v105
	s_waitcnt lgkmcnt(4)
	v_mfma_f32_32x32x16_bf16 v[0:15], v[148:151], v[194:197], v[0:15]
	v_exp_f32_e32 v106, v106
	v_exp_f32_e32 v107, v107
	s_waitcnt lgkmcnt(2)
	v_mfma_f32_32x32x16_bf16 v[16:31], v[144:147], v[140:143], v[16:31]
	v_exp_f32_e32 v108, v108
	v_exp_f32_e32 v109, v109
	s_waitcnt lgkmcnt(0)
	v_mfma_f32_32x32x16_bf16 v[0:15], v[144:147], v[136:139], v[0:15]
	v_exp_f32_e32 v110, v110
	v_exp_f32_e32 v111, v111
	s_waitcnt vmcnt(3) lgkmcnt(0)
	s_barrier
	ds_read_b64_tr_b16 v[178:179], v168 offset:24576
	ds_read_b64_tr_b16 v[180:181], v168 offset:25088
	v_add_f32_e32 v76, v112, v113
	ds_read_b128 v[72:75], v188
	v_add_f32_e32 v76, v114, v76
	v_add_f32_e32 v76, v115, v76
	v_add_f32_e32 v76, v116, v76
	v_add_f32_e32 v76, v117, v76
	v_cvt_pk_bf16_f32 v156, v112, v113
	v_cvt_pk_bf16_f32 v157, v114, v115
	s_waitcnt lgkmcnt(0)
	v_mfma_f32_32x32x16_bf16 v[128:143], v[68:71], v[72:75], 0
	ds_read_b64_tr_b16 v[112:113], v168 offset:28672
	ds_read_b64_tr_b16 v[114:115], v168 offset:29184
	ds_read_b128 v[68:71], v188
	v_add_f32_e32 v72, v118, v76
	v_add_f32_e32 v72, v119, v72
	v_add_f32_e32 v72, v120, v72
	v_add_f32_e32 v144, v121, v72
	s_waitcnt lgkmcnt(0)
	v_mfma_f32_32x32x16_bf16 v[64:79], v[64:67], v[68:71], 0
	v_cvt_pk_bf16_f32 v158, v116, v117
	v_cvt_pk_bf16_f32 v159, v118, v119
	ds_read_b64_tr_b16 v[116:117], v168 offset:25600
	ds_read_b64_tr_b16 v[118:119], v168 offset:26112
	ds_read_b128 v[190:193], v188 offset:1024
	v_add_f32_e32 v144, v122, v144
	v_add_f32_e32 v144, v123, v144
	v_add_f32_e32 v144, v124, v144
	v_add_f32_e32 v144, v125, v144
	v_cvt_pk_bf16_f32 v152, v120, v121
	v_cvt_pk_bf16_f32 v153, v122, v123
	s_waitcnt lgkmcnt(0)
	v_mfma_f32_32x32x16_bf16 v[128:143], v[164:167], v[190:193], v[128:143]
	ds_read_b64_tr_b16 v[120:121], v168 offset:29696
	ds_read_b64_tr_b16 v[122:123], v168 offset:30208
	ds_read_b128 v[164:167], v188 offset:1024
	v_add_f32_e32 v144, v126, v144
	v_add_f32_e32 v144, v127, v144
	v_add_f32_e32 v144, v96, v144
	v_add_f32_e32 v144, v97, v144
	s_waitcnt lgkmcnt(0)
	v_mfma_f32_32x32x16_bf16 v[64:79], v[92:95], v[164:167], v[64:79]
	v_cvt_pk_bf16_f32 v154, v124, v125
	v_cvt_pk_bf16_f32 v155, v126, v127
	ds_read_b64_tr_b16 v[92:93], v168 offset:26624
	ds_read_b64_tr_b16 v[94:95], v168 offset:27136
	ds_read_b128 v[124:127], v188 offset:2048
	v_add_f32_e32 v144, v98, v144
	v_add_f32_e32 v144, v99, v144
	v_add_f32_e32 v144, v100, v144
	v_add_f32_e32 v144, v101, v144
	v_cvt_pk_bf16_f32 v148, v96, v97
	v_cvt_pk_bf16_f32 v149, v98, v99
	s_waitcnt lgkmcnt(0)
	v_mfma_f32_32x32x16_bf16 v[128:143], v[160:163], v[124:127], v[128:143]
	ds_read_b64_tr_b16 v[96:97], v168 offset:30720
	ds_read_b64_tr_b16 v[98:99], v168 offset:31232
	ds_read_b128 v[124:127], v188 offset:2048
	v_add_f32_e32 v144, v102, v144
	v_add_f32_e32 v144, v103, v144
	v_add_f32_e32 v144, v104, v144
	v_add_f32_e32 v144, v105, v144
	s_waitcnt lgkmcnt(0)
	v_mfma_f32_32x32x16_bf16 v[64:79], v[84:87], v[124:127], v[64:79]
	v_cvt_pk_bf16_f32 v150, v100, v101
	v_cvt_pk_bf16_f32 v151, v102, v103
	ds_read_b64_tr_b16 v[100:101], v168 offset:27648
	ds_read_b64_tr_b16 v[102:103], v168 offset:28160
	ds_read_b128 v[84:87], v188 offset:3072
	v_add_f32_e32 v124, v106, v144
	v_add_f32_e32 v124, v107, v124
	v_add_f32_e32 v124, v108, v124
	v_add_f32_e32 v124, v109, v124
	v_cvt_pk_bf16_f32 v144, v104, v105
	v_cvt_pk_bf16_f32 v145, v106, v107
	s_waitcnt lgkmcnt(0)
	v_mfma_f32_32x32x16_bf16 v[128:143], v[88:91], v[84:87], v[128:143]
	ds_read_b64_tr_b16 v[88:89], v168 offset:31744
	ds_read_b64_tr_b16 v[90:91], v168 offset:32256
	ds_read_b128 v[84:87], v188 offset:3072
	v_add_f32_e32 v104, v110, v124
	v_add_f32_e32 v104, v111, v104
	v_add_f32_e32 v104, 0, v104
	v_cvt_pk_bf16_f32 v146, v108, v109
	s_waitcnt lgkmcnt(0)
;   #define RESC() do{ if(!NOMAX&&resc){ asm volatile("s_waitcnt lgkmcnt(0)":::"memory"); \
;       _Pragma("unroll") for(int d_=0;d_<2*VM;++d_) _Pragma("unroll") for(int r=0;r<16;++r)o[d_][r]*=wsf[crow(r,hi)]; } }while(0)
;   #define ROT() do{sl_prev=sl_cur;sl_cur=sl_next;sl_next=(sl_next==(NSLOT-1)*SLOTB)?0:sl_next+SLOTB;}while(0)
;   #define ENDW(tt) do{ if((tt)+3<NT){ if constexpr(VM==2){WAIT_BAR(3);}else{WAIT_BAR(2);} } else if((tt)+2<NT){ if constexpr(VM==2){WAIT_BAR(2);}else{WAIT_BAR(1);} } else {WAIT_BAR(0);} }while(0)
; template<int THRL,int VM,bool NOMAX> __device__ __forceinline__ void attn_unit(const bf16*Qb,const bf16*__restrict__ Kh,const bf16*__restrict__ Vh,bf16*Ob,const int NT,const int sp,float*wscr,char*shm){
;     ...
;   for(;t+1<NT;t+=2){
;     STEP(pB0,pB1,pA0,pA1,t,(t+3<NT),(t+1<NT),(t+1<NT));       ENDW(t);   RESC(); ROT();
	v_mfma_f32_32x32x16_bf16 v[64:79], v[80:83], v[84:87], v[64:79]
	v_cvt_pk_bf16_f32 v147, v110, v111
	v_lshl_add_u64 v[80:81], v[174:175], 0, s[62:63]
	s_add_i32 s86, s85, 0x2000
	s_mov_b32 s87, m0
	s_mov_b32 m0, s86
	s_nop 0
	global_load_lds_dwordx4 v[80:81], off
	s_mov_b32 m0, s87
	v_lshl_add_u64 v[80:81], v[170:171], 0, s[64:65]
	s_add_i32 s86, s85, 0xe000
	s_mov_b32 s87, m0
	s_mov_b32 m0, s86
	s_nop 0
	global_load_lds_dwordx4 v[80:81], off
	s_mov_b32 m0, s87
	v_lshl_add_u64 v[80:81], v[172:173], 0, s[64:65]
	s_add_i32 s85, s85, 0x10000
	s_mov_b32 s86, m0
	s_mov_b32 m0, s85
	s_nop 0
	global_load_lds_dwordx4 v[80:81], off
	s_mov_b32 m0, s86
	v_add_f32_e32 v198, v198, v104
	v_mfma_f32_32x32x16_bf16 v[48:63], v[156:159], v[178:181], v[48:63]
	ds_read_b64_tr_b16 v[104:105], v168 offset:32768
	ds_read_b64_tr_b16 v[106:107], v168 offset:33280
	v_exp_f32_e32 v128, v128
	v_exp_f32_e32 v129, v129
	v_mfma_f32_32x32x16_bf16 v[32:47], v[156:159], v[112:115], v[32:47]
	ds_read_b64_tr_b16 v[108:109], v168 offset:36864
	ds_read_b64_tr_b16 v[110:111], v168 offset:37376
	v_exp_f32_e32 v130, v130
	v_exp_f32_e32 v131, v131
	ds_read_b128 v[84:87], v234 offset:16384
	ds_read_b128 v[80:83], v234 offset:20480
	v_mfma_f32_32x32x16_bf16 v[48:63], v[152:155], v[116:119], v[48:63]
	ds_read_b64_tr_b16 v[178:179], v168 offset:33792
	ds_read_b64_tr_b16 v[180:181], v168 offset:34304
	v_exp_f32_e32 v132, v132
	v_exp_f32_e32 v133, v133
	ds_read_b128 v[164:167], v235 offset:16384
	ds_read_b128 v[124:127], v235 offset:20480
	v_mfma_f32_32x32x16_bf16 v[32:47], v[152:155], v[120:123], v[32:47]
	ds_read_b64_tr_b16 v[190:191], v168 offset:37888
	ds_read_b64_tr_b16 v[192:193], v168 offset:38400
	v_exp_f32_e32 v134, v134
	v_exp_f32_e32 v135, v135
	ds_read_b128 v[160:163], v236 offset:16384
	ds_read_b128 v[116:119], v236 offset:20480
	v_mfma_f32_32x32x16_bf16 v[48:63], v[148:151], v[92:95], v[48:63]
	ds_read_b64_tr_b16 v[194:195], v168 offset:34816
	ds_read_b64_tr_b16 v[196:197], v168 offset:35328
	v_exp_f32_e32 v136, v136
	v_exp_f32_e32 v137, v137
	ds_read_b128 v[120:123], v237 offset:16384
	ds_read_b128 v[112:115], v237 offset:20480
	v_mfma_f32_32x32x16_bf16 v[32:47], v[148:151], v[96:99], v[32:47]
	ds_read_b64_tr_b16 v[92:93], v168 offset:38912
	ds_read_b64_tr_b16 v[94:95], v168 offset:39424
	v_exp_f32_e32 v138, v138
	v_exp_f32_e32 v139, v139
	v_mfma_f32_32x32x16_bf16 v[48:63], v[144:147], v[100:103], v[48:63]
	ds_read_b64_tr_b16 v[96:97], v168 offset:35840
	ds_read_b64_tr_b16 v[98:99], v168 offset:36352
	v_exp_f32_e32 v140, v140
	v_exp_f32_e32 v141, v141
	v_mfma_f32_32x32x16_bf16 v[32:47], v[144:147], v[88:91], v[32:47]
	ds_read_b64_tr_b16 v[100:101], v168 offset:39936
	ds_read_b64_tr_b16 v[102:103], v168 offset:40448
	v_exp_f32_e32 v142, v142
	v_exp_f32_e32 v143, v143
	s_waitcnt lgkmcnt(14)
	v_mfma_f32_32x32x16_bf16 v[16:31], v[156:159], v[104:107], v[16:31]
	v_exp_f32_e32 v64, v64
	v_exp_f32_e32 v65, v65
	v_mfma_f32_32x32x16_bf16 v[0:15], v[156:159], v[108:111], v[0:15]
	v_exp_f32_e32 v66, v66
	v_exp_f32_e32 v67, v67
	v_mfma_f32_32x32x16_bf16 v[16:31], v[152:155], v[178:181], v[16:31]
	v_exp_f32_e32 v68, v68
	v_exp_f32_e32 v69, v69
	s_waitcnt lgkmcnt(12)
	v_mfma_f32_32x32x16_bf16 v[0:15], v[152:155], v[190:193], v[0:15]
	v_exp_f32_e32 v70, v70
	v_exp_f32_e32 v71, v71
	s_waitcnt lgkmcnt(8)
	v_mfma_f32_32x32x16_bf16 v[16:31], v[148:151], v[194:197], v[16:31]
	v_exp_f32_e32 v72, v72
	v_exp_f32_e32 v73, v73
	s_waitcnt lgkmcnt(4)
	v_mfma_f32_32x32x16_bf16 v[0:15], v[148:151], v[92:95], v[0:15]
	v_exp_f32_e32 v74, v74
	v_exp_f32_e32 v75, v75
	s_waitcnt lgkmcnt(2)
	v_mfma_f32_32x32x16_bf16 v[16:31], v[144:147], v[96:99], v[16:31]
	v_exp_f32_e32 v76, v76
	v_exp_f32_e32 v77, v77
	s_waitcnt lgkmcnt(0)
	v_mfma_f32_32x32x16_bf16 v[0:15], v[144:147], v[100:103], v[0:15]
	v_exp_f32_e32 v78, v78
	v_exp_f32_e32 v79, v79
	s_waitcnt vmcnt(3) lgkmcnt(0)
	s_barrier
	ds_read_b64_tr_b16 v[178:179], v168 offset:40960
	ds_read_b64_tr_b16 v[180:181], v168 offset:41472
	v_add_f32_e32 v92, v128, v129
	ds_read_b128 v[88:91], v188
	v_add_f32_e32 v92, v130, v92
	v_add_f32_e32 v92, v131, v92
	v_add_f32_e32 v92, v132, v92
	v_add_f32_e32 v92, v133, v92
	v_cvt_pk_bf16_f32 v156, v128, v129
	v_cvt_pk_bf16_f32 v157, v130, v131
	s_waitcnt lgkmcnt(0)
	v_mfma_f32_32x32x16_bf16 v[96:111], v[84:87], v[88:91], 0
	ds_read_b64_tr_b16 v[128:129], v168 offset:45056
	ds_read_b64_tr_b16 v[130:131], v168 offset:45568
	ds_read_b128 v[84:87], v188
	v_add_f32_e32 v88, v134, v92
	v_add_f32_e32 v88, v135, v88
	v_add_f32_e32 v88, v136, v88
	v_add_f32_e32 v144, v137, v88
	v_cvt_pk_bf16_f32 v158, v132, v133
	v_cvt_pk_bf16_f32 v159, v134, v135
	s_waitcnt lgkmcnt(0)
	v_mfma_f32_32x32x16_bf16 v[80:95], v[80:83], v[84:87], 0
	ds_read_b64_tr_b16 v[132:133], v168 offset:41984
	ds_read_b64_tr_b16 v[134:135], v168 offset:42496
	ds_read_b128 v[190:193], v188 offset:1024
	v_add_f32_e32 v144, v138, v144
	v_add_f32_e32 v144, v139, v144
	v_add_f32_e32 v144, v140, v144
	v_add_f32_e32 v144, v141, v144
	v_cvt_pk_bf16_f32 v152, v136, v137
	v_cvt_pk_bf16_f32 v153, v138, v139
	s_waitcnt lgkmcnt(0)
	v_mfma_f32_32x32x16_bf16 v[96:111], v[164:167], v[190:193], v[96:111]
	ds_read_b64_tr_b16 v[136:137], v168 offset:46080
	ds_read_b64_tr_b16 v[138:139], v168 offset:46592
	ds_read_b128 v[164:167], v188 offset:1024
	v_add_f32_e32 v144, v142, v144
	v_add_f32_e32 v144, v143, v144
	v_add_f32_e32 v144, v64, v144
	v_add_f32_e32 v144, v65, v144
	v_cvt_pk_bf16_f32 v154, v140, v141
	v_cvt_pk_bf16_f32 v155, v142, v143
	s_waitcnt lgkmcnt(0)
;   #define RESC() do{ if(!NOMAX&&resc){ asm volatile("s_waitcnt lgkmcnt(0)":::"memory"); \
;       _Pragma("unroll") for(int d_=0;d_<2*VM;++d_) _Pragma("unroll") for(int r=0;r<16;++r)o[d_][r]*=wsf[crow(r,hi)]; } }while(0)
;   #define ROT() do{sl_prev=sl_cur;sl_cur=sl_next;sl_next=(sl_next==(NSLOT-1)*SLOTB)?0:sl_next+SLOTB;}while(0)
;   #define ENDW(tt) do{ if((tt)+3<NT){ if constexpr(VM==2){WAIT_BAR(3);}else{WAIT_BAR(2);} } else if((tt)+2<NT){ if constexpr(VM==2){WAIT_BAR(2);}else{WAIT_BAR(1);} } else {WAIT_BAR(0);} }while(0)
; template<int THRL,int VM,bool NOMAX> __device__ __forceinline__ void attn_unit(const bf16*Qb,const bf16*__restrict__ Kh,const bf16*__restrict__ Vh,bf16*Ob,const int NT,const int sp,float*wscr,char*shm){
;     ...
;   for(;t+1<NT;t+=2){
;     STEP(pB0,pB1,pA0,pA1,t,(t+3<NT),(t+1<NT),(t+1<NT));       ENDW(t);   RESC(); ROT();
	v_mfma_f32_32x32x16_bf16 v[80:95], v[124:127], v[164:167], v[80:95]
	ds_read_b64_tr_b16 v[124:125], v168 offset:43008
	ds_read_b64_tr_b16 v[126:127], v168 offset:43520
	ds_read_b128 v[140:143], v188 offset:2048
	v_add_f32_e32 v144, v66, v144
	v_add_f32_e32 v144, v67, v144
	v_add_f32_e32 v144, v68, v144
	v_add_f32_e32 v144, v69, v144
	v_cvt_pk_bf16_f32 v148, v64, v65
	v_cvt_pk_bf16_f32 v149, v66, v67
	s_waitcnt lgkmcnt(0)
	v_mfma_f32_32x32x16_bf16 v[96:111], v[160:163], v[140:143], v[96:111]
	ds_read_b64_tr_b16 v[190:191], v168 offset:47104
	ds_read_b64_tr_b16 v[192:193], v168 offset:47616
	ds_read_b128 v[64:67], v188 offset:2048
	v_add_f32_e32 v140, v70, v144
	v_add_f32_e32 v140, v71, v140
	v_add_f32_e32 v140, v72, v140
	v_add_f32_e32 v140, v73, v140
	v_cvt_pk_bf16_f32 v150, v68, v69
	v_cvt_pk_bf16_f32 v151, v70, v71
	s_waitcnt lgkmcnt(0)
	v_mfma_f32_32x32x16_bf16 v[80:95], v[116:119], v[64:67], v[80:95]
	ds_read_b64_tr_b16 v[116:117], v168 offset:44032
	ds_read_b64_tr_b16 v[118:119], v168 offset:44544
	ds_read_b128 v[64:67], v188 offset:3072
	v_add_f32_e32 v68, v74, v140
	v_add_f32_e32 v68, v75, v68
	v_add_f32_e32 v68, v76, v68
	v_add_f32_e32 v68, v77, v68
	v_cvt_pk_bf16_f32 v144, v72, v73
	v_cvt_pk_bf16_f32 v145, v74, v75
	s_waitcnt lgkmcnt(0)
	v_mfma_f32_32x32x16_bf16 v[96:111], v[120:123], v[64:67], v[96:111]
	ds_read_b64_tr_b16 v[72:73], v168 offset:48128
	ds_read_b64_tr_b16 v[74:75], v168 offset:48640
	ds_read_b128 v[64:67], v188 offset:3072
	v_add_f32_e32 v68, v78, v68
	v_add_f32_e32 v68, v79, v68
	v_add_f32_e32 v68, 0, v68
	v_cvt_pk_bf16_f32 v146, v76, v77
	v_cvt_pk_bf16_f32 v147, v78, v79
	s_waitcnt lgkmcnt(0)
	v_mfma_f32_32x32x16_bf16 v[80:95], v[112:115], v[64:67], v[80:95]
	v_lshl_add_u64 v[64:65], v[170:171], 0, s[58:59]
	s_mov_b32 s85, m0
	s_mov_b32 m0, s16
	s_nop 0
	global_load_lds_dwordx4 v[64:65], off
	s_mov_b32 m0, s85
	v_lshl_add_u64 v[64:65], v[172:173], 0, s[58:59]
	s_addk_i32 s16, 0x2000
	s_mov_b32 s85, m0
	s_mov_b32 m0, s16
	s_nop 0
	global_load_lds_dwordx4 v[64:65], off
	s_mov_b32 m0, s85
	v_add_f32_e32 v174, v198, v68
	v_mfma_f32_32x32x16_bf16 v[48:63], v[156:159], v[178:181], v[48:63]
	ds_read_b64_tr_b16 v[76:77], v168 offset:49152
	ds_read_b64_tr_b16 v[78:79], v168 offset:49664
	v_exp_f32_e32 v96, v96
	v_exp_f32_e32 v97, v97
	v_mfma_f32_32x32x16_bf16 v[32:47], v[156:159], v[128:131], v[32:47]
	ds_read_b64_tr_b16 v[112:113], v168 offset:53248
	ds_read_b64_tr_b16 v[114:115], v168 offset:53760
	v_exp_f32_e32 v98, v98
	v_exp_f32_e32 v99, v99
	ds_read_b128 v[68:71], v234
	ds_read_b128 v[64:67], v234 offset:4096
	v_mfma_f32_32x32x16_bf16 v[48:63], v[152:155], v[132:135], v[48:63]
	ds_read_b64_tr_b16 v[120:121], v168 offset:50176
	ds_read_b64_tr_b16 v[122:123], v168 offset:50688
	v_exp_f32_e32 v100, v100
	v_exp_f32_e32 v101, v101
	ds_read_b128 v[164:167], v235
	ds_read_b128 v[140:143], v235 offset:4096
	v_mfma_f32_32x32x16_bf16 v[32:47], v[152:155], v[136:139], v[32:47]
	ds_read_b64_tr_b16 v[178:179], v168 offset:54272
	ds_read_b64_tr_b16 v[180:181], v168 offset:54784
	v_exp_f32_e32 v102, v102
	v_exp_f32_e32 v103, v103
	ds_read_b128 v[160:163], v236
	ds_read_b128 v[132:135], v236 offset:4096
	v_mfma_f32_32x32x16_bf16 v[48:63], v[148:151], v[124:127], v[48:63]
	ds_read_b64_tr_b16 v[194:195], v168 offset:51200
	ds_read_b64_tr_b16 v[196:197], v168 offset:51712
	v_exp_f32_e32 v104, v104
	v_exp_f32_e32 v105, v105
	ds_read_b128 v[136:139], v237
	ds_read_b128 v[128:131], v237 offset:4096
	v_mfma_f32_32x32x16_bf16 v[32:47], v[148:151], v[190:193], v[32:47]
	ds_read_b64_tr_b16 v[124:125], v168 offset:55296
	ds_read_b64_tr_b16 v[126:127], v168 offset:55808
	v_exp_f32_e32 v106, v106
	v_exp_f32_e32 v107, v107
	v_mfma_f32_32x32x16_bf16 v[48:63], v[144:147], v[116:119], v[48:63]
	ds_read_b64_tr_b16 v[190:191], v168 offset:52224
	ds_read_b64_tr_b16 v[192:193], v168 offset:52736
	v_exp_f32_e32 v108, v108
	v_exp_f32_e32 v109, v109
	v_mfma_f32_32x32x16_bf16 v[32:47], v[144:147], v[72:75], v[32:47]
	ds_read_b64_tr_b16 v[116:117], v168 offset:56320
	ds_read_b64_tr_b16 v[118:119], v168 offset:56832
	v_exp_f32_e32 v110, v110
	v_exp_f32_e32 v111, v111
	s_waitcnt lgkmcnt(14)
	v_mfma_f32_32x32x16_bf16 v[16:31], v[156:159], v[76:79], v[16:31]
	v_exp_f32_e32 v80, v80
	v_exp_f32_e32 v81, v81
	v_mfma_f32_32x32x16_bf16 v[0:15], v[156:159], v[112:115], v[0:15]
	v_exp_f32_e32 v82, v82
	v_exp_f32_e32 v83, v83
	v_mfma_f32_32x32x16_bf16 v[16:31], v[152:155], v[120:123], v[16:31]
	v_exp_f32_e32 v84, v84
	v_exp_f32_e32 v85, v85
	s_waitcnt lgkmcnt(12)
	v_mfma_f32_32x32x16_bf16 v[0:15], v[152:155], v[178:181], v[0:15]
	v_exp_f32_e32 v86, v86
	v_exp_f32_e32 v87, v87
	s_waitcnt lgkmcnt(8)
	v_mfma_f32_32x32x16_bf16 v[16:31], v[148:151], v[194:197], v[16:31]
	v_exp_f32_e32 v88, v88
	v_exp_f32_e32 v89, v89
	s_waitcnt lgkmcnt(4)
	v_mfma_f32_32x32x16_bf16 v[0:15], v[148:151], v[124:127], v[0:15]
	v_exp_f32_e32 v90, v90
	v_exp_f32_e32 v91, v91
	s_waitcnt lgkmcnt(2)
	v_mfma_f32_32x32x16_bf16 v[16:31], v[144:147], v[190:193], v[16:31]
	v_exp_f32_e32 v92, v92
	v_exp_f32_e32 v93, v93
	s_waitcnt lgkmcnt(0)
	v_mfma_f32_32x32x16_bf16 v[0:15], v[144:147], v[116:119], v[0:15]
	v_exp_f32_e32 v94, v94
	v_exp_f32_e32 v95, v95
	s_waitcnt vmcnt(2) lgkmcnt(0)
	s_barrier
;   #define RESC() do{ if(!NOMAX&&resc){ asm volatile("s_waitcnt lgkmcnt(0)":::"memory"); \
;       _Pragma("unroll") for(int d_=0;d_<2*VM;++d_) _Pragma("unroll") for(int r=0;r<16;++r)o[d_][r]*=wsf[crow(r,hi)]; } }while(0)
;   #define ROT() do{sl_prev=sl_cur;sl_cur=sl_next;sl_next=(sl_next==(NSLOT-1)*SLOTB)?0:sl_next+SLOTB;}while(0)
;   #define ENDW(tt) do{ if((tt)+3<NT){ if constexpr(VM==2){WAIT_BAR(3);}else{WAIT_BAR(2);} } else if((tt)+2<NT){ if constexpr(VM==2){WAIT_BAR(2);}else{WAIT_BAR(1);} } else {WAIT_BAR(0);} }while(0)
; template<int THRL,int VM,bool NOMAX> __device__ __forceinline__ void attn_unit(const bf16*Qb,const bf16*__restrict__ Kh,const bf16*__restrict__ Vh,bf16*Ob,const int NT,const int sp,float*wscr,char*shm){
;     ...
;   for(;t+1<NT;t+=2){
;     STEP(pB0,pB1,pA0,pA1,t,(t+3<NT),(t+1<NT),(t+1<NT));       ENDW(t);   RESC(); ROT();
	ds_read_b64_tr_b16 v[178:179], v168 offset:57344
	ds_read_b64_tr_b16 v[180:181], v168 offset:57856
	v_add_f32_e32 v76, v96, v97
	ds_read_b128 v[72:75], v188
	v_add_f32_e32 v76, v98, v76
	v_add_f32_e32 v76, v99, v76
	v_add_f32_e32 v76, v100, v76
	v_add_f32_e32 v76, v101, v76
	v_cvt_pk_bf16_f32 v156, v96, v97
	v_cvt_pk_bf16_f32 v157, v98, v99
	s_waitcnt lgkmcnt(0)
	v_mfma_f32_32x32x16_bf16 v[112:127], v[68:71], v[72:75], 0
	ds_read_b64_tr_b16 v[96:97], v168 offset:61440
	ds_read_b64_tr_b16 v[98:99], v168 offset:61952
	ds_read_b128 v[68:71], v188
	v_add_f32_e32 v72, v102, v76
	v_add_f32_e32 v72, v103, v72
	v_add_f32_e32 v72, v104, v72
	v_add_f32_e32 v144, v105, v72
	s_waitcnt lgkmcnt(0)
	v_mfma_f32_32x32x16_bf16 v[64:79], v[64:67], v[68:71], 0
	v_cvt_pk_bf16_f32 v158, v100, v101
	v_cvt_pk_bf16_f32 v159, v102, v103
	ds_read_b64_tr_b16 v[100:101], v168 offset:58368
	ds_read_b64_tr_b16 v[102:103], v168 offset:58880
	ds_read_b128 v[190:193], v188 offset:1024
	v_add_f32_e32 v144, v106, v144
	v_add_f32_e32 v144, v107, v144
	v_add_f32_e32 v144, v108, v144
	v_add_f32_e32 v144, v109, v144
	v_cvt_pk_bf16_f32 v152, v104, v105
	v_cvt_pk_bf16_f32 v153, v106, v107
	s_waitcnt lgkmcnt(0)
	v_mfma_f32_32x32x16_bf16 v[112:127], v[164:167], v[190:193], v[112:127]
	ds_read_b64_tr_b16 v[104:105], v168 offset:62464
	ds_read_b64_tr_b16 v[106:107], v168 offset:62976
	ds_read_b128 v[164:167], v188 offset:1024
	v_add_f32_e32 v144, v110, v144
	v_add_f32_e32 v144, v111, v144
	v_add_f32_e32 v144, v80, v144
	v_add_f32_e32 v144, v81, v144
	s_waitcnt lgkmcnt(0)
	v_mfma_f32_32x32x16_bf16 v[64:79], v[140:143], v[164:167], v[64:79]
	v_cvt_pk_bf16_f32 v154, v108, v109
	v_cvt_pk_bf16_f32 v155, v110, v111
	ds_read_b64_tr_b16 v[108:109], v168 offset:59392
	ds_read_b64_tr_b16 v[110:111], v168 offset:59904
	ds_read_b128 v[140:143], v188 offset:2048
	v_add_f32_e32 v144, v82, v144
	v_add_f32_e32 v144, v83, v144
	v_add_f32_e32 v144, v84, v144
	v_add_f32_e32 v144, v85, v144
	v_cvt_pk_bf16_f32 v148, v80, v81
	v_cvt_pk_bf16_f32 v149, v82, v83
	s_waitcnt lgkmcnt(0)
	v_mfma_f32_32x32x16_bf16 v[112:127], v[160:163], v[140:143], v[112:127]
	ds_read_b64_tr_b16 v[190:191], v168 offset:63488
	ds_read_b64_tr_b16 v[192:193], v168 offset:64000
	ds_read_b128 v[80:83], v188 offset:2048
	v_add_f32_e32 v140, v86, v144
	v_add_f32_e32 v140, v87, v140
	v_add_f32_e32 v140, v88, v140
	v_add_f32_e32 v140, v89, v140
	s_waitcnt lgkmcnt(0)
	v_mfma_f32_32x32x16_bf16 v[64:79], v[132:135], v[80:83], v[64:79]
	v_cvt_pk_bf16_f32 v150, v84, v85
	v_cvt_pk_bf16_f32 v151, v86, v87
	ds_read_b64_tr_b16 v[84:85], v168 offset:60416
	ds_read_b64_tr_b16 v[86:87], v168 offset:60928
	ds_read_b128 v[80:83], v188 offset:3072
	v_add_f32_e32 v132, v90, v140
	v_add_f32_e32 v132, v91, v132
	v_add_f32_e32 v132, v92, v132
	v_add_f32_e32 v132, v93, v132
	v_cvt_pk_bf16_f32 v144, v88, v89
	v_cvt_pk_bf16_f32 v145, v90, v91
	s_waitcnt lgkmcnt(0)
	v_mfma_f32_32x32x16_bf16 v[112:127], v[136:139], v[80:83], v[112:127]
	ds_read_b64_tr_b16 v[88:89], v168 offset:64512
	ds_read_b64_tr_b16 v[90:91], v168 offset:65024
	ds_read_b128 v[80:83], v188 offset:3072
	v_add_f32_e32 v132, v94, v132
	v_add_f32_e32 v132, v95, v132
	v_add_f32_e32 v132, 0, v132
	v_cvt_pk_bf16_f32 v146, v92, v93
	s_waitcnt lgkmcnt(0)
	v_mfma_f32_32x32x16_bf16 v[64:79], v[128:131], v[80:83], v[64:79]
	v_cvt_pk_bf16_f32 v147, v94, v95
	v_lshl_add_u64 v[80:81], v[170:171], 0, s[62:63]
	s_mov_b32 s16, m0
	s_mov_b32 m0, s17
	s_nop 0
	global_load_lds_dwordx4 v[80:81], off
	s_mov_b32 m0, s16
	v_lshl_add_u64 v[80:81], v[172:173], 0, s[62:63]
	s_mov_b32 s16, m0
	s_mov_b32 m0, s35
	s_nop 0
	global_load_lds_dwordx4 v[80:81], off
	s_mov_b32 m0, s16
	v_add_f32_e32 v174, v174, v132
	v_mfma_f32_32x32x16_bf16 v[48:63], v[156:159], v[178:181], v[48:63]
	ds_read_b64_tr_b16 v[92:93], v177 offset:40960
	ds_read_b64_tr_b16 v[94:95], v177 offset:41472
	v_exp_f32_e32 v112, v112
	v_exp_f32_e32 v113, v113
	v_mfma_f32_32x32x16_bf16 v[32:47], v[156:159], v[96:99], v[32:47]
	ds_read_b64_tr_b16 v[170:171], v177 offset:45056
	ds_read_b64_tr_b16 v[172:173], v177 offset:45568
	v_exp_f32_e32 v114, v114
	v_exp_f32_e32 v115, v115
	ds_read_b128 v[80:83], v234 offset:8192
	ds_read_b128 v[96:99], v234 offset:12288
	v_mfma_f32_32x32x16_bf16 v[48:63], v[152:155], v[100:103], v[48:63]
	ds_read_b64_tr_b16 v[178:179], v177 offset:41984
	ds_read_b64_tr_b16 v[180:181], v177 offset:42496
	v_exp_f32_e32 v116, v116
	v_exp_f32_e32 v117, v117
	ds_read_b128 v[164:167], v235 offset:8192
	ds_read_b128 v[140:143], v235 offset:12288
	v_mfma_f32_32x32x16_bf16 v[32:47], v[152:155], v[104:107], v[32:47]
	ds_read_b64_tr_b16 v[100:101], v177 offset:46080
	ds_read_b64_tr_b16 v[102:103], v177 offset:46592
	v_exp_f32_e32 v118, v118
	v_exp_f32_e32 v119, v119
	ds_read_b128 v[160:163], v236 offset:8192
	ds_read_b128 v[132:135], v236 offset:12288
	v_mfma_f32_32x32x16_bf16 v[48:63], v[148:151], v[108:111], v[48:63]
	ds_read_b64_tr_b16 v[104:105], v177 offset:43008
	ds_read_b64_tr_b16 v[106:107], v177 offset:43520
	v_exp_f32_e32 v120, v120
	v_exp_f32_e32 v121, v121
	ds_read_b128 v[136:139], v237 offset:8192
	ds_read_b128 v[128:131], v237 offset:12288
	v_mfma_f32_32x32x16_bf16 v[32:47], v[148:151], v[190:193], v[32:47]
	ds_read_b64_tr_b16 v[108:109], v177 offset:47104
	ds_read_b64_tr_b16 v[110:111], v177 offset:47616
	v_exp_f32_e32 v122, v122
	v_exp_f32_e32 v123, v123
	v_mfma_f32_32x32x16_bf16 v[48:63], v[144:147], v[84:87], v[48:63]
	ds_read_b64_tr_b16 v[190:191], v177 offset:44032
	ds_read_b64_tr_b16 v[192:193], v177 offset:44544
	v_exp_f32_e32 v124, v124
	v_exp_f32_e32 v125, v125
	v_mfma_f32_32x32x16_bf16 v[32:47], v[144:147], v[88:91], v[32:47]
	ds_read_b64_tr_b16 v[84:85], v177 offset:48128
	ds_read_b64_tr_b16 v[86:87], v177 offset:48640
	v_exp_f32_e32 v126, v126
	v_exp_f32_e32 v127, v127
	s_waitcnt lgkmcnt(14)
	v_mfma_f32_32x32x16_bf16 v[16:31], v[156:159], v[92:95], v[16:31]
	v_exp_f32_e32 v64, v64
	v_exp_f32_e32 v65, v65
	v_mfma_f32_32x32x16_bf16 v[0:15], v[156:159], v[170:173], v[0:15]
	v_exp_f32_e32 v66, v66
	v_exp_f32_e32 v67, v67
	v_mfma_f32_32x32x16_bf16 v[16:31], v[152:155], v[178:181], v[16:31]
	v_exp_f32_e32 v68, v68
	v_exp_f32_e32 v69, v69
	s_waitcnt lgkmcnt(12)
	v_mfma_f32_32x32x16_bf16 v[0:15], v[152:155], v[100:103], v[0:15]
	v_exp_f32_e32 v70, v70
	v_exp_f32_e32 v71, v71
	s_waitcnt lgkmcnt(8)
	v_mfma_f32_32x32x16_bf16 v[16:31], v[148:151], v[104:107], v[16:31]
	v_exp_f32_e32 v72, v72
	v_exp_f32_e32 v73, v73
	s_waitcnt lgkmcnt(4)
	v_mfma_f32_32x32x16_bf16 v[0:15], v[148:151], v[108:111], v[0:15]
	v_exp_f32_e32 v74, v74
	v_exp_f32_e32 v75, v75
	s_waitcnt lgkmcnt(2)
	v_mfma_f32_32x32x16_bf16 v[16:31], v[144:147], v[190:193], v[16:31]
	v_exp_f32_e32 v76, v76
	v_exp_f32_e32 v77, v77
	s_waitcnt lgkmcnt(0)
	v_mfma_f32_32x32x16_bf16 v[0:15], v[144:147], v[84:87], v[0:15]
	v_exp_f32_e32 v78, v78
	v_exp_f32_e32 v79, v79
	s_waitcnt vmcnt(0) lgkmcnt(0)
	s_barrier
;   #define RESC() do{ if(!NOMAX&&resc){ asm volatile("s_waitcnt lgkmcnt(0)":::"memory"); \
;       _Pragma("unroll") for(int d_=0;d_<2*VM;++d_) _Pragma("unroll") for(int r=0;r<16;++r)o[d_][r]*=wsf[crow(r,hi)]; } }while(0)
; template<int THRL,int VM,bool NOMAX> __device__ __forceinline__ void attn_unit(const bf16*Qb,const bf16*__restrict__ Kh,const bf16*__restrict__ Vh,bf16*Ob,const int NT,const int sp,float*wscr,char*shm){
;     ...
;   STEP(pB0,pB1,pA0,pA1,NT-1,false,false,false); RESC();
	ds_read_b64_tr_b16 v[170:171], v168 offset:24576
	ds_read_b64_tr_b16 v[172:173], v168 offset:25088
	v_add_f32_e32 v88, v112, v113
	ds_read_b128 v[84:87], v188
	v_add_f32_e32 v88, v114, v88
	v_add_f32_e32 v88, v115, v88
	v_add_f32_e32 v88, v116, v88
	v_add_f32_e32 v104, v117, v88
	v_cvt_pk_bf16_f32 v156, v112, v113
	v_cvt_pk_bf16_f32 v157, v114, v115
	s_waitcnt lgkmcnt(0)
	v_mfma_f32_32x32x16_bf16 v[80:95], v[80:83], v[84:87], 0
	ds_read_b64_tr_b16 v[112:113], v168 offset:28672
	ds_read_b64_tr_b16 v[114:115], v168 offset:29184
	ds_read_b128 v[100:103], v188
	v_add_f32_e32 v104, v118, v104
	v_add_f32_e32 v104, v119, v104
	v_add_f32_e32 v104, v120, v104
	v_add_f32_e32 v144, v121, v104
	v_cvt_pk_bf16_f32 v158, v116, v117
	v_cvt_pk_bf16_f32 v159, v118, v119
	s_waitcnt lgkmcnt(0)
	v_mfma_f32_32x32x16_bf16 v[96:111], v[96:99], v[100:103], 0
	ds_read_b64_tr_b16 v[116:117], v168 offset:25600
	ds_read_b64_tr_b16 v[118:119], v168 offset:26112
	ds_read_b128 v[178:181], v188 offset:1024
	v_add_f32_e32 v144, v122, v144
	v_add_f32_e32 v144, v123, v144
	v_add_f32_e32 v144, v124, v144
	v_add_f32_e32 v144, v125, v144
	v_cvt_pk_bf16_f32 v152, v120, v121
	v_cvt_pk_bf16_f32 v153, v122, v123
	s_waitcnt lgkmcnt(0)
	v_mfma_f32_32x32x16_bf16 v[80:95], v[164:167], v[178:181], v[80:95]
	ds_read_b64_tr_b16 v[120:121], v168 offset:29696
	ds_read_b64_tr_b16 v[122:123], v168 offset:30208
	ds_read_b128 v[164:167], v188 offset:1024
	v_add_f32_e32 v144, v126, v144
	v_add_f32_e32 v144, v127, v144
	v_add_f32_e32 v144, v64, v144
	v_add_f32_e32 v144, v65, v144
	v_cvt_pk_bf16_f32 v154, v124, v125
	v_cvt_pk_bf16_f32 v155, v126, v127
	s_waitcnt lgkmcnt(0)
	v_mfma_f32_32x32x16_bf16 v[96:111], v[140:143], v[164:167], v[96:111]
	ds_read_b64_tr_b16 v[124:125], v168 offset:26624
	ds_read_b64_tr_b16 v[126:127], v168 offset:27136
	ds_read_b128 v[140:143], v188 offset:2048
	v_add_f32_e32 v144, v66, v144
	v_add_f32_e32 v144, v67, v144
	v_add_f32_e32 v144, v68, v144
	v_add_f32_e32 v144, v69, v144
	v_cvt_pk_bf16_f32 v148, v64, v65
	v_cvt_pk_bf16_f32 v149, v66, v67
	s_waitcnt lgkmcnt(0)
	v_mfma_f32_32x32x16_bf16 v[80:95], v[160:163], v[140:143], v[80:95]
	ds_read_b64_tr_b16 v[64:65], v168 offset:30720
	ds_read_b64_tr_b16 v[66:67], v168 offset:31232
	ds_read_b128 v[140:143], v188 offset:2048
	v_add_f32_e32 v144, v70, v144
	v_add_f32_e32 v144, v71, v144
	v_add_f32_e32 v144, v72, v144
	v_add_f32_e32 v144, v73, v144
	v_cvt_pk_bf16_f32 v150, v68, v69
	v_cvt_pk_bf16_f32 v151, v70, v71
	s_waitcnt lgkmcnt(0)
	v_mfma_f32_32x32x16_bf16 v[96:111], v[132:135], v[140:143], v[96:111]
	ds_read_b64_tr_b16 v[68:69], v168 offset:27648
	ds_read_b64_tr_b16 v[70:71], v168 offset:28160
	ds_read_b128 v[132:135], v188 offset:3072
	v_add_f32_e32 v140, v74, v144
	v_add_f32_e32 v140, v75, v140
	v_add_f32_e32 v140, v76, v140
	v_add_f32_e32 v140, v77, v140
	v_cvt_pk_bf16_f32 v144, v72, v73
	v_cvt_pk_bf16_f32 v145, v74, v75
	s_waitcnt lgkmcnt(0)
	v_mfma_f32_32x32x16_bf16 v[80:95], v[136:139], v[132:135], v[80:95]
	ds_read_b64_tr_b16 v[72:73], v168 offset:31744
	ds_read_b64_tr_b16 v[74:75], v168 offset:32256
	ds_read_b128 v[132:135], v188 offset:3072
	v_add_f32_e32 v136, v78, v140
	v_add_f32_e32 v136, v79, v136
	v_add_f32_e32 v136, 0, v136
	v_cvt_pk_bf16_f32 v146, v76, v77
	v_cvt_pk_bf16_f32 v147, v78, v79
	s_waitcnt lgkmcnt(0)
	v_mfma_f32_32x32x16_bf16 v[96:111], v[128:131], v[132:135], v[96:111]
	v_mfma_f32_32x32x16_bf16 v[48:63], v[156:159], v[170:173], v[48:63]
	ds_read_b64_tr_b16 v[76:77], v168 offset:32768
	ds_read_b64_tr_b16 v[78:79], v168 offset:33280
	v_exp_f32_e32 v80, v80
	v_exp_f32_e32 v81, v81
	v_mfma_f32_32x32x16_bf16 v[32:47], v[156:159], v[112:115], v[32:47]
	ds_read_b64_tr_b16 v[128:129], v168 offset:36864
	ds_read_b64_tr_b16 v[130:131], v168 offset:37376
	v_exp_f32_e32 v82, v82
	v_exp_f32_e32 v83, v83
	v_mfma_f32_32x32x16_bf16 v[48:63], v[152:155], v[116:119], v[48:63]
	ds_read_b64_tr_b16 v[112:113], v168 offset:33792
	ds_read_b64_tr_b16 v[114:115], v168 offset:34304
	v_exp_f32_e32 v84, v84
	v_exp_f32_e32 v85, v85
	v_mfma_f32_32x32x16_bf16 v[32:47], v[152:155], v[120:123], v[32:47]
	ds_read_b64_tr_b16 v[116:117], v168 offset:37888
	ds_read_b64_tr_b16 v[118:119], v168 offset:38400
	v_exp_f32_e32 v86, v86
	v_exp_f32_e32 v87, v87
	v_mfma_f32_32x32x16_bf16 v[48:63], v[148:151], v[124:127], v[48:63]
	ds_read_b64_tr_b16 v[120:121], v168 offset:34816
	ds_read_b64_tr_b16 v[122:123], v168 offset:35328
	v_exp_f32_e32 v88, v88
	v_exp_f32_e32 v89, v89
	v_mfma_f32_32x32x16_bf16 v[32:47], v[148:151], v[64:67], v[32:47]
	ds_read_b64_tr_b16 v[124:125], v168 offset:38912
	ds_read_b64_tr_b16 v[126:127], v168 offset:39424
	v_exp_f32_e32 v90, v90
	v_exp_f32_e32 v91, v91
	v_mfma_f32_32x32x16_bf16 v[48:63], v[144:147], v[68:71], v[48:63]
	ds_read_b64_tr_b16 v[64:65], v168 offset:35840
	ds_read_b64_tr_b16 v[66:67], v168 offset:36352
	v_exp_f32_e32 v92, v92
	v_exp_f32_e32 v93, v93
	v_mfma_f32_32x32x16_bf16 v[32:47], v[144:147], v[72:75], v[32:47]
	ds_read_b64_tr_b16 v[68:69], v168 offset:39936
	ds_read_b64_tr_b16 v[70:71], v168 offset:40448
	v_exp_f32_e32 v94, v94
	v_exp_f32_e32 v95, v95
	s_waitcnt lgkmcnt(14)
	v_mfma_f32_32x32x16_bf16 v[16:31], v[156:159], v[76:79], v[16:31]
	v_exp_f32_e32 v96, v96
	v_exp_f32_e32 v97, v97
	s_waitcnt lgkmcnt(12)
; #define SBAR() __builtin_amdgcn_sched_barrier(0)
;   #define PKW(P,B) cvtpk_s(P[B],P[B+1])
; __device__ __forceinline__ void pv(f32x16*o,int vb,bf16x8 pa0,bf16x8 pa1,bf16x8 pa2,bf16x8 pa3){
;   #pragma unroll
;   for(int d0=0;d0<2;++d0){s16x4 lo[4],hi[4];
;     #pragma unroll
;     for(int ks=0;ks<4;++ks){
;       asm volatile("ds_read_b64_tr_b16 %0,%1 offset:%c2":"=&v"(lo[ks]):"v"(vb),"i"(d0*4096+ks*1024):"memory");
;       asm volatile("ds_read_b64_tr_b16 %0,%1 offset:%c2":"=&v"(hi[ks]):"v"(vb),"i"(d0*4096+ks*1024+512):"memory");}
;     asm volatile("s_waitcnt lgkmcnt(0)":::"memory");SBAR();
;     ...
;     o[d0]=__builtin_amdgcn_mfma_f32_32x32x16_bf16(pa0,PK(0),o[d0],0,0,0);
;     o[d0]=__builtin_amdgcn_mfma_f32_32x32x16_bf16(pa1,PK(1),o[d0],0,0,0);
;     o[d0]=__builtin_amdgcn_mfma_f32_32x32x16_bf16(pa2,PK(2),o[d0],0,0,0);
;     o[d0]=__builtin_amdgcn_mfma_f32_32x32x16_bf16(pa3,PK(3),o[d0],0,0,0);
;     ...
;   }
; template<int THRL,int VM,bool NOMAX> __device__ __forceinline__ void attn_unit(const bf16*Qb,const bf16*__restrict__ Kh,const bf16*__restrict__ Vh,bf16*Ob,const int NT,const int sp,float*wscr,char*shm){
;     ...
;   { float sacc=pB0[0]+pB0[1]; _Pragma("unroll") for(int r=2;r<16;++r)sacc+=pB0[r]; _Pragma("unroll") for(int r=0;r<16;++r)sacc+=pB1[r]; l_reg+=sacc;
;     pw0=(u32x4){PKW(pB0,0),PKW(pB0,2),PKW(pB0,4),PKW(pB0,6)};pw1=(u32x4){PKW(pB0,8),PKW(pB0,10),PKW(pB0,12),PKW(pB0,14)};pw2=(u32x4){PKW(pB1,0),PKW(pB1,2),PKW(pB1,4),PKW(pB1,6)};pw3=(u32x4){PKW(pB1,8),PKW(pB1,10),PKW(pB1,12),PKW(pB1,14)};
;     SBAR(); pv(o,vb0+VM*sl_cur,PAF(0),PAF(1),PAF(2),PAF(3)); if constexpr(VM==2) pv(o+2,vb0+VM*sl_cur+8192,PAF(0),PAF(1),PAF(2),PAF(3)); }
;     ...
;   {auto rr=__builtin_amdgcn_permlane32_swap(__float_as_uint(l_reg),__float_as_uint(l_reg),false,false);l_reg=__uint_as_float(rr[0])+__uint_as_float(rr[1]);}
;   if(hi==0)wsf[32+r32]=l_reg;asm volatile("s_waitcnt lgkmcnt(0)":::"memory");
	v_mfma_f32_32x32x16_bf16 v[0:15], v[156:159], v[128:131], v[0:15]
	v_exp_f32_e32 v98, v98
	v_exp_f32_e32 v99, v99
	s_waitcnt lgkmcnt(10)
	v_mfma_f32_32x32x16_bf16 v[16:31], v[152:155], v[112:115], v[16:31]
	v_exp_f32_e32 v100, v100
	v_exp_f32_e32 v101, v101
	s_waitcnt lgkmcnt(8)
	v_mfma_f32_32x32x16_bf16 v[0:15], v[152:155], v[116:119], v[0:15]
	v_exp_f32_e32 v102, v102
	v_exp_f32_e32 v103, v103
	s_waitcnt lgkmcnt(6)
	v_mfma_f32_32x32x16_bf16 v[16:31], v[148:151], v[120:123], v[16:31]
	v_exp_f32_e32 v104, v104
	v_exp_f32_e32 v105, v105
	s_waitcnt lgkmcnt(4)
	v_mfma_f32_32x32x16_bf16 v[0:15], v[148:151], v[124:127], v[0:15]
	v_exp_f32_e32 v106, v106
	v_exp_f32_e32 v107, v107
	s_waitcnt lgkmcnt(2)
	v_mfma_f32_32x32x16_bf16 v[16:31], v[144:147], v[64:67], v[16:31]
	v_exp_f32_e32 v108, v108
	v_exp_f32_e32 v109, v109
	s_waitcnt lgkmcnt(0)
	v_mfma_f32_32x32x16_bf16 v[0:15], v[144:147], v[68:71], v[0:15]
	v_exp_f32_e32 v110, v110
	v_exp_f32_e32 v111, v111
	v_add_f32_e32 v64, v80, v81
	v_add_f32_e32 v64, v82, v64
	v_add_f32_e32 v64, v83, v64
	v_add_f32_e32 v64, v84, v64
	v_add_f32_e32 v64, v85, v64
	v_add_f32_e32 v64, v86, v64
	v_add_f32_e32 v64, v87, v64
	v_add_f32_e32 v64, v88, v64
	v_add_f32_e32 v64, v89, v64
	v_add_f32_e32 v64, v90, v64
	v_add_f32_e32 v64, v91, v64
	v_add_f32_e32 v64, v92, v64
	v_add_f32_e32 v64, v93, v64
	v_add_f32_e32 v64, v94, v64
	v_add_f32_e32 v64, v95, v64
	v_add_f32_e32 v64, v64, v96
	v_add_f32_e32 v64, v97, v64
	v_add_f32_e32 v64, v98, v64
	v_add_f32_e32 v64, v99, v64
	v_add_f32_e32 v64, v100, v64
	v_add_f32_e32 v64, v101, v64
	v_add_f32_e32 v64, v102, v64
	v_add_f32_e32 v64, v103, v64
	v_add_f32_e32 v64, v104, v64
	v_add_f32_e32 v64, v105, v64
	v_add_f32_e32 v64, v106, v64
	v_add_f32_e32 v64, v107, v64
	v_add_f32_e32 v64, v108, v64
	v_add_f32_e32 v64, v109, v64
	v_add_f32_e32 v64, v110, v64
	v_add_f32_e32 v64, v111, v64
	v_add_f32_e32 v65, v174, v136
	v_add_f32_e32 v64, v65, v64
	v_cvt_pk_bf16_f32 v66, v80, v81
	v_cvt_pk_bf16_f32 v67, v82, v83
	v_cvt_pk_bf16_f32 v68, v84, v85
	v_cvt_pk_bf16_f32 v69, v86, v87
	v_cvt_pk_bf16_f32 v70, v88, v89
	v_cvt_pk_bf16_f32 v71, v90, v91
	v_cvt_pk_bf16_f32 v72, v92, v93
	v_cvt_pk_bf16_f32 v73, v94, v95
	v_cvt_pk_bf16_f32 v74, v96, v97
	v_cvt_pk_bf16_f32 v75, v98, v99
	v_cvt_pk_bf16_f32 v76, v100, v101
	v_cvt_pk_bf16_f32 v77, v102, v103
	v_cvt_pk_bf16_f32 v78, v104, v105
	v_cvt_pk_bf16_f32 v79, v106, v107
	v_cvt_pk_bf16_f32 v80, v108, v109
	v_cvt_pk_bf16_f32 v81, v110, v111
	v_add_u32_e32 v65, 0x4000, v176
	ds_read_b64_tr_b16 v[82:83],v65 offset:0
	ds_read_b64_tr_b16 v[84:85],v65 offset:512
	ds_read_b64_tr_b16 v[86:87],v65 offset:1024
	ds_read_b64_tr_b16 v[88:89],v65 offset:1536
	ds_read_b64_tr_b16 v[90:91],v65 offset:2048
	ds_read_b64_tr_b16 v[92:93],v65 offset:2560
	ds_read_b64_tr_b16 v[94:95],v65 offset:3072
	ds_read_b64_tr_b16 v[96:97],v65 offset:3584
	s_waitcnt lgkmcnt(0)
	s_nop 0
	v_mfma_f32_32x32x16_bf16 v[48:63], v[66:69], v[82:85], v[48:63]
	ds_read_b64_tr_b16 v[82:83],v65 offset:4096
	ds_read_b64_tr_b16 v[84:85],v65 offset:4608
	v_mfma_f32_32x32x16_bf16 v[48:63], v[70:73], v[86:89], v[48:63]
	ds_read_b64_tr_b16 v[86:87],v65 offset:5120
	ds_read_b64_tr_b16 v[88:89],v65 offset:5632
	v_mfma_f32_32x32x16_bf16 v[48:63], v[74:77], v[90:93], v[48:63]
	ds_read_b64_tr_b16 v[90:91],v65 offset:6144
	ds_read_b64_tr_b16 v[92:93],v65 offset:6656
	ds_read_b64_tr_b16 v[98:99],v65 offset:7168
	ds_read_b64_tr_b16 v[100:101],v65 offset:7680
	s_waitcnt lgkmcnt(0)
	v_mfma_f32_32x32x16_bf16 v[48:63], v[78:81], v[94:97], v[48:63]
	v_mfma_f32_32x32x16_bf16 v[32:47], v[66:69], v[82:85], v[32:47]
	v_add_u32_e32 v65, 0x6000, v176
	ds_read_b64_tr_b16 v[82:83],v65 offset:0
	ds_read_b64_tr_b16 v[84:85],v65 offset:512
	v_mfma_f32_32x32x16_bf16 v[32:47], v[70:73], v[86:89], v[32:47]
	ds_read_b64_tr_b16 v[86:87],v65 offset:1024
	ds_read_b64_tr_b16 v[88:89],v65 offset:1536
	v_mfma_f32_32x32x16_bf16 v[32:47], v[74:77], v[90:93], v[32:47]
	ds_read_b64_tr_b16 v[90:91],v65 offset:2048
	ds_read_b64_tr_b16 v[92:93],v65 offset:2560
	ds_read_b64_tr_b16 v[94:95],v65 offset:3072
	ds_read_b64_tr_b16 v[96:97],v65 offset:3584
	s_waitcnt lgkmcnt(0)
	v_mfma_f32_32x32x16_bf16 v[32:47], v[78:81], v[98:101], v[32:47]
	v_mfma_f32_32x32x16_bf16 v[16:31], v[66:69], v[82:85], v[16:31]
	ds_read_b64_tr_b16 v[82:83],v65 offset:4096
	ds_read_b64_tr_b16 v[84:85],v65 offset:4608
	v_mfma_f32_32x32x16_bf16 v[16:31], v[70:73], v[86:89], v[16:31]
	ds_read_b64_tr_b16 v[86:87],v65 offset:5120
	ds_read_b64_tr_b16 v[88:89],v65 offset:5632
	v_mfma_f32_32x32x16_bf16 v[16:31], v[74:77], v[90:93], v[16:31]
	ds_read_b64_tr_b16 v[90:91],v65 offset:6144
	ds_read_b64_tr_b16 v[92:93],v65 offset:6656
	ds_read_b64_tr_b16 v[98:99],v65 offset:7168
	ds_read_b64_tr_b16 v[100:101],v65 offset:7680
	s_waitcnt lgkmcnt(0)
	v_mfma_f32_32x32x16_bf16 v[16:31], v[78:81], v[94:97], v[16:31]
	v_mfma_f32_32x32x16_bf16 v[0:15], v[66:69], v[82:85], v[0:15]
	v_mov_b32_e32 v65, v64
	s_nop 1
	v_permlane32_swap_b32_e32 v64, v65
	v_cmp_gt_u32_e32 vcc, 32, v187
	v_mfma_f32_32x32x16_bf16 v[0:15], v[70:73], v[86:89], v[0:15]
	v_mfma_f32_32x32x16_bf16 v[0:15], v[74:77], v[90:93], v[0:15]
	v_mfma_f32_32x32x16_bf16 v[0:15], v[78:81], v[98:101], v[0:15]
	s_and_saveexec_b64 s[16:17], vcc
	s_cbranch_execz .LBB0_859
	v_add_f32_e32 v64, v64, v65
	v_lshl_add_u32 v65, v186, 2, s34
	ds_write_b32 v65, v64 offset:128
	s_branch .LBB0_859

; #define WAIT_BAR(N) asm volatile("s_waitcnt vmcnt(" #N ") lgkmcnt(0)\n\ts_barrier":::"memory")
;   #define RESC() do{ if(!NOMAX&&resc){ asm volatile("s_waitcnt lgkmcnt(0)":::"memory"); \
;       _Pragma("unroll") for(int d_=0;d_<2*VM;++d_) _Pragma("unroll") for(int r=0;r<16;++r)o[d_][r]*=wsf[crow(r,hi)]; } }while(0)
;   #define ROT() do{sl_prev=sl_cur;sl_cur=sl_next;sl_next=(sl_next==(NSLOT-1)*SLOTB)?0:sl_next+SLOTB;}while(0)
; template<int THRL,int VM,bool NOMAX> __device__ __forceinline__ void attn_unit(const bf16*Qb,const bf16*__restrict__ Kh,const bf16*__restrict__ Vh,bf16*Ob,const int NT,const int sp,float*wscr,char*shm){
;     ...
;   for(;t+5<NT;t+=2){
;     STEP(pB0,pB1,pA0,pA1,t,true,true,true);     if constexpr(VM==2){WAIT_BAR(3);}else{WAIT_BAR(2);} RESC(); ROT();
;     STEP(pA0,pA1,pB0,pB1,t+1,true,true,true);   if constexpr(VM==2){WAIT_BAR(3);}else{WAIT_BAR(2);} RESC(); ROT();
.LBB0_874:
	v_mfma_f32_32x32x16_bf16 v[112:127], v[100:103], v[218:221], 0
	v_lshl_add_u32 v206, s89, 1, v188
	s_add_i32 s88, s87, s17
	v_lshl_add_u64 v[238:239], v[180:181], 0, s[56:57]
	s_mov_b32 s89, m0
	s_mov_b32 m0, s88
	s_nop 0
	global_load_lds_dwordx4 v[238:239], off
	s_mov_b32 m0, s89
	s_lshl_b32 s88, s86, 1
	v_lshl_add_u64 v[238:239], v[178:179], 0, s[56:57]
	s_add_i32 s88, s88, s16
	s_mov_b32 s89, m0
	s_mov_b32 m0, s88
	s_nop 0
	global_load_lds_dwordx4 v[238:239], off
	s_mov_b32 m0, s89
	v_lshl_add_u64 v[238:239], v[176:177], 0, s[56:57]
	s_addk_i32 s88, 0x2000
	s_mov_b32 s89, m0
	s_mov_b32 m0, s88
	s_nop 0
	global_load_lds_dwordx4 v[238:239], off
	s_mov_b32 m0, s89
	ds_read_b64_tr_b16 v[194:195], v206 offset:24576
	ds_read_b64_tr_b16 v[196:197], v206 offset:25088
	v_add_f32_e32 v108, v80, v81
	v_add_f32_e32 v108, v82, v108
	v_add_f32_e32 v108, v83, v108
	v_add_f32_e32 v108, v84, v108
	v_add_f32_e32 v108, v85, v108
	v_cvt_pk_bf16_f32 v156, v80, v81
	v_cvt_pk_bf16_f32 v157, v82, v83
	ds_read_b64_tr_b16 v[80:81], v206 offset:28672
	ds_read_b64_tr_b16 v[82:83], v206 offset:29184
	v_add_f32_e32 v104, v86, v108
	v_add_f32_e32 v104, v87, v104
	v_add_f32_e32 v104, v88, v104
	v_add_f32_e32 v144, v89, v104
	v_mfma_f32_32x32x16_bf16 v[96:111], v[96:99], v[218:221], 0
	v_cvt_pk_bf16_f32 v158, v84, v85
	v_cvt_pk_bf16_f32 v159, v86, v87
	ds_read_b64_tr_b16 v[84:85], v206 offset:25600
	ds_read_b64_tr_b16 v[86:87], v206 offset:26112
	v_add_f32_e32 v144, v90, v144
	v_add_f32_e32 v144, v91, v144
	v_add_f32_e32 v144, v92, v144
	v_add_f32_e32 v144, v93, v144
	v_cvt_pk_bf16_f32 v152, v88, v89
	v_cvt_pk_bf16_f32 v153, v90, v91
	v_mfma_f32_32x32x16_bf16 v[112:127], v[164:167], v[222:225], v[112:127]
	ds_read_b64_tr_b16 v[88:89], v206 offset:29696
	ds_read_b64_tr_b16 v[90:91], v206 offset:30208
	v_add_f32_e32 v144, v94, v144
	v_add_f32_e32 v144, v95, v144
	v_add_f32_e32 v144, v64, v144
	v_add_f32_e32 v144, v65, v144
	v_mfma_f32_32x32x16_bf16 v[96:111], v[160:163], v[222:225], v[96:111]
	v_cvt_pk_bf16_f32 v154, v92, v93
	v_cvt_pk_bf16_f32 v155, v94, v95
	ds_read_b64_tr_b16 v[92:93], v206 offset:26624
	ds_read_b64_tr_b16 v[94:95], v206 offset:27136
	v_add_f32_e32 v144, v66, v144
	v_add_f32_e32 v144, v67, v144
	v_add_f32_e32 v144, v68, v144
	v_add_f32_e32 v144, v69, v144
	v_cvt_pk_bf16_f32 v148, v64, v65
	v_cvt_pk_bf16_f32 v149, v66, v67
	v_mfma_f32_32x32x16_bf16 v[112:127], v[140:143], v[226:229], v[112:127]
	ds_read_b64_tr_b16 v[198:199], v206 offset:30720
	ds_read_b64_tr_b16 v[200:201], v206 offset:31232
	v_add_f32_e32 v140, v70, v144
	v_add_f32_e32 v140, v71, v140
	v_add_f32_e32 v140, v72, v140
	v_add_f32_e32 v140, v73, v140
	v_mfma_f32_32x32x16_bf16 v[96:111], v[136:139], v[226:229], v[96:111]
	v_cvt_pk_bf16_f32 v150, v68, v69
	v_cvt_pk_bf16_f32 v151, v70, v71
	ds_read_b64_tr_b16 v[202:203], v206 offset:27648
	ds_read_b64_tr_b16 v[204:205], v206 offset:28160
	v_add_f32_e32 v68, v74, v140
	v_add_f32_e32 v68, v75, v68
	v_add_f32_e32 v68, v76, v68
	v_add_f32_e32 v68, v77, v68
	v_cvt_pk_bf16_f32 v144, v72, v73
	v_cvt_pk_bf16_f32 v145, v74, v75
	v_mfma_f32_32x32x16_bf16 v[112:127], v[132:135], v[230:233], v[112:127]
	ds_read_b64_tr_b16 v[72:73], v206 offset:31744
	ds_read_b64_tr_b16 v[74:75], v206 offset:32256
	v_add_f32_e32 v68, v78, v68
	v_add_f32_e32 v68, v79, v68
	v_add_f32_e32 v68, 0, v68
	v_cvt_pk_bf16_f32 v146, v76, v77
	v_mfma_f32_32x32x16_bf16 v[96:111], v[128:131], v[230:233], v[96:111]
	v_cvt_pk_bf16_f32 v147, v78, v79
	v_add_f32_e32 v193, v193, v68
	s_waitcnt lgkmcnt(12)
	v_mfma_f32_32x32x16_bf16 v[48:63], v[156:159], v[194:197], v[48:63]
	ds_read_b64_tr_b16 v[76:77], v206 offset:32768
	ds_read_b64_tr_b16 v[78:79], v206 offset:33280
	v_exp_f32_e32 v112, v112
	v_exp_f32_e32 v113, v113
	v_mfma_f32_32x32x16_bf16 v[32:47], v[156:159], v[80:83], v[32:47]
	ds_read_b64_tr_b16 v[194:195], v206 offset:36864
	ds_read_b64_tr_b16 v[196:197], v206 offset:37376
	v_exp_f32_e32 v114, v114
	v_exp_f32_e32 v115, v115
	v_add_u32_e32 v242, s86, v234
	v_add_u32_e32 v243, s86, v235
	v_add_u32_e32 v244, s86, v236
	v_add_u32_e32 v245, s86, v237
	ds_read_b128 v[68:71], v242
	ds_read_b128 v[64:67], v242 offset:4096
	s_waitcnt lgkmcnt(14)
	v_mfma_f32_32x32x16_bf16 v[48:63], v[152:155], v[84:87], v[48:63]
	ds_read_b64_tr_b16 v[80:81], v206 offset:33792
	ds_read_b64_tr_b16 v[82:83], v206 offset:34304
	v_exp_f32_e32 v116, v116
	v_exp_f32_e32 v117, v117
	ds_read_b128 v[164:167], v243
	ds_read_b128 v[140:143], v243 offset:4096
	v_mfma_f32_32x32x16_bf16 v[32:47], v[152:155], v[88:91], v[32:47]
	ds_read_b64_tr_b16 v[84:85], v206 offset:37888
	ds_read_b64_tr_b16 v[86:87], v206 offset:38400
	v_exp_f32_e32 v118, v118
	v_exp_f32_e32 v119, v119
	ds_read_b128 v[160:163], v244
	ds_read_b128 v[132:135], v244 offset:4096
	s_waitcnt lgkmcnt(14)
	v_mfma_f32_32x32x16_bf16 v[48:63], v[148:151], v[92:95], v[48:63]
	ds_read_b64_tr_b16 v[88:89], v206 offset:34816
	ds_read_b64_tr_b16 v[90:91], v206 offset:35328
	v_exp_f32_e32 v120, v120
	v_exp_f32_e32 v121, v121
	ds_read_b128 v[136:139], v245
	ds_read_b128 v[128:131], v245 offset:4096
	v_mfma_f32_32x32x16_bf16 v[32:47], v[148:151], v[198:201], v[32:47]
	ds_read_b64_tr_b16 v[92:93], v206 offset:38912
	ds_read_b64_tr_b16 v[94:95], v206 offset:39424
	v_exp_f32_e32 v122, v122
	v_exp_f32_e32 v123, v123
	s_waitcnt lgkmcnt(14)
	v_mfma_f32_32x32x16_bf16 v[48:63], v[144:147], v[202:205], v[48:63]
	ds_read_b64_tr_b16 v[198:199], v206 offset:35840
	ds_read_b64_tr_b16 v[200:201], v206 offset:36352
	v_exp_f32_e32 v124, v124
	v_exp_f32_e32 v125, v125
	v_mfma_f32_32x32x16_bf16 v[32:47], v[144:147], v[72:75], v[32:47]
	ds_read_b64_tr_b16 v[202:203], v206 offset:39936
	ds_read_b64_tr_b16 v[204:205], v206 offset:40448
	v_exp_f32_e32 v126, v126
	v_exp_f32_e32 v127, v127
	s_waitcnt lgkmcnt(14)
	v_mfma_f32_32x32x16_bf16 v[16:31], v[156:159], v[76:79], v[16:31]
	v_exp_f32_e32 v96, v96
	v_exp_f32_e32 v97, v97
	v_mfma_f32_32x32x16_bf16 v[0:15], v[156:159], v[194:197], v[0:15]
	v_exp_f32_e32 v98, v98
	v_exp_f32_e32 v99, v99
	v_mfma_f32_32x32x16_bf16 v[16:31], v[152:155], v[80:83], v[16:31]
	v_exp_f32_e32 v100, v100
	v_exp_f32_e32 v101, v101
	s_waitcnt lgkmcnt(12)
	v_mfma_f32_32x32x16_bf16 v[0:15], v[152:155], v[84:87], v[0:15]
	v_exp_f32_e32 v102, v102
	v_exp_f32_e32 v103, v103
	s_waitcnt lgkmcnt(8)
	v_mfma_f32_32x32x16_bf16 v[16:31], v[148:151], v[88:91], v[16:31]
	v_exp_f32_e32 v104, v104
	v_exp_f32_e32 v105, v105
	s_waitcnt lgkmcnt(4)
	v_mfma_f32_32x32x16_bf16 v[0:15], v[148:151], v[92:95], v[0:15]
	v_exp_f32_e32 v106, v106
	v_exp_f32_e32 v107, v107
	s_waitcnt lgkmcnt(2)
	v_mfma_f32_32x32x16_bf16 v[16:31], v[144:147], v[198:201], v[16:31]
	v_exp_f32_e32 v108, v108
	v_exp_f32_e32 v109, v109
	s_waitcnt lgkmcnt(0)
	v_mfma_f32_32x32x16_bf16 v[0:15], v[144:147], v[202:205], v[0:15]
	v_exp_f32_e32 v110, v110
	v_exp_f32_e32 v111, v111
	s_waitcnt vmcnt(3) lgkmcnt(0)
	s_barrier
; #define WAIT_BAR(N) asm volatile("s_waitcnt vmcnt(" #N ") lgkmcnt(0)\n\ts_barrier":::"memory")
;   #define RESC() do{ if(!NOMAX&&resc){ asm volatile("s_waitcnt lgkmcnt(0)":::"memory"); \
;       _Pragma("unroll") for(int d_=0;d_<2*VM;++d_) _Pragma("unroll") for(int r=0;r<16;++r)o[d_][r]*=wsf[crow(r,hi)]; } }while(0)
;   #define ROT() do{sl_prev=sl_cur;sl_cur=sl_next;sl_next=(sl_next==(NSLOT-1)*SLOTB)?0:sl_next+SLOTB;}while(0)
; template<int THRL,int VM,bool NOMAX> __device__ __forceinline__ void attn_unit(const bf16*Qb,const bf16*__restrict__ Kh,const bf16*__restrict__ Vh,bf16*Ob,const int NT,const int sp,float*wscr,char*shm){
;     ...
;   for(;t+5<NT;t+=2){
;     STEP(pB0,pB1,pA0,pA1,t,true,true,true);     if constexpr(VM==2){WAIT_BAR(3);}else{WAIT_BAR(2);} RESC(); ROT();
;     STEP(pA0,pA1,pB0,pB1,t+1,true,true,true);   if constexpr(VM==2){WAIT_BAR(3);}else{WAIT_BAR(2);} RESC(); ROT();
	v_mfma_f32_32x32x16_bf16 v[80:95], v[68:71], v[218:221], 0
	s_add_i32 s88, s86, 0x2000
	s_cmpk_lg_i32 s86, 0x4000
	s_cselect_b32 s88, s88, 0
	v_lshl_add_u32 v206, s87, 1, v188
	s_add_i32 s87, s86, s17
	s_mov_b32 s89, m0
	s_mov_b32 m0, s87
	s_nop 0
	global_load_lds_dwordx4 v[180:181], off
	s_mov_b32 m0, s89
	s_lshl_b32 s87, s88, 1
	s_add_i32 s87, s87, s16
	s_mov_b32 s89, m0
	s_mov_b32 m0, s87
	s_nop 0
	global_load_lds_dwordx4 v[178:179], off
	s_mov_b32 m0, s89
	s_addk_i32 s87, 0x2000
	s_mov_b32 s89, m0
	s_mov_b32 m0, s87
	s_nop 0
	global_load_lds_dwordx4 v[176:177], off
	s_mov_b32 m0, s89
	ds_read_b64_tr_b16 v[194:195], v206 offset:24576
	ds_read_b64_tr_b16 v[196:197], v206 offset:25088
	v_add_f32_e32 v76, v112, v113
	v_add_f32_e32 v76, v114, v76
	v_add_f32_e32 v76, v115, v76
	v_add_f32_e32 v76, v116, v76
	v_add_f32_e32 v76, v117, v76
	v_cvt_pk_bf16_f32 v156, v112, v113
	v_cvt_pk_bf16_f32 v157, v114, v115
	ds_read_b64_tr_b16 v[112:113], v206 offset:28672
	ds_read_b64_tr_b16 v[114:115], v206 offset:29184
	v_add_f32_e32 v72, v118, v76
	v_add_f32_e32 v72, v119, v72
	v_add_f32_e32 v72, v120, v72
	v_add_f32_e32 v144, v121, v72
	v_mfma_f32_32x32x16_bf16 v[64:79], v[64:67], v[218:221], 0
	v_cvt_pk_bf16_f32 v158, v116, v117
	v_cvt_pk_bf16_f32 v159, v118, v119
	ds_read_b64_tr_b16 v[116:117], v206 offset:25600
	ds_read_b64_tr_b16 v[118:119], v206 offset:26112
	v_add_f32_e32 v144, v122, v144
	v_add_f32_e32 v144, v123, v144
	v_add_f32_e32 v144, v124, v144
	v_add_f32_e32 v144, v125, v144
	v_mfma_f32_32x32x16_bf16 v[80:95], v[164:167], v[222:225], v[80:95]
	v_cvt_pk_bf16_f32 v152, v120, v121
	v_cvt_pk_bf16_f32 v153, v122, v123
	ds_read_b64_tr_b16 v[120:121], v206 offset:29696
	ds_read_b64_tr_b16 v[122:123], v206 offset:30208
	v_add_f32_e32 v144, v126, v144
	v_add_f32_e32 v144, v127, v144
	v_add_f32_e32 v144, v96, v144
	v_add_f32_e32 v144, v97, v144
	v_mfma_f32_32x32x16_bf16 v[64:79], v[140:143], v[222:225], v[64:79]
	v_cvt_pk_bf16_f32 v154, v124, v125
	v_cvt_pk_bf16_f32 v155, v126, v127
	ds_read_b64_tr_b16 v[124:125], v206 offset:26624
	ds_read_b64_tr_b16 v[126:127], v206 offset:27136
	v_add_f32_e32 v144, v98, v144
	v_add_f32_e32 v144, v99, v144
	v_add_f32_e32 v144, v100, v144
	v_add_f32_e32 v144, v101, v144
	v_mfma_f32_32x32x16_bf16 v[80:95], v[160:163], v[226:229], v[80:95]
	v_cvt_pk_bf16_f32 v148, v96, v97
	v_cvt_pk_bf16_f32 v149, v98, v99
	ds_read_b64_tr_b16 v[198:199], v206 offset:30720
	ds_read_b64_tr_b16 v[200:201], v206 offset:31232
	v_add_f32_e32 v140, v102, v144
	v_add_f32_e32 v140, v103, v140
	v_add_f32_e32 v140, v104, v140
	v_add_f32_e32 v140, v105, v140
	v_mfma_f32_32x32x16_bf16 v[64:79], v[132:135], v[226:229], v[64:79]
	v_cvt_pk_bf16_f32 v150, v100, v101
	v_cvt_pk_bf16_f32 v151, v102, v103
	ds_read_b64_tr_b16 v[202:203], v206 offset:27648
	ds_read_b64_tr_b16 v[204:205], v206 offset:28160
	v_add_f32_e32 v100, v106, v140
	v_add_f32_e32 v100, v107, v100
	v_add_f32_e32 v100, v108, v100
	v_add_f32_e32 v100, v109, v100
	v_mfma_f32_32x32x16_bf16 v[80:95], v[136:139], v[230:233], v[80:95]
	v_cvt_pk_bf16_f32 v144, v104, v105
	v_cvt_pk_bf16_f32 v145, v106, v107
	ds_read_b64_tr_b16 v[104:105], v206 offset:31744
	ds_read_b64_tr_b16 v[106:107], v206 offset:32256
	v_add_f32_e32 v100, v110, v100
	v_add_f32_e32 v100, v111, v100
	v_add_f32_e32 v100, 0, v100
	v_cvt_pk_bf16_f32 v146, v108, v109
	v_mfma_f32_32x32x16_bf16 v[64:79], v[128:131], v[230:233], v[64:79]
	v_cvt_pk_bf16_f32 v147, v110, v111
	v_add_f32_e32 v193, v193, v100
	s_waitcnt lgkmcnt(12)
	v_mfma_f32_32x32x16_bf16 v[48:63], v[156:159], v[194:197], v[48:63]
	ds_read_b64_tr_b16 v[108:109], v206 offset:32768
	ds_read_b64_tr_b16 v[110:111], v206 offset:33280
	v_exp_f32_e32 v80, v80
	v_exp_f32_e32 v81, v81
	v_mfma_f32_32x32x16_bf16 v[32:47], v[156:159], v[112:115], v[32:47]
	ds_read_b64_tr_b16 v[194:195], v206 offset:36864
	ds_read_b64_tr_b16 v[196:197], v206 offset:37376
	v_exp_f32_e32 v82, v82
	v_exp_f32_e32 v83, v83
	v_add_u32_e32 v242, s88, v234
	v_add_u32_e32 v243, s88, v235
	v_add_u32_e32 v244, s88, v236
	v_add_u32_e32 v245, s88, v237
	ds_read_b128 v[100:103], v242
	ds_read_b128 v[96:99], v242 offset:4096
	s_waitcnt lgkmcnt(14)
	v_mfma_f32_32x32x16_bf16 v[48:63], v[152:155], v[116:119], v[48:63]
	ds_read_b64_tr_b16 v[112:113], v206 offset:33792
	ds_read_b64_tr_b16 v[114:115], v206 offset:34304
	v_exp_f32_e32 v84, v84
	v_exp_f32_e32 v85, v85
	ds_read_b128 v[164:167], v243
	ds_read_b128 v[160:163], v243 offset:4096
	v_mfma_f32_32x32x16_bf16 v[32:47], v[152:155], v[120:123], v[32:47]
	ds_read_b64_tr_b16 v[116:117], v206 offset:37888
	ds_read_b64_tr_b16 v[118:119], v206 offset:38400
	v_exp_f32_e32 v86, v86
	v_exp_f32_e32 v87, v87
	ds_read_b128 v[140:143], v244
	ds_read_b128 v[136:139], v244 offset:4096
	s_waitcnt lgkmcnt(14)
	v_mfma_f32_32x32x16_bf16 v[48:63], v[148:151], v[124:127], v[48:63]
	ds_read_b64_tr_b16 v[120:121], v206 offset:34816
	ds_read_b64_tr_b16 v[122:123], v206 offset:35328
	v_exp_f32_e32 v88, v88
	v_exp_f32_e32 v89, v89
	ds_read_b128 v[132:135], v245
	ds_read_b128 v[128:131], v245 offset:4096
	v_mfma_f32_32x32x16_bf16 v[32:47], v[148:151], v[198:201], v[32:47]
	ds_read_b64_tr_b16 v[124:125], v206 offset:38912
	ds_read_b64_tr_b16 v[126:127], v206 offset:39424
	v_exp_f32_e32 v90, v90
	v_exp_f32_e32 v91, v91
	s_waitcnt lgkmcnt(14)
	v_mfma_f32_32x32x16_bf16 v[48:63], v[144:147], v[202:205], v[48:63]
	ds_read_b64_tr_b16 v[198:199], v206 offset:35840
	ds_read_b64_tr_b16 v[200:201], v206 offset:36352
	v_exp_f32_e32 v92, v92
	v_exp_f32_e32 v93, v93
	v_mfma_f32_32x32x16_bf16 v[32:47], v[144:147], v[104:107], v[32:47]
	ds_read_b64_tr_b16 v[202:203], v206 offset:39936
	ds_read_b64_tr_b16 v[204:205], v206 offset:40448
	v_exp_f32_e32 v94, v94
	v_exp_f32_e32 v95, v95
	s_waitcnt lgkmcnt(14)
	v_mfma_f32_32x32x16_bf16 v[16:31], v[156:159], v[108:111], v[16:31]
	v_exp_f32_e32 v64, v64
	v_exp_f32_e32 v65, v65
	v_mfma_f32_32x32x16_bf16 v[0:15], v[156:159], v[194:197], v[0:15]
	v_exp_f32_e32 v66, v66
	v_exp_f32_e32 v67, v67
	v_mfma_f32_32x32x16_bf16 v[16:31], v[152:155], v[112:115], v[16:31]
	v_exp_f32_e32 v68, v68
	v_exp_f32_e32 v69, v69
	s_waitcnt lgkmcnt(12)
	v_mfma_f32_32x32x16_bf16 v[0:15], v[152:155], v[116:119], v[0:15]
	v_exp_f32_e32 v70, v70
	v_exp_f32_e32 v71, v71
	s_waitcnt lgkmcnt(8)
	v_mfma_f32_32x32x16_bf16 v[16:31], v[148:151], v[120:123], v[16:31]
	v_exp_f32_e32 v72, v72
	v_exp_f32_e32 v73, v73
	s_waitcnt lgkmcnt(4)
	v_mfma_f32_32x32x16_bf16 v[0:15], v[148:151], v[124:127], v[0:15]
	v_exp_f32_e32 v74, v74
	v_exp_f32_e32 v75, v75
	s_waitcnt lgkmcnt(2)
	v_mfma_f32_32x32x16_bf16 v[16:31], v[144:147], v[198:201], v[16:31]
	v_exp_f32_e32 v76, v76
	v_exp_f32_e32 v77, v77
	s_waitcnt lgkmcnt(0)
	v_mfma_f32_32x32x16_bf16 v[0:15], v[144:147], v[202:205], v[0:15]
	v_exp_f32_e32 v78, v78
	v_exp_f32_e32 v79, v79
	s_add_i32 s90, s88, 0x2000
	s_waitcnt vmcnt(3) lgkmcnt(0)
	s_barrier
; #define WAIT_BAR(N) asm volatile("s_waitcnt vmcnt(" #N ") lgkmcnt(0)\n\ts_barrier":::"memory")
;   #define RESC() do{ if(!NOMAX&&resc){ asm volatile("s_waitcnt lgkmcnt(0)":::"memory"); \
;       _Pragma("unroll") for(int d_=0;d_<2*VM;++d_) _Pragma("unroll") for(int r=0;r<16;++r)o[d_][r]*=wsf[crow(r,hi)]; } }while(0)
;   #define ROT() do{sl_prev=sl_cur;sl_cur=sl_next;sl_next=(sl_next==(NSLOT-1)*SLOTB)?0:sl_next+SLOTB;}while(0)
;   #define ENDW(tt) do{ if((tt)+3<NT){ if constexpr(VM==2){WAIT_BAR(3);}else{WAIT_BAR(2);} } else if((tt)+2<NT){ if constexpr(VM==2){WAIT_BAR(2);}else{WAIT_BAR(1);} } else {WAIT_BAR(0);} }while(0)
; template<int THRL,int VM,bool NOMAX> __device__ __forceinline__ void attn_unit(const bf16*Qb,const bf16*__restrict__ Kh,const bf16*__restrict__ Vh,bf16*Ob,const int NT,const int sp,float*wscr,char*shm){
;     ...
;   for(;t+5<NT;t+=2){
;     STEP(pB0,pB1,pA0,pA1,t,true,true,true);     if constexpr(VM==2){WAIT_BAR(3);}else{WAIT_BAR(2);} RESC(); ROT();
;     STEP(pA0,pA1,pB0,pB1,t+1,true,true,true);   if constexpr(VM==2){WAIT_BAR(3);}else{WAIT_BAR(2);} RESC(); ROT();
;   }
;     ...
;   for(;t+1<NT;t+=2){
;     STEP(pB0,pB1,pA0,pA1,t,(t+3<NT),(t+1<NT),(t+1<NT));       ENDW(t);   RESC(); ROT();
	s_cmpk_lg_i32 s88, 0x4000
	s_mov_b32 s89, s86
	s_cselect_b32 s86, s90, 0
	s_add_i32 s85, s85, 2
	v_lshl_add_u64 v[176:177], v[176:177], 0, s[58:59]
	v_lshl_add_u64 v[178:179], v[178:179], 0, s[58:59]
	v_lshl_add_u64 v[180:181], v[180:181], 0, s[58:59]
	s_mov_b32 s87, s88
	s_cmp_lt_u32 s85, 57
	s_cbranch_scc1 .LBB0_874
	s_and_b32 s34, s34, 0x3fffffc0
	s_lshl_b32 s34, s34, 2
	s_add_i32 s34, s34, 0
	s_add_i32 s34, s34, 0x12000
	s_cmp_lg_u32 0, -1
	s_cselect_b32 s85, 0, 0
	s_add_i32 s86, s85, 0x6000
	v_add_u32_e32 v104, s86, v191
	v_add3_u32 v176, v104, v190, v192
	v_add_u32_e32 v177, 0x6000, v188
	ds_read_b64_tr_b16 v[178:179], v188 offset:40960
	ds_read_b64_tr_b16 v[180:181], v188 offset:41472
	v_add_f32_e32 v108, v80, v81
	ds_read_b128 v[104:107], v168
	v_add_f32_e32 v108, v82, v108
	v_add_f32_e32 v108, v83, v108
	v_add_f32_e32 v108, v84, v108
	v_add_f32_e32 v108, v85, v108
	v_cvt_pk_bf16_f32 v156, v80, v81
	v_cvt_pk_bf16_f32 v157, v82, v83
	s_waitcnt lgkmcnt(0)
	v_mfma_f32_32x32x16_bf16 v[112:127], v[100:103], v[104:107], 0
	ds_read_b64_tr_b16 v[80:81], v188 offset:45056
	ds_read_b64_tr_b16 v[82:83], v188 offset:45568
	ds_read_b128 v[100:103], v168
	v_add_f32_e32 v104, v86, v108
	v_add_f32_e32 v104, v87, v104
	v_add_f32_e32 v104, v88, v104
	v_add_f32_e32 v144, v89, v104
	v_cvt_pk_bf16_f32 v158, v84, v85
	v_cvt_pk_bf16_f32 v159, v86, v87
	s_waitcnt lgkmcnt(0)
	v_mfma_f32_32x32x16_bf16 v[96:111], v[96:99], v[100:103], 0
	ds_read_b64_tr_b16 v[84:85], v188 offset:41984
	ds_read_b64_tr_b16 v[86:87], v188 offset:42496
	ds_read_b128 v[194:197], v168 offset:1024
	v_add_f32_e32 v144, v90, v144
	v_add_f32_e32 v144, v91, v144
	v_add_f32_e32 v144, v92, v144
	v_add_f32_e32 v144, v93, v144
	v_cvt_pk_bf16_f32 v152, v88, v89
	v_cvt_pk_bf16_f32 v153, v90, v91
	s_waitcnt lgkmcnt(0)
	v_mfma_f32_32x32x16_bf16 v[112:127], v[164:167], v[194:197], v[112:127]
	ds_read_b64_tr_b16 v[88:89], v188 offset:46080
	ds_read_b64_tr_b16 v[90:91], v188 offset:46592
	ds_read_b128 v[164:167], v168 offset:1024
	v_add_f32_e32 v144, v94, v144
	v_add_f32_e32 v144, v95, v144
	v_add_f32_e32 v144, v64, v144
	v_add_f32_e32 v144, v65, v144
	v_cvt_pk_bf16_f32 v154, v92, v93
	v_cvt_pk_bf16_f32 v155, v94, v95
	s_waitcnt lgkmcnt(0)
	v_mfma_f32_32x32x16_bf16 v[96:111], v[160:163], v[164:167], v[96:111]
	ds_read_b64_tr_b16 v[194:195], v188 offset:43008
	ds_read_b64_tr_b16 v[196:197], v188 offset:43520
	ds_read_b128 v[92:95], v168 offset:2048
	v_add_f32_e32 v144, v66, v144
	v_add_f32_e32 v144, v67, v144
	v_add_f32_e32 v144, v68, v144
	v_add_f32_e32 v144, v69, v144
	v_cvt_pk_bf16_f32 v148, v64, v65
	v_cvt_pk_bf16_f32 v149, v66, v67
	s_waitcnt lgkmcnt(0)
	v_mfma_f32_32x32x16_bf16 v[112:127], v[140:143], v[92:95], v[112:127]
	ds_read_b64_tr_b16 v[140:141], v188 offset:47104
	ds_read_b64_tr_b16 v[142:143], v188 offset:47616
	ds_read_b128 v[64:67], v168 offset:2048
	v_add_f32_e32 v92, v70, v144
	v_add_f32_e32 v92, v71, v92
	v_add_f32_e32 v92, v72, v92
	v_add_f32_e32 v92, v73, v92
	v_cvt_pk_bf16_f32 v150, v68, v69
	v_cvt_pk_bf16_f32 v151, v70, v71
	s_waitcnt lgkmcnt(0)
	v_mfma_f32_32x32x16_bf16 v[96:111], v[136:139], v[64:67], v[96:111]
	ds_read_b64_tr_b16 v[136:137], v188 offset:44032
	ds_read_b64_tr_b16 v[138:139], v188 offset:44544
	ds_read_b128 v[64:67], v168 offset:3072
	v_add_f32_e32 v68, v74, v92
	v_add_f32_e32 v68, v75, v68
	v_add_f32_e32 v68, v76, v68
	v_add_f32_e32 v68, v77, v68
	v_cvt_pk_bf16_f32 v144, v72, v73
	v_cvt_pk_bf16_f32 v145, v74, v75
	s_waitcnt lgkmcnt(0)
	v_mfma_f32_32x32x16_bf16 v[112:127], v[132:135], v[64:67], v[112:127]
	ds_read_b64_tr_b16 v[72:73], v188 offset:48128
	ds_read_b64_tr_b16 v[74:75], v188 offset:48640
	ds_read_b128 v[64:67], v168 offset:3072
	v_add_f32_e32 v68, v78, v68
	v_add_f32_e32 v68, v79, v68
	v_add_f32_e32 v68, 0, v68
	v_cvt_pk_bf16_f32 v146, v76, v77
	v_cvt_pk_bf16_f32 v147, v78, v79
	s_waitcnt lgkmcnt(0)
	v_mfma_f32_32x32x16_bf16 v[96:111], v[128:131], v[64:67], v[96:111]
	s_add_i32 s85, s85, s35
	v_lshl_add_u64 v[64:65], v[174:175], 0, s[60:61]
	s_add_i32 s35, s85, 0x4000
	s_mov_b32 s86, m0
	s_mov_b32 m0, s35
	s_nop 0
	global_load_lds_dwordx4 v[64:65], off
	s_mov_b32 m0, s86
	v_lshl_add_u64 v[64:65], v[170:171], 0, s[62:63]
	s_mov_b32 s35, m0
	s_mov_b32 m0, s16
	s_nop 0
	global_load_lds_dwordx4 v[64:65], off
	s_mov_b32 m0, s35
	v_lshl_add_u64 v[64:65], v[172:173], 0, s[62:63]
	s_add_i32 s35, s16, 0x2000
	s_mov_b32 s86, m0
	s_mov_b32 m0, s35
	s_nop 0
	global_load_lds_dwordx4 v[64:65], off
	s_mov_b32 m0, s86
	v_add_f32_e32 v198, v193, v68
	v_mfma_f32_32x32x16_bf16 v[48:63], v[156:159], v[178:181], v[48:63]
	ds_read_b64_tr_b16 v[76:77], v188 offset:49152
	ds_read_b64_tr_b16 v[78:79], v188 offset:49664
	v_exp_f32_e32 v112, v112
	v_exp_f32_e32 v113, v113
	v_mfma_f32_32x32x16_bf16 v[32:47], v[156:159], v[80:83], v[32:47]
	ds_read_b64_tr_b16 v[128:129], v188 offset:53248
	ds_read_b64_tr_b16 v[130:131], v188 offset:53760
	v_exp_f32_e32 v114, v114
	v_exp_f32_e32 v115, v115
	ds_read_b128 v[68:71], v234
	ds_read_b128 v[64:67], v234 offset:4096
	v_mfma_f32_32x32x16_bf16 v[48:63], v[152:155], v[84:87], v[48:63]
	ds_read_b64_tr_b16 v[132:133], v188 offset:50176
	ds_read_b64_tr_b16 v[134:135], v188 offset:50688
	v_exp_f32_e32 v116, v116
	v_exp_f32_e32 v117, v117
	ds_read_b128 v[164:167], v235
	ds_read_b128 v[92:95], v235 offset:4096
	v_mfma_f32_32x32x16_bf16 v[32:47], v[152:155], v[88:91], v[32:47]
	ds_read_b64_tr_b16 v[178:179], v188 offset:54272
	ds_read_b64_tr_b16 v[180:181], v188 offset:54784
	v_exp_f32_e32 v118, v118
	v_exp_f32_e32 v119, v119
	ds_read_b128 v[160:163], v236
	ds_read_b128 v[84:87], v236 offset:4096
	v_mfma_f32_32x32x16_bf16 v[48:63], v[148:151], v[194:197], v[48:63]
	ds_read_b64_tr_b16 v[190:191], v188 offset:51200
	ds_read_b64_tr_b16 v[192:193], v188 offset:51712
	v_exp_f32_e32 v120, v120
	v_exp_f32_e32 v121, v121
	ds_read_b128 v[88:91], v237
	ds_read_b128 v[80:83], v237 offset:4096
	v_mfma_f32_32x32x16_bf16 v[32:47], v[148:151], v[140:143], v[32:47]
	ds_read_b64_tr_b16 v[194:195], v188 offset:55296
	ds_read_b64_tr_b16 v[196:197], v188 offset:55808
	v_exp_f32_e32 v122, v122
	v_exp_f32_e32 v123, v123
	v_mfma_f32_32x32x16_bf16 v[48:63], v[144:147], v[136:139], v[48:63]
	ds_read_b64_tr_b16 v[140:141], v188 offset:52224
	ds_read_b64_tr_b16 v[142:143], v188 offset:52736
	v_exp_f32_e32 v124, v124
	v_exp_f32_e32 v125, v125
	v_mfma_f32_32x32x16_bf16 v[32:47], v[144:147], v[72:75], v[32:47]
	ds_read_b64_tr_b16 v[136:137], v188 offset:56320
	ds_read_b64_tr_b16 v[138:139], v188 offset:56832
	v_exp_f32_e32 v126, v126
	v_exp_f32_e32 v127, v127
	s_waitcnt lgkmcnt(14)
;   #define RESC() do{ if(!NOMAX&&resc){ asm volatile("s_waitcnt lgkmcnt(0)":::"memory"); \
;       _Pragma("unroll") for(int d_=0;d_<2*VM;++d_) _Pragma("unroll") for(int r=0;r<16;++r)o[d_][r]*=wsf[crow(r,hi)]; } }while(0)
;   #define ROT() do{sl_prev=sl_cur;sl_cur=sl_next;sl_next=(sl_next==(NSLOT-1)*SLOTB)?0:sl_next+SLOTB;}while(0)
;   #define ENDW(tt) do{ if((tt)+3<NT){ if constexpr(VM==2){WAIT_BAR(3);}else{WAIT_BAR(2);} } else if((tt)+2<NT){ if constexpr(VM==2){WAIT_BAR(2);}else{WAIT_BAR(1);} } else {WAIT_BAR(0);} }while(0)
; template<int THRL,int VM,bool NOMAX> __device__ __forceinline__ void attn_unit(const bf16*Qb,const bf16*__restrict__ Kh,const bf16*__restrict__ Vh,bf16*Ob,const int NT,const int sp,float*wscr,char*shm){
;     ...
;   for(;t+1<NT;t+=2){
;     STEP(pB0,pB1,pA0,pA1,t,(t+3<NT),(t+1<NT),(t+1<NT));       ENDW(t);   RESC(); ROT();
	v_mfma_f32_32x32x16_bf16 v[16:31], v[156:159], v[76:79], v[16:31]
	v_exp_f32_e32 v96, v96
	v_exp_f32_e32 v97, v97
	v_mfma_f32_32x32x16_bf16 v[0:15], v[156:159], v[128:131], v[0:15]
	v_exp_f32_e32 v98, v98
	v_exp_f32_e32 v99, v99
	v_mfma_f32_32x32x16_bf16 v[16:31], v[152:155], v[132:135], v[16:31]
	v_exp_f32_e32 v100, v100
	v_exp_f32_e32 v101, v101
	s_waitcnt lgkmcnt(12)
	v_mfma_f32_32x32x16_bf16 v[0:15], v[152:155], v[178:181], v[0:15]
	v_exp_f32_e32 v102, v102
	v_exp_f32_e32 v103, v103
	s_waitcnt lgkmcnt(8)
	v_mfma_f32_32x32x16_bf16 v[16:31], v[148:151], v[190:193], v[16:31]
	v_exp_f32_e32 v104, v104
	v_exp_f32_e32 v105, v105
	s_waitcnt lgkmcnt(4)
	v_mfma_f32_32x32x16_bf16 v[0:15], v[148:151], v[194:197], v[0:15]
	v_exp_f32_e32 v106, v106
	v_exp_f32_e32 v107, v107
	s_waitcnt lgkmcnt(2)
	v_mfma_f32_32x32x16_bf16 v[16:31], v[144:147], v[140:143], v[16:31]
	v_exp_f32_e32 v108, v108
	v_exp_f32_e32 v109, v109
	s_waitcnt lgkmcnt(0)
	v_mfma_f32_32x32x16_bf16 v[0:15], v[144:147], v[136:139], v[0:15]
	v_exp_f32_e32 v110, v110
	v_exp_f32_e32 v111, v111
	s_waitcnt vmcnt(3) lgkmcnt(0)
	s_barrier
	ds_read_b64_tr_b16 v[178:179], v188 offset:57344
	ds_read_b64_tr_b16 v[180:181], v188 offset:57856
	v_add_f32_e32 v76, v112, v113
	ds_read_b128 v[72:75], v168
	v_add_f32_e32 v76, v114, v76
	v_add_f32_e32 v76, v115, v76
	v_add_f32_e32 v76, v116, v76
	v_add_f32_e32 v76, v117, v76
	v_cvt_pk_bf16_f32 v156, v112, v113
	v_cvt_pk_bf16_f32 v157, v114, v115
	s_waitcnt lgkmcnt(0)
	v_mfma_f32_32x32x16_bf16 v[128:143], v[68:71], v[72:75], 0
	ds_read_b64_tr_b16 v[112:113], v188 offset:61440
	ds_read_b64_tr_b16 v[114:115], v188 offset:61952
	ds_read_b128 v[68:71], v168
	v_add_f32_e32 v72, v118, v76
	v_add_f32_e32 v72, v119, v72
	v_add_f32_e32 v72, v120, v72
	v_add_f32_e32 v144, v121, v72
	s_waitcnt lgkmcnt(0)
	v_mfma_f32_32x32x16_bf16 v[64:79], v[64:67], v[68:71], 0
	v_cvt_pk_bf16_f32 v158, v116, v117
	v_cvt_pk_bf16_f32 v159, v118, v119
	ds_read_b64_tr_b16 v[116:117], v188 offset:58368
	ds_read_b64_tr_b16 v[118:119], v188 offset:58880
	ds_read_b128 v[190:193], v168 offset:1024
	v_add_f32_e32 v144, v122, v144
	v_add_f32_e32 v144, v123, v144
	v_add_f32_e32 v144, v124, v144
	v_add_f32_e32 v144, v125, v144
	v_cvt_pk_bf16_f32 v152, v120, v121
	v_cvt_pk_bf16_f32 v153, v122, v123
	s_waitcnt lgkmcnt(0)
	v_mfma_f32_32x32x16_bf16 v[128:143], v[164:167], v[190:193], v[128:143]
	ds_read_b64_tr_b16 v[120:121], v188 offset:62464
	ds_read_b64_tr_b16 v[122:123], v188 offset:62976
	ds_read_b128 v[164:167], v168 offset:1024
	v_add_f32_e32 v144, v126, v144
	v_add_f32_e32 v144, v127, v144
	v_add_f32_e32 v144, v96, v144
	v_add_f32_e32 v144, v97, v144
	s_waitcnt lgkmcnt(0)
	v_mfma_f32_32x32x16_bf16 v[64:79], v[92:95], v[164:167], v[64:79]
	v_cvt_pk_bf16_f32 v154, v124, v125
	v_cvt_pk_bf16_f32 v155, v126, v127
	ds_read_b64_tr_b16 v[92:93], v188 offset:59392
	ds_read_b64_tr_b16 v[94:95], v188 offset:59904
	ds_read_b128 v[124:127], v168 offset:2048
	v_add_f32_e32 v144, v98, v144
	v_add_f32_e32 v144, v99, v144
	v_add_f32_e32 v144, v100, v144
	v_add_f32_e32 v144, v101, v144
	v_cvt_pk_bf16_f32 v148, v96, v97
	v_cvt_pk_bf16_f32 v149, v98, v99
	s_waitcnt lgkmcnt(0)
	v_mfma_f32_32x32x16_bf16 v[128:143], v[160:163], v[124:127], v[128:143]
	ds_read_b64_tr_b16 v[96:97], v188 offset:63488
	ds_read_b64_tr_b16 v[98:99], v188 offset:64000
	ds_read_b128 v[124:127], v168 offset:2048
	v_add_f32_e32 v144, v102, v144
	v_add_f32_e32 v144, v103, v144
	v_add_f32_e32 v144, v104, v144
	v_add_f32_e32 v144, v105, v144
	s_waitcnt lgkmcnt(0)
	v_mfma_f32_32x32x16_bf16 v[64:79], v[84:87], v[124:127], v[64:79]
	v_cvt_pk_bf16_f32 v150, v100, v101
	v_cvt_pk_bf16_f32 v151, v102, v103
	ds_read_b64_tr_b16 v[100:101], v188 offset:60416
	ds_read_b64_tr_b16 v[102:103], v188 offset:60928
	ds_read_b128 v[84:87], v168 offset:3072
	v_add_f32_e32 v124, v106, v144
	v_add_f32_e32 v124, v107, v124
	v_add_f32_e32 v124, v108, v124
	v_add_f32_e32 v124, v109, v124
	v_cvt_pk_bf16_f32 v144, v104, v105
	v_cvt_pk_bf16_f32 v145, v106, v107
	s_waitcnt lgkmcnt(0)
	v_mfma_f32_32x32x16_bf16 v[128:143], v[88:91], v[84:87], v[128:143]
	ds_read_b64_tr_b16 v[88:89], v188 offset:64512
	ds_read_b64_tr_b16 v[90:91], v188 offset:65024
	ds_read_b128 v[84:87], v168 offset:3072
	v_add_f32_e32 v104, v110, v124
	v_add_f32_e32 v104, v111, v104
	v_add_f32_e32 v104, 0, v104
	v_cvt_pk_bf16_f32 v146, v108, v109
	s_waitcnt lgkmcnt(0)
;   #define RESC() do{ if(!NOMAX&&resc){ asm volatile("s_waitcnt lgkmcnt(0)":::"memory"); \
;       _Pragma("unroll") for(int d_=0;d_<2*VM;++d_) _Pragma("unroll") for(int r=0;r<16;++r)o[d_][r]*=wsf[crow(r,hi)]; } }while(0)
;   #define ROT() do{sl_prev=sl_cur;sl_cur=sl_next;sl_next=(sl_next==(NSLOT-1)*SLOTB)?0:sl_next+SLOTB;}while(0)
;   #define ENDW(tt) do{ if((tt)+3<NT){ if constexpr(VM==2){WAIT_BAR(3);}else{WAIT_BAR(2);} } else if((tt)+2<NT){ if constexpr(VM==2){WAIT_BAR(2);}else{WAIT_BAR(1);} } else {WAIT_BAR(0);} }while(0)
; template<int THRL,int VM,bool NOMAX> __device__ __forceinline__ void attn_unit(const bf16*Qb,const bf16*__restrict__ Kh,const bf16*__restrict__ Vh,bf16*Ob,const int NT,const int sp,float*wscr,char*shm){
;     ...
;   for(;t+1<NT;t+=2){
;     STEP(pB0,pB1,pA0,pA1,t,(t+3<NT),(t+1<NT),(t+1<NT));       ENDW(t);   RESC(); ROT();
	v_mfma_f32_32x32x16_bf16 v[64:79], v[80:83], v[84:87], v[64:79]
	v_cvt_pk_bf16_f32 v147, v110, v111
	v_lshl_add_u64 v[80:81], v[174:175], 0, s[64:65]
	s_mov_b32 s86, m0
	s_mov_b32 m0, s17
	s_nop 0
	global_load_lds_dwordx4 v[80:81], off
	s_mov_b32 m0, s86
	v_lshl_add_u64 v[80:81], v[170:171], 0, s[66:67]
	s_add_i32 s17, s85, 0xa000
	s_mov_b32 s86, m0
	s_mov_b32 m0, s17
	s_nop 0
	global_load_lds_dwordx4 v[80:81], off
	s_mov_b32 m0, s86
	v_lshl_add_u64 v[80:81], v[172:173], 0, s[66:67]
	s_add_i32 s17, s85, 0xc000
	s_mov_b32 s86, m0
	s_mov_b32 m0, s17
	s_nop 0
	global_load_lds_dwordx4 v[80:81], off
	s_mov_b32 m0, s86
	v_add_f32_e32 v198, v198, v104
	v_mfma_f32_32x32x16_bf16 v[48:63], v[156:159], v[178:181], v[48:63]
	ds_read_b64_tr_b16 v[104:105], v177 offset:40960
	ds_read_b64_tr_b16 v[106:107], v177 offset:41472
	v_exp_f32_e32 v128, v128
	v_exp_f32_e32 v129, v129
	v_mfma_f32_32x32x16_bf16 v[32:47], v[156:159], v[112:115], v[32:47]
	ds_read_b64_tr_b16 v[108:109], v177 offset:45056
	ds_read_b64_tr_b16 v[110:111], v177 offset:45568
	v_exp_f32_e32 v130, v130
	v_exp_f32_e32 v131, v131
	ds_read_b128 v[84:87], v234 offset:8192
	ds_read_b128 v[80:83], v234 offset:12288
	v_mfma_f32_32x32x16_bf16 v[48:63], v[152:155], v[116:119], v[48:63]
	ds_read_b64_tr_b16 v[178:179], v177 offset:41984
	ds_read_b64_tr_b16 v[180:181], v177 offset:42496
	v_exp_f32_e32 v132, v132
	v_exp_f32_e32 v133, v133
	ds_read_b128 v[164:167], v235 offset:8192
	ds_read_b128 v[124:127], v235 offset:12288
	v_mfma_f32_32x32x16_bf16 v[32:47], v[152:155], v[120:123], v[32:47]
	ds_read_b64_tr_b16 v[190:191], v177 offset:46080
	ds_read_b64_tr_b16 v[192:193], v177 offset:46592
	v_exp_f32_e32 v134, v134
	v_exp_f32_e32 v135, v135
	ds_read_b128 v[160:163], v236 offset:8192
	ds_read_b128 v[116:119], v236 offset:12288
	v_mfma_f32_32x32x16_bf16 v[48:63], v[148:151], v[92:95], v[48:63]
	ds_read_b64_tr_b16 v[194:195], v177 offset:43008
	ds_read_b64_tr_b16 v[196:197], v177 offset:43520
	v_exp_f32_e32 v136, v136
	v_exp_f32_e32 v137, v137
	ds_read_b128 v[120:123], v237 offset:8192
	ds_read_b128 v[112:115], v237 offset:12288
	v_mfma_f32_32x32x16_bf16 v[32:47], v[148:151], v[96:99], v[32:47]
	ds_read_b64_tr_b16 v[92:93], v177 offset:47104
	ds_read_b64_tr_b16 v[94:95], v177 offset:47616
	v_exp_f32_e32 v138, v138
	v_exp_f32_e32 v139, v139
	v_mfma_f32_32x32x16_bf16 v[48:63], v[144:147], v[100:103], v[48:63]
	ds_read_b64_tr_b16 v[96:97], v177 offset:44032
	ds_read_b64_tr_b16 v[98:99], v177 offset:44544
	v_exp_f32_e32 v140, v140
	v_exp_f32_e32 v141, v141
	v_mfma_f32_32x32x16_bf16 v[32:47], v[144:147], v[88:91], v[32:47]
	ds_read_b64_tr_b16 v[100:101], v177 offset:48128
	ds_read_b64_tr_b16 v[102:103], v177 offset:48640
	v_exp_f32_e32 v142, v142
	v_exp_f32_e32 v143, v143
	s_waitcnt lgkmcnt(14)
	v_mfma_f32_32x32x16_bf16 v[16:31], v[156:159], v[104:107], v[16:31]
	v_exp_f32_e32 v64, v64
	v_exp_f32_e32 v65, v65
	v_mfma_f32_32x32x16_bf16 v[0:15], v[156:159], v[108:111], v[0:15]
	v_exp_f32_e32 v66, v66
	v_exp_f32_e32 v67, v67
	v_mfma_f32_32x32x16_bf16 v[16:31], v[152:155], v[178:181], v[16:31]
	v_exp_f32_e32 v68, v68
	v_exp_f32_e32 v69, v69
	s_waitcnt lgkmcnt(12)
	v_mfma_f32_32x32x16_bf16 v[0:15], v[152:155], v[190:193], v[0:15]
	v_exp_f32_e32 v70, v70
	v_exp_f32_e32 v71, v71
	s_waitcnt lgkmcnt(8)
	v_mfma_f32_32x32x16_bf16 v[16:31], v[148:151], v[194:197], v[16:31]
	v_exp_f32_e32 v72, v72
	v_exp_f32_e32 v73, v73
	s_waitcnt lgkmcnt(4)
	v_mfma_f32_32x32x16_bf16 v[0:15], v[148:151], v[92:95], v[0:15]
	v_exp_f32_e32 v74, v74
	v_exp_f32_e32 v75, v75
	s_waitcnt lgkmcnt(2)
	v_mfma_f32_32x32x16_bf16 v[16:31], v[144:147], v[96:99], v[16:31]
	v_exp_f32_e32 v76, v76
	v_exp_f32_e32 v77, v77
	s_waitcnt lgkmcnt(0)
	v_mfma_f32_32x32x16_bf16 v[0:15], v[144:147], v[100:103], v[0:15]
	v_exp_f32_e32 v78, v78
	v_exp_f32_e32 v79, v79
	s_waitcnt vmcnt(3) lgkmcnt(0)
	s_barrier
	ds_read_b64_tr_b16 v[178:179], v188 offset:24576
	ds_read_b64_tr_b16 v[180:181], v188 offset:25088
	v_add_f32_e32 v92, v128, v129
	ds_read_b128 v[88:91], v168
	v_add_f32_e32 v92, v130, v92
	v_add_f32_e32 v92, v131, v92
	v_add_f32_e32 v92, v132, v92
	v_add_f32_e32 v92, v133, v92
	v_cvt_pk_bf16_f32 v156, v128, v129
	v_cvt_pk_bf16_f32 v157, v130, v131
	s_waitcnt lgkmcnt(0)
	v_mfma_f32_32x32x16_bf16 v[96:111], v[84:87], v[88:91], 0
	ds_read_b64_tr_b16 v[128:129], v188 offset:28672
	ds_read_b64_tr_b16 v[130:131], v188 offset:29184
	ds_read_b128 v[84:87], v168
	v_add_f32_e32 v88, v134, v92
	v_add_f32_e32 v88, v135, v88
	v_add_f32_e32 v88, v136, v88
	v_add_f32_e32 v144, v137, v88
	v_cvt_pk_bf16_f32 v158, v132, v133
	v_cvt_pk_bf16_f32 v159, v134, v135
	s_waitcnt lgkmcnt(0)
	v_mfma_f32_32x32x16_bf16 v[80:95], v[80:83], v[84:87], 0
	ds_read_b64_tr_b16 v[132:133], v188 offset:25600
	ds_read_b64_tr_b16 v[134:135], v188 offset:26112
	ds_read_b128 v[190:193], v168 offset:1024
	v_add_f32_e32 v144, v138, v144
	v_add_f32_e32 v144, v139, v144
	v_add_f32_e32 v144, v140, v144
	v_add_f32_e32 v144, v141, v144
	v_cvt_pk_bf16_f32 v152, v136, v137
	v_cvt_pk_bf16_f32 v153, v138, v139
	s_waitcnt lgkmcnt(0)
	v_mfma_f32_32x32x16_bf16 v[96:111], v[164:167], v[190:193], v[96:111]
	ds_read_b64_tr_b16 v[136:137], v188 offset:29696
	ds_read_b64_tr_b16 v[138:139], v188 offset:30208
	ds_read_b128 v[164:167], v168 offset:1024
	v_add_f32_e32 v144, v142, v144
	v_add_f32_e32 v144, v143, v144
	v_add_f32_e32 v144, v64, v144
	v_add_f32_e32 v144, v65, v144
	v_cvt_pk_bf16_f32 v154, v140, v141
	v_cvt_pk_bf16_f32 v155, v142, v143
	s_waitcnt lgkmcnt(0)
;   #define RESC() do{ if(!NOMAX&&resc){ asm volatile("s_waitcnt lgkmcnt(0)":::"memory"); \
;       _Pragma("unroll") for(int d_=0;d_<2*VM;++d_) _Pragma("unroll") for(int r=0;r<16;++r)o[d_][r]*=wsf[crow(r,hi)]; } }while(0)
;   #define ROT() do{sl_prev=sl_cur;sl_cur=sl_next;sl_next=(sl_next==(NSLOT-1)*SLOTB)?0:sl_next+SLOTB;}while(0)
;   #define ENDW(tt) do{ if((tt)+3<NT){ if constexpr(VM==2){WAIT_BAR(3);}else{WAIT_BAR(2);} } else if((tt)+2<NT){ if constexpr(VM==2){WAIT_BAR(2);}else{WAIT_BAR(1);} } else {WAIT_BAR(0);} }while(0)
; template<int THRL,int VM,bool NOMAX> __device__ __forceinline__ void attn_unit(const bf16*Qb,const bf16*__restrict__ Kh,const bf16*__restrict__ Vh,bf16*Ob,const int NT,const int sp,float*wscr,char*shm){
;     ...
;   for(;t+1<NT;t+=2){
;     STEP(pB0,pB1,pA0,pA1,t,(t+3<NT),(t+1<NT),(t+1<NT));       ENDW(t);   RESC(); ROT();
	v_mfma_f32_32x32x16_bf16 v[80:95], v[124:127], v[164:167], v[80:95]
	ds_read_b64_tr_b16 v[124:125], v188 offset:26624
	ds_read_b64_tr_b16 v[126:127], v188 offset:27136
	ds_read_b128 v[140:143], v168 offset:2048
	v_add_f32_e32 v144, v66, v144
	v_add_f32_e32 v144, v67, v144
	v_add_f32_e32 v144, v68, v144
	v_add_f32_e32 v144, v69, v144
	v_cvt_pk_bf16_f32 v148, v64, v65
	v_cvt_pk_bf16_f32 v149, v66, v67
	s_waitcnt lgkmcnt(0)
	v_mfma_f32_32x32x16_bf16 v[96:111], v[160:163], v[140:143], v[96:111]
	ds_read_b64_tr_b16 v[190:191], v188 offset:30720
	ds_read_b64_tr_b16 v[192:193], v188 offset:31232
	ds_read_b128 v[64:67], v168 offset:2048
	v_add_f32_e32 v140, v70, v144
	v_add_f32_e32 v140, v71, v140
	v_add_f32_e32 v140, v72, v140
	v_add_f32_e32 v140, v73, v140
	v_cvt_pk_bf16_f32 v150, v68, v69
	v_cvt_pk_bf16_f32 v151, v70, v71
	s_waitcnt lgkmcnt(0)
	v_mfma_f32_32x32x16_bf16 v[80:95], v[116:119], v[64:67], v[80:95]
	ds_read_b64_tr_b16 v[116:117], v188 offset:27648
	ds_read_b64_tr_b16 v[118:119], v188 offset:28160
	ds_read_b128 v[64:67], v168 offset:3072
	v_add_f32_e32 v68, v74, v140
	v_add_f32_e32 v68, v75, v68
	v_add_f32_e32 v68, v76, v68
	v_add_f32_e32 v68, v77, v68
	v_cvt_pk_bf16_f32 v144, v72, v73
	v_cvt_pk_bf16_f32 v145, v74, v75
	s_waitcnt lgkmcnt(0)
	v_mfma_f32_32x32x16_bf16 v[96:111], v[120:123], v[64:67], v[96:111]
	ds_read_b64_tr_b16 v[72:73], v188 offset:31744
	ds_read_b64_tr_b16 v[74:75], v188 offset:32256
	ds_read_b128 v[64:67], v168 offset:3072
	v_add_f32_e32 v68, v78, v68
	v_add_f32_e32 v68, v79, v68
	v_add_f32_e32 v68, 0, v68
	v_cvt_pk_bf16_f32 v146, v76, v77
	v_cvt_pk_bf16_f32 v147, v78, v79
	s_waitcnt lgkmcnt(0)
	v_mfma_f32_32x32x16_bf16 v[80:95], v[112:115], v[64:67], v[80:95]
	v_lshl_add_u64 v[64:65], v[170:171], 0, s[60:61]
	s_add_i32 s17, s85, 0xe000
	s_mov_b32 s86, m0
	s_mov_b32 m0, s17
	s_nop 0
	global_load_lds_dwordx4 v[64:65], off
	s_mov_b32 m0, s86
	v_lshl_add_u64 v[64:65], v[172:173], 0, s[60:61]
	s_add_i32 s85, s85, 0x10000
	s_mov_b32 s17, m0
	s_mov_b32 m0, s85
	s_nop 0
	global_load_lds_dwordx4 v[64:65], off
	s_mov_b32 m0, s17
	v_add_f32_e32 v174, v198, v68
	v_mfma_f32_32x32x16_bf16 v[48:63], v[156:159], v[178:181], v[48:63]
	ds_read_b64_tr_b16 v[76:77], v188 offset:32768
	ds_read_b64_tr_b16 v[78:79], v188 offset:33280
	v_exp_f32_e32 v96, v96
	v_exp_f32_e32 v97, v97
	v_mfma_f32_32x32x16_bf16 v[32:47], v[156:159], v[128:131], v[32:47]
	ds_read_b64_tr_b16 v[112:113], v188 offset:36864
	ds_read_b64_tr_b16 v[114:115], v188 offset:37376
	v_exp_f32_e32 v98, v98
	v_exp_f32_e32 v99, v99
	ds_read_b128 v[68:71], v234 offset:16384
	ds_read_b128 v[64:67], v234 offset:20480
	v_mfma_f32_32x32x16_bf16 v[48:63], v[152:155], v[132:135], v[48:63]
	ds_read_b64_tr_b16 v[120:121], v188 offset:33792
	ds_read_b64_tr_b16 v[122:123], v188 offset:34304
	v_exp_f32_e32 v100, v100
	v_exp_f32_e32 v101, v101
	ds_read_b128 v[164:167], v235 offset:16384
	ds_read_b128 v[140:143], v235 offset:20480
	v_mfma_f32_32x32x16_bf16 v[32:47], v[152:155], v[136:139], v[32:47]
	ds_read_b64_tr_b16 v[178:179], v188 offset:37888
	ds_read_b64_tr_b16 v[180:181], v188 offset:38400
	v_exp_f32_e32 v102, v102
	v_exp_f32_e32 v103, v103
	ds_read_b128 v[160:163], v236 offset:16384
	ds_read_b128 v[132:135], v236 offset:20480
	v_mfma_f32_32x32x16_bf16 v[48:63], v[148:151], v[124:127], v[48:63]
	ds_read_b64_tr_b16 v[194:195], v188 offset:34816
	ds_read_b64_tr_b16 v[196:197], v188 offset:35328
	v_exp_f32_e32 v104, v104
	v_exp_f32_e32 v105, v105
	ds_read_b128 v[136:139], v237 offset:16384
	ds_read_b128 v[128:131], v237 offset:20480
	v_mfma_f32_32x32x16_bf16 v[32:47], v[148:151], v[190:193], v[32:47]
	ds_read_b64_tr_b16 v[124:125], v188 offset:38912
	ds_read_b64_tr_b16 v[126:127], v188 offset:39424
	v_exp_f32_e32 v106, v106
	v_exp_f32_e32 v107, v107
	v_mfma_f32_32x32x16_bf16 v[48:63], v[144:147], v[116:119], v[48:63]
	ds_read_b64_tr_b16 v[190:191], v188 offset:35840
	ds_read_b64_tr_b16 v[192:193], v188 offset:36352
	v_exp_f32_e32 v108, v108
	v_exp_f32_e32 v109, v109
	v_mfma_f32_32x32x16_bf16 v[32:47], v[144:147], v[72:75], v[32:47]
	ds_read_b64_tr_b16 v[116:117], v188 offset:39936
	ds_read_b64_tr_b16 v[118:119], v188 offset:40448
	v_exp_f32_e32 v110, v110
	v_exp_f32_e32 v111, v111
	s_waitcnt lgkmcnt(14)
	v_mfma_f32_32x32x16_bf16 v[16:31], v[156:159], v[76:79], v[16:31]
	v_exp_f32_e32 v80, v80
	v_exp_f32_e32 v81, v81
	v_mfma_f32_32x32x16_bf16 v[0:15], v[156:159], v[112:115], v[0:15]
	v_exp_f32_e32 v82, v82
	v_exp_f32_e32 v83, v83
	v_mfma_f32_32x32x16_bf16 v[16:31], v[152:155], v[120:123], v[16:31]
	v_exp_f32_e32 v84, v84
	v_exp_f32_e32 v85, v85
	s_waitcnt lgkmcnt(12)
	v_mfma_f32_32x32x16_bf16 v[0:15], v[152:155], v[178:181], v[0:15]
	v_exp_f32_e32 v86, v86
	v_exp_f32_e32 v87, v87
	s_waitcnt lgkmcnt(8)
	v_mfma_f32_32x32x16_bf16 v[16:31], v[148:151], v[194:197], v[16:31]
	v_exp_f32_e32 v88, v88
	v_exp_f32_e32 v89, v89
	s_waitcnt lgkmcnt(4)
	v_mfma_f32_32x32x16_bf16 v[0:15], v[148:151], v[124:127], v[0:15]
	v_exp_f32_e32 v90, v90
	v_exp_f32_e32 v91, v91
	s_waitcnt lgkmcnt(2)
	v_mfma_f32_32x32x16_bf16 v[16:31], v[144:147], v[190:193], v[16:31]
	v_exp_f32_e32 v92, v92
	v_exp_f32_e32 v93, v93
	s_waitcnt lgkmcnt(0)
	v_mfma_f32_32x32x16_bf16 v[0:15], v[144:147], v[116:119], v[0:15]
	v_exp_f32_e32 v94, v94
	v_exp_f32_e32 v95, v95
	s_waitcnt vmcnt(2) lgkmcnt(0)
	s_barrier
;   #define RESC() do{ if(!NOMAX&&resc){ asm volatile("s_waitcnt lgkmcnt(0)":::"memory"); \
;       _Pragma("unroll") for(int d_=0;d_<2*VM;++d_) _Pragma("unroll") for(int r=0;r<16;++r)o[d_][r]*=wsf[crow(r,hi)]; } }while(0)
;   #define ROT() do{sl_prev=sl_cur;sl_cur=sl_next;sl_next=(sl_next==(NSLOT-1)*SLOTB)?0:sl_next+SLOTB;}while(0)
;   #define ENDW(tt) do{ if((tt)+3<NT){ if constexpr(VM==2){WAIT_BAR(3);}else{WAIT_BAR(2);} } else if((tt)+2<NT){ if constexpr(VM==2){WAIT_BAR(2);}else{WAIT_BAR(1);} } else {WAIT_BAR(0);} }while(0)
; template<int THRL,int VM,bool NOMAX> __device__ __forceinline__ void attn_unit(const bf16*Qb,const bf16*__restrict__ Kh,const bf16*__restrict__ Vh,bf16*Ob,const int NT,const int sp,float*wscr,char*shm){
;     ...
;   for(;t+1<NT;t+=2){
;     STEP(pB0,pB1,pA0,pA1,t,(t+3<NT),(t+1<NT),(t+1<NT));       ENDW(t);   RESC(); ROT();
	ds_read_b64_tr_b16 v[178:179], v188 offset:40960
	ds_read_b64_tr_b16 v[180:181], v188 offset:41472
	v_add_f32_e32 v76, v96, v97
	ds_read_b128 v[72:75], v168
	v_add_f32_e32 v76, v98, v76
	v_add_f32_e32 v76, v99, v76
	v_add_f32_e32 v76, v100, v76
	v_add_f32_e32 v76, v101, v76
	v_cvt_pk_bf16_f32 v156, v96, v97
	v_cvt_pk_bf16_f32 v157, v98, v99
	s_waitcnt lgkmcnt(0)
	v_mfma_f32_32x32x16_bf16 v[112:127], v[68:71], v[72:75], 0
	ds_read_b64_tr_b16 v[96:97], v188 offset:45056
	ds_read_b64_tr_b16 v[98:99], v188 offset:45568
	ds_read_b128 v[68:71], v168
	v_add_f32_e32 v72, v102, v76
	v_add_f32_e32 v72, v103, v72
	v_add_f32_e32 v72, v104, v72
	v_add_f32_e32 v144, v105, v72
	s_waitcnt lgkmcnt(0)
	v_mfma_f32_32x32x16_bf16 v[64:79], v[64:67], v[68:71], 0
	v_cvt_pk_bf16_f32 v158, v100, v101
	v_cvt_pk_bf16_f32 v159, v102, v103
	ds_read_b64_tr_b16 v[100:101], v188 offset:41984
	ds_read_b64_tr_b16 v[102:103], v188 offset:42496
	ds_read_b128 v[190:193], v168 offset:1024
	v_add_f32_e32 v144, v106, v144
	v_add_f32_e32 v144, v107, v144
	v_add_f32_e32 v144, v108, v144
	v_add_f32_e32 v144, v109, v144
	v_cvt_pk_bf16_f32 v152, v104, v105
	v_cvt_pk_bf16_f32 v153, v106, v107
	s_waitcnt lgkmcnt(0)
	v_mfma_f32_32x32x16_bf16 v[112:127], v[164:167], v[190:193], v[112:127]
	ds_read_b64_tr_b16 v[104:105], v188 offset:46080
	ds_read_b64_tr_b16 v[106:107], v188 offset:46592
	ds_read_b128 v[164:167], v168 offset:1024
	v_add_f32_e32 v144, v110, v144
	v_add_f32_e32 v144, v111, v144
	v_add_f32_e32 v144, v80, v144
	v_add_f32_e32 v144, v81, v144
	s_waitcnt lgkmcnt(0)
	v_mfma_f32_32x32x16_bf16 v[64:79], v[140:143], v[164:167], v[64:79]
	v_cvt_pk_bf16_f32 v154, v108, v109
	v_cvt_pk_bf16_f32 v155, v110, v111
	ds_read_b64_tr_b16 v[108:109], v188 offset:43008
	ds_read_b64_tr_b16 v[110:111], v188 offset:43520
	ds_read_b128 v[140:143], v168 offset:2048
	v_add_f32_e32 v144, v82, v144
	v_add_f32_e32 v144, v83, v144
	v_add_f32_e32 v144, v84, v144
	v_add_f32_e32 v144, v85, v144
	v_cvt_pk_bf16_f32 v148, v80, v81
	v_cvt_pk_bf16_f32 v149, v82, v83
	s_waitcnt lgkmcnt(0)
	v_mfma_f32_32x32x16_bf16 v[112:127], v[160:163], v[140:143], v[112:127]
	ds_read_b64_tr_b16 v[190:191], v188 offset:47104
	ds_read_b64_tr_b16 v[192:193], v188 offset:47616
	ds_read_b128 v[80:83], v168 offset:2048
	v_add_f32_e32 v140, v86, v144
	v_add_f32_e32 v140, v87, v140
	v_add_f32_e32 v140, v88, v140
	v_add_f32_e32 v140, v89, v140
	s_waitcnt lgkmcnt(0)
	v_mfma_f32_32x32x16_bf16 v[64:79], v[132:135], v[80:83], v[64:79]
	v_cvt_pk_bf16_f32 v150, v84, v85
	v_cvt_pk_bf16_f32 v151, v86, v87
	ds_read_b64_tr_b16 v[84:85], v188 offset:44032
	ds_read_b64_tr_b16 v[86:87], v188 offset:44544
	ds_read_b128 v[80:83], v168 offset:3072
	v_add_f32_e32 v132, v90, v140
	v_add_f32_e32 v132, v91, v132
	v_add_f32_e32 v132, v92, v132
	v_add_f32_e32 v132, v93, v132
	v_cvt_pk_bf16_f32 v144, v88, v89
	v_cvt_pk_bf16_f32 v145, v90, v91
	s_waitcnt lgkmcnt(0)
	v_mfma_f32_32x32x16_bf16 v[112:127], v[136:139], v[80:83], v[112:127]
	ds_read_b64_tr_b16 v[88:89], v188 offset:48128
	ds_read_b64_tr_b16 v[90:91], v188 offset:48640
	ds_read_b128 v[80:83], v168 offset:3072
	v_add_f32_e32 v132, v94, v132
	v_add_f32_e32 v132, v95, v132
	v_add_f32_e32 v132, 0, v132
	v_cvt_pk_bf16_f32 v146, v92, v93
	s_waitcnt lgkmcnt(0)
	v_mfma_f32_32x32x16_bf16 v[64:79], v[128:131], v[80:83], v[64:79]
	v_cvt_pk_bf16_f32 v147, v94, v95
	v_lshl_add_u64 v[80:81], v[170:171], 0, s[64:65]
	s_mov_b32 s17, m0
	s_mov_b32 m0, s16
	s_nop 0
	global_load_lds_dwordx4 v[80:81], off
	s_mov_b32 m0, s17
	v_lshl_add_u64 v[80:81], v[172:173], 0, s[64:65]
	s_mov_b32 s16, m0
	s_mov_b32 m0, s35
	s_nop 0
	global_load_lds_dwordx4 v[80:81], off
	s_mov_b32 m0, s16
	v_add_f32_e32 v174, v174, v132
	v_mfma_f32_32x32x16_bf16 v[48:63], v[156:159], v[178:181], v[48:63]
	ds_read_b64_tr_b16 v[92:93], v188 offset:49152
	ds_read_b64_tr_b16 v[94:95], v188 offset:49664
	v_exp_f32_e32 v112, v112
	v_exp_f32_e32 v113, v113
	v_mfma_f32_32x32x16_bf16 v[32:47], v[156:159], v[96:99], v[32:47]
	ds_read_b64_tr_b16 v[170:171], v188 offset:53248
	ds_read_b64_tr_b16 v[172:173], v188 offset:53760
	v_exp_f32_e32 v114, v114
	v_exp_f32_e32 v115, v115
	ds_read_b128 v[80:83], v234
	ds_read_b128 v[96:99], v234 offset:4096
	v_mfma_f32_32x32x16_bf16 v[48:63], v[152:155], v[100:103], v[48:63]
	ds_read_b64_tr_b16 v[178:179], v188 offset:50176
	ds_read_b64_tr_b16 v[180:181], v188 offset:50688
	v_exp_f32_e32 v116, v116
	v_exp_f32_e32 v117, v117
	ds_read_b128 v[164:167], v235
	ds_read_b128 v[140:143], v235 offset:4096
	v_mfma_f32_32x32x16_bf16 v[32:47], v[152:155], v[104:107], v[32:47]
	ds_read_b64_tr_b16 v[100:101], v188 offset:54272
	ds_read_b64_tr_b16 v[102:103], v188 offset:54784
	v_exp_f32_e32 v118, v118
	v_exp_f32_e32 v119, v119
	ds_read_b128 v[160:163], v236
	ds_read_b128 v[132:135], v236 offset:4096
	v_mfma_f32_32x32x16_bf16 v[48:63], v[148:151], v[108:111], v[48:63]
	ds_read_b64_tr_b16 v[104:105], v188 offset:51200
	ds_read_b64_tr_b16 v[106:107], v188 offset:51712
	v_exp_f32_e32 v120, v120
	v_exp_f32_e32 v121, v121
	ds_read_b128 v[136:139], v237
	ds_read_b128 v[128:131], v237 offset:4096
	v_mfma_f32_32x32x16_bf16 v[32:47], v[148:151], v[190:193], v[32:47]
	ds_read_b64_tr_b16 v[108:109], v188 offset:55296
	ds_read_b64_tr_b16 v[110:111], v188 offset:55808
	v_exp_f32_e32 v122, v122
	v_exp_f32_e32 v123, v123
	v_mfma_f32_32x32x16_bf16 v[48:63], v[144:147], v[84:87], v[48:63]
	ds_read_b64_tr_b16 v[190:191], v188 offset:52224
	ds_read_b64_tr_b16 v[192:193], v188 offset:52736
	v_exp_f32_e32 v124, v124
	v_exp_f32_e32 v125, v125
	v_mfma_f32_32x32x16_bf16 v[32:47], v[144:147], v[88:91], v[32:47]
	ds_read_b64_tr_b16 v[84:85], v188 offset:56320
	ds_read_b64_tr_b16 v[86:87], v188 offset:56832
	v_exp_f32_e32 v126, v126
	v_exp_f32_e32 v127, v127
	s_waitcnt lgkmcnt(14)
	v_mfma_f32_32x32x16_bf16 v[16:31], v[156:159], v[92:95], v[16:31]
	v_exp_f32_e32 v64, v64
	v_exp_f32_e32 v65, v65
	v_mfma_f32_32x32x16_bf16 v[0:15], v[156:159], v[170:173], v[0:15]
	v_exp_f32_e32 v66, v66
	v_exp_f32_e32 v67, v67
	v_mfma_f32_32x32x16_bf16 v[16:31], v[152:155], v[178:181], v[16:31]
	v_exp_f32_e32 v68, v68
	v_exp_f32_e32 v69, v69
	s_waitcnt lgkmcnt(12)
	v_mfma_f32_32x32x16_bf16 v[0:15], v[152:155], v[100:103], v[0:15]
	v_exp_f32_e32 v70, v70
	v_exp_f32_e32 v71, v71
	s_waitcnt lgkmcnt(8)
	v_mfma_f32_32x32x16_bf16 v[16:31], v[148:151], v[104:107], v[16:31]
	v_exp_f32_e32 v72, v72
	v_exp_f32_e32 v73, v73
	s_waitcnt lgkmcnt(4)
	v_mfma_f32_32x32x16_bf16 v[0:15], v[148:151], v[108:111], v[0:15]
	v_exp_f32_e32 v74, v74
	v_exp_f32_e32 v75, v75
	s_waitcnt lgkmcnt(2)
	v_mfma_f32_32x32x16_bf16 v[16:31], v[144:147], v[190:193], v[16:31]
	v_exp_f32_e32 v76, v76
	v_exp_f32_e32 v77, v77
	s_waitcnt lgkmcnt(0)
	v_mfma_f32_32x32x16_bf16 v[0:15], v[144:147], v[84:87], v[0:15]
	v_exp_f32_e32 v78, v78
	v_exp_f32_e32 v79, v79
	s_waitcnt vmcnt(0) lgkmcnt(0)
	s_barrier
;   #define RESC() do{ if(!NOMAX&&resc){ asm volatile("s_waitcnt lgkmcnt(0)":::"memory"); \
;       _Pragma("unroll") for(int d_=0;d_<2*VM;++d_) _Pragma("unroll") for(int r=0;r<16;++r)o[d_][r]*=wsf[crow(r,hi)]; } }while(0)
; template<int THRL,int VM,bool NOMAX> __device__ __forceinline__ void attn_unit(const bf16*Qb,const bf16*__restrict__ Kh,const bf16*__restrict__ Vh,bf16*Ob,const int NT,const int sp,float*wscr,char*shm){
;     ...
;   STEP(pB0,pB1,pA0,pA1,NT-1,false,false,false); RESC();
	ds_read_b64_tr_b16 v[170:171], v188 offset:57344
	ds_read_b64_tr_b16 v[172:173], v188 offset:57856
	v_add_f32_e32 v88, v112, v113
	ds_read_b128 v[84:87], v168
	v_add_f32_e32 v88, v114, v88
	v_add_f32_e32 v88, v115, v88
	v_add_f32_e32 v88, v116, v88
	v_add_f32_e32 v104, v117, v88
	v_cvt_pk_bf16_f32 v156, v112, v113
	v_cvt_pk_bf16_f32 v157, v114, v115
	s_waitcnt lgkmcnt(0)
	v_mfma_f32_32x32x16_bf16 v[80:95], v[80:83], v[84:87], 0
	ds_read_b64_tr_b16 v[112:113], v188 offset:61440
	ds_read_b64_tr_b16 v[114:115], v188 offset:61952
	ds_read_b128 v[100:103], v168
	v_add_f32_e32 v104, v118, v104
	v_add_f32_e32 v104, v119, v104
	v_add_f32_e32 v104, v120, v104
	v_add_f32_e32 v144, v121, v104
	v_cvt_pk_bf16_f32 v158, v116, v117
	v_cvt_pk_bf16_f32 v159, v118, v119
	s_waitcnt lgkmcnt(0)
	v_mfma_f32_32x32x16_bf16 v[96:111], v[96:99], v[100:103], 0
	ds_read_b64_tr_b16 v[116:117], v188 offset:58368
	ds_read_b64_tr_b16 v[118:119], v188 offset:58880
	ds_read_b128 v[178:181], v168 offset:1024
	v_add_f32_e32 v144, v122, v144
	v_add_f32_e32 v144, v123, v144
	v_add_f32_e32 v144, v124, v144
	v_add_f32_e32 v144, v125, v144
	v_cvt_pk_bf16_f32 v152, v120, v121
	v_cvt_pk_bf16_f32 v153, v122, v123
	s_waitcnt lgkmcnt(0)
	v_mfma_f32_32x32x16_bf16 v[80:95], v[164:167], v[178:181], v[80:95]
	ds_read_b64_tr_b16 v[120:121], v188 offset:62464
	ds_read_b64_tr_b16 v[122:123], v188 offset:62976
	ds_read_b128 v[164:167], v168 offset:1024
	v_add_f32_e32 v144, v126, v144
	v_add_f32_e32 v144, v127, v144
	v_add_f32_e32 v144, v64, v144
	v_add_f32_e32 v144, v65, v144
	v_cvt_pk_bf16_f32 v154, v124, v125
	v_cvt_pk_bf16_f32 v155, v126, v127
	s_waitcnt lgkmcnt(0)
	v_mfma_f32_32x32x16_bf16 v[96:111], v[140:143], v[164:167], v[96:111]
	ds_read_b64_tr_b16 v[124:125], v188 offset:59392
	ds_read_b64_tr_b16 v[126:127], v188 offset:59904
	ds_read_b128 v[140:143], v168 offset:2048
	v_add_f32_e32 v144, v66, v144
	v_add_f32_e32 v144, v67, v144
	v_add_f32_e32 v144, v68, v144
	v_add_f32_e32 v144, v69, v144
	v_cvt_pk_bf16_f32 v148, v64, v65
	v_cvt_pk_bf16_f32 v149, v66, v67
	s_waitcnt lgkmcnt(0)
	v_mfma_f32_32x32x16_bf16 v[80:95], v[160:163], v[140:143], v[80:95]
	ds_read_b64_tr_b16 v[64:65], v188 offset:63488
	ds_read_b64_tr_b16 v[66:67], v188 offset:64000
	ds_read_b128 v[140:143], v168 offset:2048
	v_add_f32_e32 v144, v70, v144
	v_add_f32_e32 v144, v71, v144
	v_add_f32_e32 v144, v72, v144
	v_add_f32_e32 v144, v73, v144
	v_cvt_pk_bf16_f32 v150, v68, v69
	v_cvt_pk_bf16_f32 v151, v70, v71
	s_waitcnt lgkmcnt(0)
	v_mfma_f32_32x32x16_bf16 v[96:111], v[132:135], v[140:143], v[96:111]
	ds_read_b64_tr_b16 v[68:69], v188 offset:60416
	ds_read_b64_tr_b16 v[70:71], v188 offset:60928
	ds_read_b128 v[132:135], v168 offset:3072
	v_add_f32_e32 v140, v74, v144
	v_add_f32_e32 v140, v75, v140
	v_add_f32_e32 v140, v76, v140
	v_add_f32_e32 v140, v77, v140
	v_cvt_pk_bf16_f32 v144, v72, v73
	v_cvt_pk_bf16_f32 v145, v74, v75
	s_waitcnt lgkmcnt(0)
	v_mfma_f32_32x32x16_bf16 v[80:95], v[136:139], v[132:135], v[80:95]
	ds_read_b64_tr_b16 v[72:73], v188 offset:64512
	ds_read_b64_tr_b16 v[74:75], v188 offset:65024
	ds_read_b128 v[132:135], v168 offset:3072
	v_add_f32_e32 v136, v78, v140
	v_add_f32_e32 v136, v79, v136
	v_add_f32_e32 v136, 0, v136
	v_cvt_pk_bf16_f32 v146, v76, v77
	v_cvt_pk_bf16_f32 v147, v78, v79
	s_waitcnt lgkmcnt(0)
	v_mfma_f32_32x32x16_bf16 v[96:111], v[128:131], v[132:135], v[96:111]
	v_mfma_f32_32x32x16_bf16 v[48:63], v[156:159], v[170:173], v[48:63]
	ds_read_b64_tr_b16 v[76:77], v177 offset:40960
	ds_read_b64_tr_b16 v[78:79], v177 offset:41472
	v_exp_f32_e32 v80, v80
	v_exp_f32_e32 v81, v81
	v_mfma_f32_32x32x16_bf16 v[32:47], v[156:159], v[112:115], v[32:47]
	ds_read_b64_tr_b16 v[128:129], v177 offset:45056
	ds_read_b64_tr_b16 v[130:131], v177 offset:45568
	v_exp_f32_e32 v82, v82
	v_exp_f32_e32 v83, v83
	v_mfma_f32_32x32x16_bf16 v[48:63], v[152:155], v[116:119], v[48:63]
	ds_read_b64_tr_b16 v[112:113], v177 offset:41984
	ds_read_b64_tr_b16 v[114:115], v177 offset:42496
	v_exp_f32_e32 v84, v84
	v_exp_f32_e32 v85, v85
	v_mfma_f32_32x32x16_bf16 v[32:47], v[152:155], v[120:123], v[32:47]
	ds_read_b64_tr_b16 v[116:117], v177 offset:46080
	ds_read_b64_tr_b16 v[118:119], v177 offset:46592
	v_exp_f32_e32 v86, v86
	v_exp_f32_e32 v87, v87
	v_mfma_f32_32x32x16_bf16 v[48:63], v[148:151], v[124:127], v[48:63]
	ds_read_b64_tr_b16 v[120:121], v177 offset:43008
	ds_read_b64_tr_b16 v[122:123], v177 offset:43520
	v_exp_f32_e32 v88, v88
	v_exp_f32_e32 v89, v89
	v_mfma_f32_32x32x16_bf16 v[32:47], v[148:151], v[64:67], v[32:47]
	ds_read_b64_tr_b16 v[124:125], v177 offset:47104
	ds_read_b64_tr_b16 v[126:127], v177 offset:47616
	v_exp_f32_e32 v90, v90
	v_exp_f32_e32 v91, v91
	v_mfma_f32_32x32x16_bf16 v[48:63], v[144:147], v[68:71], v[48:63]
	ds_read_b64_tr_b16 v[64:65], v177 offset:44032
	ds_read_b64_tr_b16 v[66:67], v177 offset:44544
	v_exp_f32_e32 v92, v92
	v_exp_f32_e32 v93, v93
	v_mfma_f32_32x32x16_bf16 v[32:47], v[144:147], v[72:75], v[32:47]
	ds_read_b64_tr_b16 v[68:69], v177 offset:48128
	ds_read_b64_tr_b16 v[70:71], v177 offset:48640
	v_exp_f32_e32 v94, v94
	v_exp_f32_e32 v95, v95
	s_waitcnt lgkmcnt(14)
	v_mfma_f32_32x32x16_bf16 v[16:31], v[156:159], v[76:79], v[16:31]
	v_exp_f32_e32 v96, v96
	v_exp_f32_e32 v97, v97
	s_waitcnt lgkmcnt(12)
; #define SBAR() __builtin_amdgcn_sched_barrier(0)
;   #define PKW(P,B) cvtpk_s(P[B],P[B+1])
; __device__ __forceinline__ void pv(f32x16*o,int vb,bf16x8 pa0,bf16x8 pa1,bf16x8 pa2,bf16x8 pa3){
;   #pragma unroll
;   for(int d0=0;d0<2;++d0){s16x4 lo[4],hi[4];
;     #pragma unroll
;     for(int ks=0;ks<4;++ks){
;       asm volatile("ds_read_b64_tr_b16 %0,%1 offset:%c2":"=&v"(lo[ks]):"v"(vb),"i"(d0*4096+ks*1024):"memory");
;       asm volatile("ds_read_b64_tr_b16 %0,%1 offset:%c2":"=&v"(hi[ks]):"v"(vb),"i"(d0*4096+ks*1024+512):"memory");}
;     asm volatile("s_waitcnt lgkmcnt(0)":::"memory");SBAR();
;     ...
;     o[d0]=__builtin_amdgcn_mfma_f32_32x32x16_bf16(pa0,PK(0),o[d0],0,0,0);
;     o[d0]=__builtin_amdgcn_mfma_f32_32x32x16_bf16(pa1,PK(1),o[d0],0,0,0);
;     o[d0]=__builtin_amdgcn_mfma_f32_32x32x16_bf16(pa2,PK(2),o[d0],0,0,0);
;     o[d0]=__builtin_amdgcn_mfma_f32_32x32x16_bf16(pa3,PK(3),o[d0],0,0,0);
;     ...
;   }
; template<int THRL,int VM,bool NOMAX> __device__ __forceinline__ void attn_unit(const bf16*Qb,const bf16*__restrict__ Kh,const bf16*__restrict__ Vh,bf16*Ob,const int NT,const int sp,float*wscr,char*shm){
;     ...
;   { float sacc=pB0[0]+pB0[1]; _Pragma("unroll") for(int r=2;r<16;++r)sacc+=pB0[r]; _Pragma("unroll") for(int r=0;r<16;++r)sacc+=pB1[r]; l_reg+=sacc;
;     pw0=(u32x4){PKW(pB0,0),PKW(pB0,2),PKW(pB0,4),PKW(pB0,6)};pw1=(u32x4){PKW(pB0,8),PKW(pB0,10),PKW(pB0,12),PKW(pB0,14)};pw2=(u32x4){PKW(pB1,0),PKW(pB1,2),PKW(pB1,4),PKW(pB1,6)};pw3=(u32x4){PKW(pB1,8),PKW(pB1,10),PKW(pB1,12),PKW(pB1,14)};
;     SBAR(); pv(o,vb0+VM*sl_cur,PAF(0),PAF(1),PAF(2),PAF(3)); if constexpr(VM==2) pv(o+2,vb0+VM*sl_cur+8192,PAF(0),PAF(1),PAF(2),PAF(3)); }
;     ...
;   {auto rr=__builtin_amdgcn_permlane32_swap(__float_as_uint(l_reg),__float_as_uint(l_reg),false,false);l_reg=__uint_as_float(rr[0])+__uint_as_float(rr[1]);}
;   if(hi==0)wsf[32+r32]=l_reg;asm volatile("s_waitcnt lgkmcnt(0)":::"memory");
	v_mfma_f32_32x32x16_bf16 v[0:15], v[156:159], v[128:131], v[0:15]
	v_exp_f32_e32 v98, v98
	v_exp_f32_e32 v99, v99
	s_waitcnt lgkmcnt(10)
	v_mfma_f32_32x32x16_bf16 v[16:31], v[152:155], v[112:115], v[16:31]
	v_exp_f32_e32 v100, v100
	v_exp_f32_e32 v101, v101
	s_waitcnt lgkmcnt(8)
	v_mfma_f32_32x32x16_bf16 v[0:15], v[152:155], v[116:119], v[0:15]
	v_exp_f32_e32 v102, v102
	v_exp_f32_e32 v103, v103
	s_waitcnt lgkmcnt(6)
	v_mfma_f32_32x32x16_bf16 v[16:31], v[148:151], v[120:123], v[16:31]
	v_exp_f32_e32 v104, v104
	v_exp_f32_e32 v105, v105
	s_waitcnt lgkmcnt(4)
	v_mfma_f32_32x32x16_bf16 v[0:15], v[148:151], v[124:127], v[0:15]
	v_exp_f32_e32 v106, v106
	v_exp_f32_e32 v107, v107
	s_waitcnt lgkmcnt(2)
	v_mfma_f32_32x32x16_bf16 v[16:31], v[144:147], v[64:67], v[16:31]
	v_exp_f32_e32 v108, v108
	v_exp_f32_e32 v109, v109
	s_waitcnt lgkmcnt(0)
	v_mfma_f32_32x32x16_bf16 v[0:15], v[144:147], v[68:71], v[0:15]
	v_exp_f32_e32 v110, v110
	v_exp_f32_e32 v111, v111
	v_add_f32_e32 v64, v80, v81
	v_add_f32_e32 v64, v82, v64
	v_add_f32_e32 v64, v83, v64
	v_add_f32_e32 v64, v84, v64
	v_add_f32_e32 v64, v85, v64
	v_add_f32_e32 v64, v86, v64
	v_add_f32_e32 v64, v87, v64
	v_add_f32_e32 v64, v88, v64
	v_add_f32_e32 v64, v89, v64
	v_add_f32_e32 v64, v90, v64
	v_add_f32_e32 v64, v91, v64
	v_add_f32_e32 v64, v92, v64
	v_add_f32_e32 v64, v93, v64
	v_add_f32_e32 v64, v94, v64
	v_add_f32_e32 v64, v95, v64
	v_add_f32_e32 v64, v64, v96
	v_add_f32_e32 v64, v97, v64
	v_add_f32_e32 v64, v98, v64
	v_add_f32_e32 v64, v99, v64
	v_add_f32_e32 v64, v100, v64
	v_add_f32_e32 v64, v101, v64
	v_add_f32_e32 v64, v102, v64
	v_add_f32_e32 v64, v103, v64
	v_add_f32_e32 v64, v104, v64
	v_add_f32_e32 v64, v105, v64
	v_add_f32_e32 v64, v106, v64
	v_add_f32_e32 v64, v107, v64
	v_add_f32_e32 v64, v108, v64
	v_add_f32_e32 v64, v109, v64
	v_add_f32_e32 v64, v110, v64
	v_add_f32_e32 v64, v111, v64
	v_add_f32_e32 v65, v174, v136
	v_add_f32_e32 v64, v65, v64
	v_cvt_pk_bf16_f32 v66, v80, v81
	v_cvt_pk_bf16_f32 v67, v82, v83
	v_cvt_pk_bf16_f32 v68, v84, v85
	v_cvt_pk_bf16_f32 v69, v86, v87
	v_cvt_pk_bf16_f32 v70, v88, v89
	v_cvt_pk_bf16_f32 v71, v90, v91
	v_cvt_pk_bf16_f32 v72, v92, v93
	v_cvt_pk_bf16_f32 v73, v94, v95
	v_cvt_pk_bf16_f32 v74, v96, v97
	v_cvt_pk_bf16_f32 v75, v98, v99
	v_cvt_pk_bf16_f32 v76, v100, v101
	v_cvt_pk_bf16_f32 v77, v102, v103
	v_cvt_pk_bf16_f32 v78, v104, v105
	v_cvt_pk_bf16_f32 v79, v106, v107
	v_cvt_pk_bf16_f32 v80, v108, v109
	v_cvt_pk_bf16_f32 v81, v110, v111
	ds_read_b64_tr_b16 v[82:83],v176 offset:0
	ds_read_b64_tr_b16 v[84:85],v176 offset:512
	ds_read_b64_tr_b16 v[86:87],v176 offset:1024
	ds_read_b64_tr_b16 v[88:89],v176 offset:1536
	ds_read_b64_tr_b16 v[90:91],v176 offset:2048
	ds_read_b64_tr_b16 v[92:93],v176 offset:2560
	ds_read_b64_tr_b16 v[94:95],v176 offset:3072
	ds_read_b64_tr_b16 v[96:97],v176 offset:3584
	s_waitcnt lgkmcnt(0)
	s_nop 0
	v_mfma_f32_32x32x16_bf16 v[48:63], v[66:69], v[82:85], v[48:63]
	ds_read_b64_tr_b16 v[82:83],v176 offset:4096
	ds_read_b64_tr_b16 v[84:85],v176 offset:4608
	v_mfma_f32_32x32x16_bf16 v[48:63], v[70:73], v[86:89], v[48:63]
	ds_read_b64_tr_b16 v[86:87],v176 offset:5120
	ds_read_b64_tr_b16 v[88:89],v176 offset:5632
	v_mfma_f32_32x32x16_bf16 v[48:63], v[74:77], v[90:93], v[48:63]
	ds_read_b64_tr_b16 v[90:91],v176 offset:6144
	ds_read_b64_tr_b16 v[92:93],v176 offset:6656
	ds_read_b64_tr_b16 v[98:99],v176 offset:7168
	ds_read_b64_tr_b16 v[100:101],v176 offset:7680
	s_waitcnt lgkmcnt(0)
	v_mfma_f32_32x32x16_bf16 v[48:63], v[78:81], v[94:97], v[48:63]
	v_mfma_f32_32x32x16_bf16 v[32:47], v[66:69], v[82:85], v[32:47]
	v_add_u32_e32 v65, 0x2000, v176
	ds_read_b64_tr_b16 v[82:83],v65 offset:0
	ds_read_b64_tr_b16 v[84:85],v65 offset:512
	v_mfma_f32_32x32x16_bf16 v[32:47], v[70:73], v[86:89], v[32:47]
	ds_read_b64_tr_b16 v[86:87],v65 offset:1024
	ds_read_b64_tr_b16 v[88:89],v65 offset:1536
	v_mfma_f32_32x32x16_bf16 v[32:47], v[74:77], v[90:93], v[32:47]
	ds_read_b64_tr_b16 v[90:91],v65 offset:2048
	ds_read_b64_tr_b16 v[92:93],v65 offset:2560
	ds_read_b64_tr_b16 v[94:95],v65 offset:3072
	ds_read_b64_tr_b16 v[96:97],v65 offset:3584
	s_waitcnt lgkmcnt(0)
	v_mfma_f32_32x32x16_bf16 v[32:47], v[78:81], v[98:101], v[32:47]
	v_mfma_f32_32x32x16_bf16 v[16:31], v[66:69], v[82:85], v[16:31]
	ds_read_b64_tr_b16 v[82:83],v65 offset:4096
	ds_read_b64_tr_b16 v[84:85],v65 offset:4608
	v_mfma_f32_32x32x16_bf16 v[16:31], v[70:73], v[86:89], v[16:31]
	ds_read_b64_tr_b16 v[86:87],v65 offset:5120
	ds_read_b64_tr_b16 v[88:89],v65 offset:5632
	v_mfma_f32_32x32x16_bf16 v[16:31], v[74:77], v[90:93], v[16:31]
	ds_read_b64_tr_b16 v[90:91],v65 offset:6144
	ds_read_b64_tr_b16 v[92:93],v65 offset:6656
	ds_read_b64_tr_b16 v[98:99],v65 offset:7168
	ds_read_b64_tr_b16 v[100:101],v65 offset:7680
	s_waitcnt lgkmcnt(0)
	v_mfma_f32_32x32x16_bf16 v[16:31], v[78:81], v[94:97], v[16:31]
	v_mfma_f32_32x32x16_bf16 v[0:15], v[66:69], v[82:85], v[0:15]
	v_mov_b32_e32 v65, v64
	s_nop 1
	v_permlane32_swap_b32_e32 v64, v65
	v_cmp_gt_u32_e32 vcc, 32, v187
	v_mfma_f32_32x32x16_bf16 v[0:15], v[70:73], v[86:89], v[0:15]
	v_mfma_f32_32x32x16_bf16 v[0:15], v[74:77], v[90:93], v[0:15]
	v_mfma_f32_32x32x16_bf16 v[0:15], v[78:81], v[98:101], v[0:15]
	s_and_saveexec_b64 s[16:17], vcc
	s_cbranch_execz .LBB0_870
	v_add_f32_e32 v64, v64, v65
	v_lshl_add_u32 v65, v186, 2, s34
	ds_write_b32 v65, v64 offset:128
	s_branch .LBB0_870

; #define WAIT_BAR(N) asm volatile("s_waitcnt vmcnt(" #N ") lgkmcnt(0)\n\ts_barrier":::"memory")
;   #define RESC() do{ if(!NOMAX&&resc){ asm volatile("s_waitcnt lgkmcnt(0)":::"memory"); \
;       _Pragma("unroll") for(int d_=0;d_<2*VM;++d_) _Pragma("unroll") for(int r=0;r<16;++r)o[d_][r]*=wsf[crow(r,hi)]; } }while(0)
;   #define ROT() do{sl_prev=sl_cur;sl_cur=sl_next;sl_next=(sl_next==(NSLOT-1)*SLOTB)?0:sl_next+SLOTB;}while(0)
; template<int THRL,int VM,bool NOMAX> __device__ __forceinline__ void attn_unit(const bf16*Qb,const bf16*__restrict__ Kh,const bf16*__restrict__ Vh,bf16*Ob,const int NT,const int sp,float*wscr,char*shm){
;     ...
;   for(;t+5<NT;t+=2){
;     STEP(pB0,pB1,pA0,pA1,t,true,true,true);     if constexpr(VM==2){WAIT_BAR(3);}else{WAIT_BAR(2);} RESC(); ROT();
;     STEP(pA0,pA1,pB0,pB1,t+1,true,true,true);   if constexpr(VM==2){WAIT_BAR(3);}else{WAIT_BAR(2);} RESC(); ROT();
.LBB0_882:
	v_mfma_f32_32x32x16_bf16 v[96:111], v[84:87], v[156:159], 0
	v_add_u32_e32 v187, s54, v182
	v_lshl_add_u64 v[238:239], v[176:177], 0, s[38:39]
	s_add_i32 s53, s52, s33
	s_mov_b32 s54, m0
	s_mov_b32 m0, s53
	s_nop 0
	global_load_lds_dwordx4 v[238:239], off
	s_mov_b32 m0, s54
	v_lshl_add_u64 v[238:239], v[174:175], 0, s[38:39]
	s_add_i32 s53, s35, s16
	s_mov_b32 s54, m0
	s_mov_b32 m0, s53
	s_nop 0
	global_load_lds_dwordx4 v[238:239], off
	s_mov_b32 m0, s54
	ds_read_b64_tr_b16 v[188:189], v187 offset:24576
	ds_read_b64_tr_b16 v[190:191], v187 offset:25088
	v_add_f32_e32 v88, v64, v65
	v_add_f32_e32 v88, v66, v88
	v_add_f32_e32 v88, v67, v88
	v_add_f32_e32 v88, v68, v88
	v_add_f32_e32 v88, v69, v88
	v_cvt_pk_bf16_f32 v140, v64, v65
	v_cvt_pk_bf16_f32 v141, v66, v67
	ds_read_b64_tr_b16 v[64:65], v187 offset:28672
	ds_read_b64_tr_b16 v[66:67], v187 offset:29184
	v_add_f32_e32 v84, v70, v88
	v_add_f32_e32 v84, v71, v84
	v_add_f32_e32 v84, v72, v84
	v_add_f32_e32 v128, v73, v84
	s_waitcnt lgkmcnt(10)
	v_mfma_f32_32x32x16_bf16 v[80:95], v[80:83], v[156:159], 0
	v_cvt_pk_bf16_f32 v142, v68, v69
	v_cvt_pk_bf16_f32 v143, v70, v71
	ds_read_b64_tr_b16 v[68:69], v187 offset:25600
	ds_read_b64_tr_b16 v[70:71], v187 offset:26112
	v_add_f32_e32 v128, v74, v128
	v_add_f32_e32 v128, v75, v128
	v_add_f32_e32 v128, v76, v128
	v_add_f32_e32 v128, v77, v128
	v_cvt_pk_bf16_f32 v136, v72, v73
	v_cvt_pk_bf16_f32 v137, v74, v75
	s_waitcnt lgkmcnt(11)
	v_mfma_f32_32x32x16_bf16 v[96:111], v[164:167], v[152:155], v[96:111]
	ds_read_b64_tr_b16 v[72:73], v187 offset:29696
	ds_read_b64_tr_b16 v[74:75], v187 offset:30208
	s_waitcnt lgkmcnt(12)
	v_mfma_f32_32x32x16_bf16 v[80:95], v[160:163], v[152:155], v[80:95]
	v_add_f32_e32 v128, v78, v128
	v_add_f32_e32 v128, v79, v128
	v_add_f32_e32 v128, v48, v128
	v_add_f32_e32 v128, v49, v128
	v_cvt_pk_bf16_f32 v138, v76, v77
	v_cvt_pk_bf16_f32 v139, v78, v79
	ds_read_b64_tr_b16 v[76:77], v187 offset:26624
	ds_read_b64_tr_b16 v[78:79], v187 offset:27136
	v_add_f32_e32 v128, v50, v128
	v_add_f32_e32 v128, v51, v128
	v_add_f32_e32 v128, v52, v128
	v_add_f32_e32 v128, v53, v128
	v_cvt_pk_bf16_f32 v132, v48, v49
	v_cvt_pk_bf16_f32 v133, v50, v51
	s_waitcnt lgkmcnt(13)
	v_mfma_f32_32x32x16_bf16 v[96:111], v[124:127], v[148:151], v[96:111]
	ds_read_b64_tr_b16 v[48:49], v187 offset:30720
	ds_read_b64_tr_b16 v[50:51], v187 offset:31232
	s_waitcnt lgkmcnt(14)
	v_mfma_f32_32x32x16_bf16 v[80:95], v[120:123], v[148:151], v[80:95]
	v_add_f32_e32 v124, v54, v128
	v_add_f32_e32 v124, v55, v124
	v_add_f32_e32 v124, v56, v124
	v_add_f32_e32 v124, v57, v124
	v_cvt_pk_bf16_f32 v134, v52, v53
	v_cvt_pk_bf16_f32 v135, v54, v55
	ds_read_b64_tr_b16 v[52:53], v187 offset:27648
	ds_read_b64_tr_b16 v[54:55], v187 offset:28160
	v_add_f32_e32 v120, v58, v124
	v_add_f32_e32 v120, v59, v120
	v_add_f32_e32 v120, v60, v120
	v_add_f32_e32 v120, v61, v120
	v_cvt_pk_bf16_f32 v128, v56, v57
	v_cvt_pk_bf16_f32 v129, v58, v59
	s_waitcnt lgkmcnt(14)
	v_mfma_f32_32x32x16_bf16 v[96:111], v[116:119], v[144:147], v[96:111]
	ds_read_b64_tr_b16 v[56:57], v187 offset:31744
	ds_read_b64_tr_b16 v[58:59], v187 offset:32256
	v_mfma_f32_32x32x16_bf16 v[80:95], v[112:115], v[144:147], v[80:95]
	v_add_f32_e32 v116, v62, v120
	v_add_f32_e32 v116, v63, v116
	v_add_f32_e32 v116, 0, v116
	v_cvt_pk_bf16_f32 v130, v60, v61
	v_cvt_pk_bf16_f32 v131, v62, v63
	v_add_f32_e32 v202, v186, v116
	s_waitcnt lgkmcnt(14)
	v_mfma_f32_32x32x16_bf16 v[16:31], v[140:143], v[188:191], v[16:31]
	v_exp_f32_e32 v96, v96
	v_exp_f32_e32 v97, v97
	v_exp_f32_e32 v98, v98
	v_exp_f32_e32 v99, v99
	s_waitcnt lgkmcnt(12)
	v_mfma_f32_32x32x16_bf16 v[32:47], v[140:143], v[64:67], v[32:47]
	v_exp_f32_e32 v100, v100
	v_exp_f32_e32 v101, v101
	v_exp_f32_e32 v102, v102
	v_exp_f32_e32 v103, v103
	v_add_u32_e32 v242, s35, v234
	v_add_u32_e32 v243, s35, v235
	v_add_u32_e32 v244, s35, v236
	v_add_u32_e32 v245, s35, v237
	ds_read_b128 v[60:63], v242
	ds_read_b128 v[112:115], v242 offset:4096
	s_waitcnt lgkmcnt(12)
	v_mfma_f32_32x32x16_bf16 v[16:31], v[136:139], v[68:71], v[16:31]
	v_exp_f32_e32 v104, v104
	v_exp_f32_e32 v105, v105
	v_exp_f32_e32 v106, v106
	v_exp_f32_e32 v107, v107
	ds_read_b128 v[116:119], v243
	ds_read_b128 v[120:123], v243 offset:4096
	s_waitcnt lgkmcnt(12)
	v_mfma_f32_32x32x16_bf16 v[32:47], v[136:139], v[72:75], v[32:47]
	v_exp_f32_e32 v108, v108
	v_exp_f32_e32 v109, v109
	v_exp_f32_e32 v110, v110
	v_exp_f32_e32 v111, v111
	ds_read_b128 v[124:127], v244
	ds_read_b128 v[160:163], v244 offset:4096
	s_waitcnt lgkmcnt(12)
	v_mfma_f32_32x32x16_bf16 v[16:31], v[132:135], v[76:79], v[16:31]
	v_exp_f32_e32 v80, v80
	v_exp_f32_e32 v81, v81
	v_exp_f32_e32 v82, v82
	v_exp_f32_e32 v83, v83
	ds_read_b128 v[164:167], v245
	ds_read_b128 v[186:189], v245 offset:4096
	s_waitcnt lgkmcnt(12)
	v_mfma_f32_32x32x16_bf16 v[32:47], v[132:135], v[48:51], v[32:47]
	v_exp_f32_e32 v84, v84
	v_exp_f32_e32 v85, v85
	v_exp_f32_e32 v86, v86
	v_exp_f32_e32 v87, v87
	s_waitcnt lgkmcnt(10)
	v_mfma_f32_32x32x16_bf16 v[16:31], v[128:131], v[52:55], v[16:31]
	v_exp_f32_e32 v88, v88
	v_exp_f32_e32 v89, v89
	v_exp_f32_e32 v90, v90
	v_exp_f32_e32 v91, v91
	s_waitcnt lgkmcnt(8)
	v_mfma_f32_32x32x16_bf16 v[32:47], v[128:131], v[56:59], v[32:47]
	v_exp_f32_e32 v92, v92
	v_exp_f32_e32 v93, v93
	v_exp_f32_e32 v94, v94
	v_exp_f32_e32 v95, v95
	s_waitcnt vmcnt(2) lgkmcnt(0)
	s_barrier
; #define WAIT_BAR(N) asm volatile("s_waitcnt vmcnt(" #N ") lgkmcnt(0)\n\ts_barrier":::"memory")
;   #define RESC() do{ if(!NOMAX&&resc){ asm volatile("s_waitcnt lgkmcnt(0)":::"memory"); \
;       _Pragma("unroll") for(int d_=0;d_<2*VM;++d_) _Pragma("unroll") for(int r=0;r<16;++r)o[d_][r]*=wsf[crow(r,hi)]; } }while(0)
;   #define ROT() do{sl_prev=sl_cur;sl_cur=sl_next;sl_next=(sl_next==(NSLOT-1)*SLOTB)?0:sl_next+SLOTB;}while(0)
; template<int THRL,int VM,bool NOMAX> __device__ __forceinline__ void attn_unit(const bf16*Qb,const bf16*__restrict__ Kh,const bf16*__restrict__ Vh,bf16*Ob,const int NT,const int sp,float*wscr,char*shm){
;     ...
;   for(;t+5<NT;t+=2){
;     STEP(pB0,pB1,pA0,pA1,t,true,true,true);     if constexpr(VM==2){WAIT_BAR(3);}else{WAIT_BAR(2);} RESC(); ROT();
;     STEP(pA0,pA1,pB0,pB1,t+1,true,true,true);   if constexpr(VM==2){WAIT_BAR(3);}else{WAIT_BAR(2);} RESC(); ROT();
	v_mfma_f32_32x32x16_bf16 v[64:79], v[60:63], v[156:159], 0
	s_add_i32 s53, s35, 0x2000
	s_cmpk_lg_i32 s35, 0x4000
	s_cselect_b32 s53, s53, 0
	v_add_u32_e32 v203, s52, v182
	s_add_i32 s52, s35, s33
	s_mov_b32 s54, m0
	s_mov_b32 m0, s52
	s_nop 0
	global_load_lds_dwordx4 v[176:177], off
	s_mov_b32 m0, s54
	s_add_i32 s52, s53, s16
	s_mov_b32 s54, m0
	s_mov_b32 m0, s52
	s_nop 0
	global_load_lds_dwordx4 v[174:175], off
	s_mov_b32 m0, s54
	ds_read_b64_tr_b16 v[190:191], v203 offset:24576
	ds_read_b64_tr_b16 v[192:193], v203 offset:25088
	v_add_f32_e32 v48, v96, v97
	v_add_f32_e32 v48, v98, v48
	v_add_f32_e32 v48, v99, v48
	v_add_f32_e32 v48, v100, v48
	v_add_f32_e32 v48, v101, v48
	v_cvt_pk_bf16_f32 v140, v96, v97
	v_cvt_pk_bf16_f32 v141, v98, v99
	ds_read_b64_tr_b16 v[96:97], v203 offset:28672
	ds_read_b64_tr_b16 v[98:99], v203 offset:29184
	v_add_f32_e32 v48, v102, v48
	v_add_f32_e32 v48, v103, v48
	v_add_f32_e32 v48, v104, v48
	v_add_f32_e32 v128, v105, v48
	s_waitcnt lgkmcnt(10)
	v_mfma_f32_32x32x16_bf16 v[48:63], v[112:115], v[156:159], 0
	v_cvt_pk_bf16_f32 v142, v100, v101
	v_cvt_pk_bf16_f32 v143, v102, v103
	ds_read_b64_tr_b16 v[100:101], v203 offset:25600
	ds_read_b64_tr_b16 v[102:103], v203 offset:26112
	s_waitcnt lgkmcnt(11)
	v_mfma_f32_32x32x16_bf16 v[64:79], v[116:119], v[152:155], v[64:79]
	v_add_f32_e32 v112, v106, v128
	v_add_f32_e32 v112, v107, v112
	v_add_f32_e32 v112, v108, v112
	v_add_f32_e32 v112, v109, v112
	v_cvt_pk_bf16_f32 v136, v104, v105
	v_cvt_pk_bf16_f32 v137, v106, v107
	ds_read_b64_tr_b16 v[104:105], v203 offset:29696
	ds_read_b64_tr_b16 v[106:107], v203 offset:30208
	s_waitcnt lgkmcnt(12)
	v_mfma_f32_32x32x16_bf16 v[48:63], v[120:123], v[152:155], v[48:63]
	v_add_f32_e32 v112, v110, v112
	v_add_f32_e32 v112, v111, v112
	v_add_f32_e32 v112, v80, v112
	v_add_f32_e32 v112, v81, v112
	v_cvt_pk_bf16_f32 v138, v108, v109
	v_cvt_pk_bf16_f32 v139, v110, v111
	ds_read_b64_tr_b16 v[108:109], v203 offset:26624
	ds_read_b64_tr_b16 v[110:111], v203 offset:27136
	s_waitcnt lgkmcnt(13)
	v_mfma_f32_32x32x16_bf16 v[64:79], v[124:127], v[148:151], v[64:79]
	v_add_f32_e32 v112, v82, v112
	v_add_f32_e32 v112, v83, v112
	v_add_f32_e32 v112, v84, v112
	v_add_f32_e32 v112, v85, v112
	v_cvt_pk_bf16_f32 v132, v80, v81
	v_cvt_pk_bf16_f32 v133, v82, v83
	ds_read_b64_tr_b16 v[194:195], v203 offset:30720
	ds_read_b64_tr_b16 v[196:197], v203 offset:31232
	s_waitcnt lgkmcnt(14)
	v_mfma_f32_32x32x16_bf16 v[48:63], v[160:163], v[148:151], v[48:63]
	v_add_f32_e32 v80, v86, v112
	v_add_f32_e32 v80, v87, v80
	v_add_f32_e32 v80, v88, v80
	v_add_f32_e32 v80, v89, v80
	v_cvt_pk_bf16_f32 v134, v84, v85
	v_cvt_pk_bf16_f32 v135, v86, v87
	ds_read_b64_tr_b16 v[198:199], v203 offset:27648
	ds_read_b64_tr_b16 v[200:201], v203 offset:28160
	s_waitcnt lgkmcnt(14)
	v_mfma_f32_32x32x16_bf16 v[64:79], v[164:167], v[144:147], v[64:79]
	v_add_f32_e32 v80, v90, v80
	v_add_f32_e32 v80, v91, v80
	v_add_f32_e32 v80, v92, v80
	v_add_f32_e32 v80, v93, v80
	v_cvt_pk_bf16_f32 v128, v88, v89
	v_cvt_pk_bf16_f32 v129, v90, v91
	ds_read_b64_tr_b16 v[88:89], v203 offset:31744
	ds_read_b64_tr_b16 v[90:91], v203 offset:32256
	v_mfma_f32_32x32x16_bf16 v[48:63], v[186:189], v[144:147], v[48:63]
	v_add_f32_e32 v80, v94, v80
	v_add_f32_e32 v80, v95, v80
	v_add_f32_e32 v80, 0, v80
	v_cvt_pk_bf16_f32 v130, v92, v93
	v_cvt_pk_bf16_f32 v131, v94, v95
	v_add_f32_e32 v186, v202, v80
	s_waitcnt lgkmcnt(14)
	v_mfma_f32_32x32x16_bf16 v[16:31], v[140:143], v[190:193], v[16:31]
	v_exp_f32_e32 v64, v64
	v_exp_f32_e32 v65, v65
	v_exp_f32_e32 v66, v66
	v_exp_f32_e32 v67, v67
	s_waitcnt lgkmcnt(12)
	v_mfma_f32_32x32x16_bf16 v[32:47], v[140:143], v[96:99], v[32:47]
	v_exp_f32_e32 v68, v68
	v_exp_f32_e32 v69, v69
	v_exp_f32_e32 v70, v70
	v_exp_f32_e32 v71, v71
	v_add_u32_e32 v242, s53, v234
	v_add_u32_e32 v243, s53, v235
	v_add_u32_e32 v244, s53, v236
	v_add_u32_e32 v245, s53, v237
	ds_read_b128 v[84:87], v242
	ds_read_b128 v[80:83], v242 offset:4096
	s_waitcnt lgkmcnt(12)
	v_mfma_f32_32x32x16_bf16 v[16:31], v[136:139], v[100:103], v[16:31]
	v_exp_f32_e32 v72, v72
	v_exp_f32_e32 v73, v73
	v_exp_f32_e32 v74, v74
	v_exp_f32_e32 v75, v75
	ds_read_b128 v[164:167], v243
	ds_read_b128 v[160:163], v243 offset:4096
	s_waitcnt lgkmcnt(12)
	v_mfma_f32_32x32x16_bf16 v[32:47], v[136:139], v[104:107], v[32:47]
	v_exp_f32_e32 v76, v76
	v_exp_f32_e32 v77, v77
	v_exp_f32_e32 v78, v78
	v_exp_f32_e32 v79, v79
	ds_read_b128 v[124:127], v244
	ds_read_b128 v[120:123], v244 offset:4096
	s_waitcnt lgkmcnt(12)
	v_mfma_f32_32x32x16_bf16 v[16:31], v[132:135], v[108:111], v[16:31]
	v_exp_f32_e32 v48, v48
	v_exp_f32_e32 v49, v49
	v_exp_f32_e32 v50, v50
	v_exp_f32_e32 v51, v51
	ds_read_b128 v[116:119], v245
	ds_read_b128 v[112:115], v245 offset:4096
	s_waitcnt lgkmcnt(12)
	v_mfma_f32_32x32x16_bf16 v[32:47], v[132:135], v[194:197], v[32:47]
	v_exp_f32_e32 v52, v52
	v_exp_f32_e32 v53, v53
	v_exp_f32_e32 v54, v54
	v_exp_f32_e32 v55, v55
	s_waitcnt lgkmcnt(10)
	v_mfma_f32_32x32x16_bf16 v[16:31], v[128:131], v[198:201], v[16:31]
	v_exp_f32_e32 v56, v56
	v_exp_f32_e32 v57, v57
	v_exp_f32_e32 v58, v58
	v_exp_f32_e32 v59, v59
	s_waitcnt lgkmcnt(8)
	v_mfma_f32_32x32x16_bf16 v[32:47], v[128:131], v[88:91], v[32:47]
	v_exp_f32_e32 v60, v60
	v_exp_f32_e32 v61, v61
	v_exp_f32_e32 v62, v62
	v_exp_f32_e32 v63, v63
	s_add_i32 s55, s53, 0x2000
	s_waitcnt vmcnt(2) lgkmcnt(0)
	s_barrier
	s_cmpk_lg_i32 s53, 0x4000
	s_mov_b32 s54, s35
	s_cselect_b32 s35, s55, 0
	s_add_i32 s34, s34, 2
	v_lshl_add_u64 v[174:175], v[174:175], 0, s[8:9]
	v_lshl_add_u64 v[176:177], v[176:177], 0, s[8:9]
	s_mov_b32 s52, s53
	s_cmpk_lt_u32 s34, 0x79
	s_cbranch_scc1 .LBB0_882
;   #define RESC() do{ if(!NOMAX&&resc){ asm volatile("s_waitcnt lgkmcnt(0)":::"memory"); \
;       _Pragma("unroll") for(int d_=0;d_<2*VM;++d_) _Pragma("unroll") for(int r=0;r<16;++r)o[d_][r]*=wsf[crow(r,hi)]; } }while(0)
;   #define ROT() do{sl_prev=sl_cur;sl_cur=sl_next;sl_next=(sl_next==(NSLOT-1)*SLOTB)?0:sl_next+SLOTB;}while(0)
;   #define ENDW(tt) do{ if((tt)+3<NT){ if constexpr(VM==2){WAIT_BAR(3);}else{WAIT_BAR(2);} } else if((tt)+2<NT){ if constexpr(VM==2){WAIT_BAR(2);}else{WAIT_BAR(1);} } else {WAIT_BAR(0);} }while(0)
; template<int THRL,int VM,bool NOMAX> __device__ __forceinline__ void attn_unit(const bf16*Qb,const bf16*__restrict__ Kh,const bf16*__restrict__ Vh,bf16*Ob,const int NT,const int sp,float*wscr,char*shm){
;     ...
;   for(;t+1<NT;t+=2){
;     STEP(pB0,pB1,pA0,pA1,t,(t+3<NT),(t+1<NT),(t+1<NT));       ENDW(t);   RESC(); ROT();
	s_and_b32 s29, s29, 0x3fffffc0
	s_lshl_b32 s29, s29, 2
	s_add_i32 s29, s29, 0
	s_cmp_lg_u32 0, -1
	s_cselect_b32 s34, 0, 0
	s_add_i32 s35, s34, 0x6000
	v_add3_u32 v174, v185, s35, v184
	ds_read_b64_tr_b16 v[188:189], v182 offset:40960
	ds_read_b64_tr_b16 v[190:191], v182 offset:41472
	v_add_f32_e32 v88, v64, v65
	v_add_f32_e32 v88, v66, v88
	v_add_f32_e32 v88, v67, v88
	v_add_f32_e32 v88, v68, v88
	v_add_f32_e32 v88, v69, v88
	v_cvt_pk_bf16_f32 v140, v64, v65
	v_cvt_pk_bf16_f32 v141, v66, v67
	s_waitcnt lgkmcnt(9)
	v_mfma_f32_32x32x16_bf16 v[96:111], v[84:87], v[156:159], 0
	ds_read_b64_tr_b16 v[64:65], v182 offset:45056
	ds_read_b64_tr_b16 v[66:67], v182 offset:45568
	v_add_f32_e32 v84, v70, v88
	v_add_f32_e32 v84, v71, v84
	v_add_f32_e32 v84, v72, v84
	v_add_f32_e32 v128, v73, v84
	v_cvt_pk_bf16_f32 v142, v68, v69
	v_cvt_pk_bf16_f32 v143, v70, v71
	s_waitcnt lgkmcnt(10)
	v_mfma_f32_32x32x16_bf16 v[80:95], v[80:83], v[156:159], 0
	ds_read_b64_tr_b16 v[68:69], v182 offset:41984
	ds_read_b64_tr_b16 v[70:71], v182 offset:42496
	v_add_f32_e32 v128, v74, v128
	v_add_f32_e32 v128, v75, v128
	v_add_f32_e32 v128, v76, v128
	v_add_f32_e32 v128, v77, v128
	v_cvt_pk_bf16_f32 v136, v72, v73
	v_cvt_pk_bf16_f32 v137, v74, v75
	s_waitcnt lgkmcnt(11)
	v_mfma_f32_32x32x16_bf16 v[96:111], v[164:167], v[152:155], v[96:111]
	ds_read_b64_tr_b16 v[72:73], v182 offset:46080
	ds_read_b64_tr_b16 v[74:75], v182 offset:46592
	v_add_f32_e32 v128, v78, v128
	v_add_f32_e32 v128, v79, v128
	v_add_f32_e32 v128, v48, v128
	v_add_f32_e32 v128, v49, v128
	v_cvt_pk_bf16_f32 v138, v76, v77
	v_cvt_pk_bf16_f32 v139, v78, v79
	s_waitcnt lgkmcnt(12)
	v_mfma_f32_32x32x16_bf16 v[80:95], v[160:163], v[152:155], v[80:95]
	ds_read_b64_tr_b16 v[76:77], v182 offset:43008
	ds_read_b64_tr_b16 v[78:79], v182 offset:43520
	v_add_f32_e32 v128, v50, v128
	v_add_f32_e32 v128, v51, v128
	v_add_f32_e32 v128, v52, v128
	v_add_f32_e32 v128, v53, v128
	v_cvt_pk_bf16_f32 v132, v48, v49
	v_cvt_pk_bf16_f32 v133, v50, v51
	s_waitcnt lgkmcnt(13)
	v_mfma_f32_32x32x16_bf16 v[96:111], v[124:127], v[148:151], v[96:111]
	ds_read_b64_tr_b16 v[48:49], v182 offset:47104
	ds_read_b64_tr_b16 v[50:51], v182 offset:47616
	v_add_f32_e32 v124, v54, v128
	v_add_f32_e32 v124, v55, v124
	v_add_f32_e32 v124, v56, v124
	v_add_f32_e32 v124, v57, v124
	v_cvt_pk_bf16_f32 v134, v52, v53
	v_cvt_pk_bf16_f32 v135, v54, v55
	s_waitcnt lgkmcnt(14)
	v_mfma_f32_32x32x16_bf16 v[80:95], v[120:123], v[148:151], v[80:95]
	ds_read_b64_tr_b16 v[52:53], v182 offset:44032
	ds_read_b64_tr_b16 v[54:55], v182 offset:44544
	v_add_f32_e32 v120, v58, v124
	v_add_f32_e32 v120, v59, v120
	v_add_f32_e32 v120, v60, v120
	v_add_f32_e32 v120, v61, v120
	v_cvt_pk_bf16_f32 v128, v56, v57
	v_cvt_pk_bf16_f32 v129, v58, v59
	s_waitcnt lgkmcnt(14)
	v_mfma_f32_32x32x16_bf16 v[96:111], v[116:119], v[144:147], v[96:111]
	ds_read_b64_tr_b16 v[56:57], v182 offset:48128
	ds_read_b64_tr_b16 v[58:59], v182 offset:48640
	v_add_f32_e32 v116, v62, v120
	v_add_f32_e32 v116, v63, v116
	v_add_f32_e32 v116, 0, v116
	v_cvt_pk_bf16_f32 v130, v60, v61
	v_cvt_pk_bf16_f32 v131, v62, v63
	v_mfma_f32_32x32x16_bf16 v[80:95], v[112:115], v[144:147], v[80:95]
	v_lshl_add_u64 v[60:61], v[172:173], 0, s[40:41]
	s_mov_b32 s35, m0
	s_mov_b32 m0, s33
	s_nop 0
	global_load_lds_dwordx4 v[60:61], off
	s_mov_b32 m0, s35
	s_add_i32 s33, s34, s17
	v_lshl_add_u64 v[60:61], v[170:171], 0, s[42:43]
	s_add_i32 s17, s33, 0x8000
	s_mov_b32 s34, m0
	s_mov_b32 m0, s17
	s_nop 0
	global_load_lds_dwordx4 v[60:61], off
	s_mov_b32 m0, s34
	v_add_f32_e32 v175, v186, v116
	s_waitcnt lgkmcnt(14)
	v_mfma_f32_32x32x16_bf16 v[16:31], v[140:143], v[188:191], v[16:31]
	v_exp_f32_e32 v96, v96
	v_exp_f32_e32 v97, v97
	v_exp_f32_e32 v98, v98
	v_exp_f32_e32 v99, v99
	s_waitcnt lgkmcnt(12)
	v_mfma_f32_32x32x16_bf16 v[32:47], v[140:143], v[64:67], v[32:47]
	v_exp_f32_e32 v100, v100
	v_exp_f32_e32 v101, v101
	v_exp_f32_e32 v102, v102
	v_exp_f32_e32 v103, v103
	ds_read_b128 v[60:63], v234 offset:8192
	ds_read_b128 v[64:67], v234 offset:12288
	s_waitcnt lgkmcnt(12)
	v_mfma_f32_32x32x16_bf16 v[16:31], v[136:139], v[68:71], v[16:31]
	v_exp_f32_e32 v104, v104
	v_exp_f32_e32 v105, v105
	v_exp_f32_e32 v106, v106
	v_exp_f32_e32 v107, v107
	ds_read_b128 v[68:71], v235 offset:8192
	ds_read_b128 v[160:163], v235 offset:12288
	s_waitcnt lgkmcnt(12)
	v_mfma_f32_32x32x16_bf16 v[32:47], v[136:139], v[72:75], v[32:47]
	v_exp_f32_e32 v108, v108
	v_exp_f32_e32 v109, v109
	v_exp_f32_e32 v110, v110
	v_exp_f32_e32 v111, v111
	ds_read_b128 v[72:75], v236 offset:8192
	ds_read_b128 v[164:167], v236 offset:12288
	s_waitcnt lgkmcnt(12)
	v_mfma_f32_32x32x16_bf16 v[16:31], v[132:135], v[76:79], v[16:31]
	v_exp_f32_e32 v80, v80
	v_exp_f32_e32 v81, v81
	v_exp_f32_e32 v82, v82
	v_exp_f32_e32 v83, v83
	ds_read_b128 v[76:79], v237 offset:8192
	ds_read_b128 v[184:187], v237 offset:12288
	s_waitcnt lgkmcnt(12)
	v_mfma_f32_32x32x16_bf16 v[32:47], v[132:135], v[48:51], v[32:47]
	v_exp_f32_e32 v84, v84
	v_exp_f32_e32 v85, v85
	v_exp_f32_e32 v86, v86
	v_exp_f32_e32 v87, v87
	s_waitcnt lgkmcnt(10)
	v_mfma_f32_32x32x16_bf16 v[16:31], v[128:131], v[52:55], v[16:31]
	v_exp_f32_e32 v88, v88
	v_exp_f32_e32 v89, v89
	v_exp_f32_e32 v90, v90
	v_exp_f32_e32 v91, v91
	s_waitcnt lgkmcnt(8)
	v_mfma_f32_32x32x16_bf16 v[32:47], v[128:131], v[56:59], v[32:47]
	v_exp_f32_e32 v92, v92
	v_exp_f32_e32 v93, v93
	v_exp_f32_e32 v94, v94
	v_exp_f32_e32 v95, v95
	s_waitcnt vmcnt(2) lgkmcnt(0)
	s_barrier
;   #define RESC() do{ if(!NOMAX&&resc){ asm volatile("s_waitcnt lgkmcnt(0)":::"memory"); \
;       _Pragma("unroll") for(int d_=0;d_<2*VM;++d_) _Pragma("unroll") for(int r=0;r<16;++r)o[d_][r]*=wsf[crow(r,hi)]; } }while(0)
;   #define ROT() do{sl_prev=sl_cur;sl_cur=sl_next;sl_next=(sl_next==(NSLOT-1)*SLOTB)?0:sl_next+SLOTB;}while(0)
;   #define ENDW(tt) do{ if((tt)+3<NT){ if constexpr(VM==2){WAIT_BAR(3);}else{WAIT_BAR(2);} } else if((tt)+2<NT){ if constexpr(VM==2){WAIT_BAR(2);}else{WAIT_BAR(1);} } else {WAIT_BAR(0);} }while(0)
; template<int THRL,int VM,bool NOMAX> __device__ __forceinline__ void attn_unit(const bf16*Qb,const bf16*__restrict__ Kh,const bf16*__restrict__ Vh,bf16*Ob,const int NT,const int sp,float*wscr,char*shm){
;     ...
;   for(;t+1<NT;t+=2){
;     STEP(pB0,pB1,pA0,pA1,t,(t+3<NT),(t+1<NT),(t+1<NT));       ENDW(t);   RESC(); ROT();
	ds_read_b64_tr_b16 v[188:189], v182 offset:24576
	ds_read_b64_tr_b16 v[190:191], v182 offset:25088
	v_add_f32_e32 v48, v96, v97
	v_add_f32_e32 v48, v98, v48
	v_add_f32_e32 v48, v99, v48
	v_add_f32_e32 v48, v100, v48
	v_add_f32_e32 v48, v101, v48
	v_cvt_pk_bf16_f32 v140, v96, v97
	v_cvt_pk_bf16_f32 v141, v98, v99
	s_waitcnt lgkmcnt(9)
	v_mfma_f32_32x32x16_bf16 v[112:127], v[60:63], v[156:159], 0
	ds_read_b64_tr_b16 v[96:97], v182 offset:28672
	ds_read_b64_tr_b16 v[98:99], v182 offset:29184
	v_add_f32_e32 v48, v102, v48
	v_add_f32_e32 v48, v103, v48
	v_add_f32_e32 v48, v104, v48
	v_add_f32_e32 v128, v105, v48
	s_waitcnt lgkmcnt(10)
	v_mfma_f32_32x32x16_bf16 v[48:63], v[64:67], v[156:159], 0
	v_cvt_pk_bf16_f32 v142, v100, v101
	v_cvt_pk_bf16_f32 v143, v102, v103
	ds_read_b64_tr_b16 v[64:65], v182 offset:25600
	ds_read_b64_tr_b16 v[66:67], v182 offset:26112
	v_add_f32_e32 v100, v106, v128
	v_add_f32_e32 v100, v107, v100
	v_add_f32_e32 v100, v108, v100
	v_add_f32_e32 v100, v109, v100
	v_cvt_pk_bf16_f32 v136, v104, v105
	v_cvt_pk_bf16_f32 v137, v106, v107
	s_waitcnt lgkmcnt(11)
	v_mfma_f32_32x32x16_bf16 v[112:127], v[68:71], v[152:155], v[112:127]
	ds_read_b64_tr_b16 v[68:69], v182 offset:29696
	ds_read_b64_tr_b16 v[70:71], v182 offset:30208
	s_waitcnt lgkmcnt(12)
	v_mfma_f32_32x32x16_bf16 v[48:63], v[160:163], v[152:155], v[48:63]
	v_add_f32_e32 v100, v110, v100
	v_add_f32_e32 v100, v111, v100
	v_add_f32_e32 v100, v80, v100
	v_add_f32_e32 v104, v81, v100
	v_cvt_pk_bf16_f32 v138, v108, v109
	v_cvt_pk_bf16_f32 v139, v110, v111
	ds_read_b64_tr_b16 v[100:101], v182 offset:26624
	ds_read_b64_tr_b16 v[102:103], v182 offset:27136
	v_add_f32_e32 v104, v82, v104
	v_add_f32_e32 v104, v83, v104
	v_add_f32_e32 v104, v84, v104
	v_add_f32_e32 v104, v85, v104
	v_cvt_pk_bf16_f32 v132, v80, v81
	v_cvt_pk_bf16_f32 v133, v82, v83
	s_waitcnt lgkmcnt(13)
	v_mfma_f32_32x32x16_bf16 v[112:127], v[72:75], v[148:151], v[112:127]
	ds_read_b64_tr_b16 v[72:73], v182 offset:30720
	ds_read_b64_tr_b16 v[74:75], v182 offset:31232
	s_waitcnt lgkmcnt(14)
	v_mfma_f32_32x32x16_bf16 v[48:63], v[164:167], v[148:151], v[48:63]
	v_add_f32_e32 v80, v86, v104
	v_add_f32_e32 v80, v87, v80
	v_add_f32_e32 v80, v88, v80
	v_add_f32_e32 v104, v89, v80
	v_cvt_pk_bf16_f32 v134, v84, v85
	v_cvt_pk_bf16_f32 v135, v86, v87
	ds_read_b64_tr_b16 v[80:81], v182 offset:27648
	ds_read_b64_tr_b16 v[82:83], v182 offset:28160
	v_add_f32_e32 v84, v90, v104
	v_add_f32_e32 v84, v91, v84
	v_add_f32_e32 v84, v92, v84
	v_add_f32_e32 v84, v93, v84
	v_cvt_pk_bf16_f32 v128, v88, v89
	v_cvt_pk_bf16_f32 v129, v90, v91
	s_waitcnt lgkmcnt(14)
	v_mfma_f32_32x32x16_bf16 v[112:127], v[76:79], v[144:147], v[112:127]
	ds_read_b64_tr_b16 v[76:77], v182 offset:31744
	ds_read_b64_tr_b16 v[78:79], v182 offset:32256
	v_mfma_f32_32x32x16_bf16 v[48:63], v[184:187], v[144:147], v[48:63]
	v_add_f32_e32 v84, v94, v84
	v_add_f32_e32 v84, v95, v84
	v_add_f32_e32 v84, 0, v84
	v_cvt_pk_bf16_f32 v130, v92, v93
	v_cvt_pk_bf16_f32 v131, v94, v95
	s_nop 0
	v_add_f32_e32 v175, v175, v84
	v_lshl_add_u64 v[84:85], v[172:173], 0, s[44:45]
	s_add_i32 s34, s33, 0x2000
	s_mov_b32 s35, m0
	s_mov_b32 m0, s34
	s_nop 0
	global_load_lds_dwordx4 v[84:85], off
	s_mov_b32 m0, s35
	v_lshl_add_u64 v[84:85], v[170:171], 0, s[48:49]
	s_add_i32 s33, s33, 0xa000
	s_mov_b32 s34, m0
	s_mov_b32 m0, s33
	s_nop 0
	global_load_lds_dwordx4 v[84:85], off
	s_mov_b32 m0, s34
	s_waitcnt lgkmcnt(14)
	v_mfma_f32_32x32x16_bf16 v[16:31], v[140:143], v[188:191], v[16:31]
	v_exp_f32_e32 v112, v112
	v_exp_f32_e32 v113, v113
	v_exp_f32_e32 v114, v114
	v_exp_f32_e32 v115, v115
	s_waitcnt lgkmcnt(12)
	v_mfma_f32_32x32x16_bf16 v[32:47], v[140:143], v[96:99], v[32:47]
	v_exp_f32_e32 v116, v116
	v_exp_f32_e32 v117, v117
	v_exp_f32_e32 v118, v118
	v_exp_f32_e32 v119, v119
	ds_read_b128 v[84:87], v234 offset:16384
	ds_read_b128 v[96:99], v234 offset:20480
	s_waitcnt lgkmcnt(12)
	v_mfma_f32_32x32x16_bf16 v[16:31], v[136:139], v[64:67], v[16:31]
	v_exp_f32_e32 v120, v120
	v_exp_f32_e32 v121, v121
	v_exp_f32_e32 v122, v122
	v_exp_f32_e32 v123, v123
	ds_read_b128 v[104:107], v235 offset:16384
	ds_read_b128 v[108:111], v235 offset:20480
	s_waitcnt lgkmcnt(12)
	v_mfma_f32_32x32x16_bf16 v[32:47], v[136:139], v[68:71], v[32:47]
	v_exp_f32_e32 v124, v124
	v_exp_f32_e32 v125, v125
	v_exp_f32_e32 v126, v126
	v_exp_f32_e32 v127, v127
	ds_read_b128 v[160:163], v236 offset:16384
	ds_read_b128 v[164:167], v236 offset:20480
	s_waitcnt lgkmcnt(12)
	v_mfma_f32_32x32x16_bf16 v[16:31], v[132:135], v[100:103], v[16:31]
	v_exp_f32_e32 v48, v48
	v_exp_f32_e32 v49, v49
	v_exp_f32_e32 v50, v50
	v_exp_f32_e32 v51, v51
	ds_read_b128 v[100:103], v237 offset:16384
	ds_read_b128 v[184:187], v237 offset:20480
	s_waitcnt lgkmcnt(12)
	v_mfma_f32_32x32x16_bf16 v[32:47], v[132:135], v[72:75], v[32:47]
	v_exp_f32_e32 v52, v52
	v_exp_f32_e32 v53, v53
	v_exp_f32_e32 v54, v54
	v_exp_f32_e32 v55, v55
	s_waitcnt lgkmcnt(10)
	v_mfma_f32_32x32x16_bf16 v[16:31], v[128:131], v[80:83], v[16:31]
	v_exp_f32_e32 v56, v56
	v_exp_f32_e32 v57, v57
	v_exp_f32_e32 v58, v58
	v_exp_f32_e32 v59, v59
	s_waitcnt lgkmcnt(8)
	v_mfma_f32_32x32x16_bf16 v[32:47], v[128:131], v[76:79], v[32:47]
	v_exp_f32_e32 v60, v60
	v_exp_f32_e32 v61, v61
	v_exp_f32_e32 v62, v62
	v_exp_f32_e32 v63, v63
	s_waitcnt vmcnt(2) lgkmcnt(0)
	s_barrier
;   #define RESC() do{ if(!NOMAX&&resc){ asm volatile("s_waitcnt lgkmcnt(0)":::"memory"); \
;       _Pragma("unroll") for(int d_=0;d_<2*VM;++d_) _Pragma("unroll") for(int r=0;r<16;++r)o[d_][r]*=wsf[crow(r,hi)]; } }while(0)
;   #define ROT() do{sl_prev=sl_cur;sl_cur=sl_next;sl_next=(sl_next==(NSLOT-1)*SLOTB)?0:sl_next+SLOTB;}while(0)
;   #define ENDW(tt) do{ if((tt)+3<NT){ if constexpr(VM==2){WAIT_BAR(3);}else{WAIT_BAR(2);} } else if((tt)+2<NT){ if constexpr(VM==2){WAIT_BAR(2);}else{WAIT_BAR(1);} } else {WAIT_BAR(0);} }while(0)
; template<int THRL,int VM,bool NOMAX> __device__ __forceinline__ void attn_unit(const bf16*Qb,const bf16*__restrict__ Kh,const bf16*__restrict__ Vh,bf16*Ob,const int NT,const int sp,float*wscr,char*shm){
;     ...
;   for(;t+1<NT;t+=2){
;     STEP(pB0,pB1,pA0,pA1,t,(t+3<NT),(t+1<NT),(t+1<NT));       ENDW(t);   RESC(); ROT();
	ds_read_b64_tr_b16 v[188:189], v182 offset:32768
	ds_read_b64_tr_b16 v[190:191], v182 offset:33280
	v_add_f32_e32 v64, v112, v113
	v_add_f32_e32 v64, v114, v64
	v_add_f32_e32 v64, v115, v64
	v_add_f32_e32 v64, v116, v64
	v_add_f32_e32 v64, v117, v64
	v_cvt_pk_bf16_f32 v140, v112, v113
	v_cvt_pk_bf16_f32 v141, v114, v115
	s_waitcnt lgkmcnt(9)
	v_mfma_f32_32x32x16_bf16 v[80:95], v[84:87], v[156:159], 0
	ds_read_b64_tr_b16 v[112:113], v182 offset:36864
	ds_read_b64_tr_b16 v[114:115], v182 offset:37376
	v_add_f32_e32 v64, v118, v64
	v_add_f32_e32 v64, v119, v64
	v_add_f32_e32 v64, v120, v64
	v_add_f32_e32 v128, v121, v64
	v_cvt_pk_bf16_f32 v142, v116, v117
	v_cvt_pk_bf16_f32 v143, v118, v119
	s_waitcnt lgkmcnt(10)
	v_mfma_f32_32x32x16_bf16 v[64:79], v[96:99], v[156:159], 0
	ds_read_b64_tr_b16 v[96:97], v182 offset:33792
	ds_read_b64_tr_b16 v[98:99], v182 offset:34304
	v_add_f32_e32 v116, v122, v128
	v_add_f32_e32 v116, v123, v116
	v_add_f32_e32 v116, v124, v116
	v_add_f32_e32 v116, v125, v116
	v_cvt_pk_bf16_f32 v136, v120, v121
	v_cvt_pk_bf16_f32 v137, v122, v123
	s_waitcnt lgkmcnt(11)
	v_mfma_f32_32x32x16_bf16 v[80:95], v[104:107], v[152:155], v[80:95]
	ds_read_b64_tr_b16 v[104:105], v182 offset:37888
	ds_read_b64_tr_b16 v[106:107], v182 offset:38400
	v_add_f32_e32 v116, v126, v116
	v_add_f32_e32 v116, v127, v116
	v_add_f32_e32 v116, v48, v116
	v_add_f32_e32 v116, v49, v116
	v_cvt_pk_bf16_f32 v138, v124, v125
	v_cvt_pk_bf16_f32 v139, v126, v127
	s_waitcnt lgkmcnt(12)
	v_mfma_f32_32x32x16_bf16 v[64:79], v[108:111], v[152:155], v[64:79]
	ds_read_b64_tr_b16 v[108:109], v182 offset:34816
	ds_read_b64_tr_b16 v[110:111], v182 offset:35328
	v_add_f32_e32 v116, v50, v116
	v_add_f32_e32 v116, v51, v116
	v_add_f32_e32 v116, v52, v116
	v_add_f32_e32 v116, v53, v116
	v_cvt_pk_bf16_f32 v132, v48, v49
	v_cvt_pk_bf16_f32 v133, v50, v51
	s_waitcnt lgkmcnt(13)
	v_mfma_f32_32x32x16_bf16 v[80:95], v[160:163], v[148:151], v[80:95]
	ds_read_b64_tr_b16 v[48:49], v182 offset:38912
	ds_read_b64_tr_b16 v[50:51], v182 offset:39424
	v_add_f32_e32 v116, v54, v116
	v_add_f32_e32 v116, v55, v116
	v_add_f32_e32 v116, v56, v116
	v_add_f32_e32 v116, v57, v116
	v_cvt_pk_bf16_f32 v134, v52, v53
	v_cvt_pk_bf16_f32 v135, v54, v55
	s_waitcnt lgkmcnt(14)
	v_mfma_f32_32x32x16_bf16 v[64:79], v[164:167], v[148:151], v[64:79]
	ds_read_b64_tr_b16 v[52:53], v182 offset:35840
	ds_read_b64_tr_b16 v[54:55], v182 offset:36352
	v_add_f32_e32 v116, v58, v116
	v_add_f32_e32 v116, v59, v116
	v_add_f32_e32 v116, v60, v116
	v_add_f32_e32 v116, v61, v116
	v_cvt_pk_bf16_f32 v128, v56, v57
	v_cvt_pk_bf16_f32 v129, v58, v59
	s_waitcnt lgkmcnt(14)
	v_mfma_f32_32x32x16_bf16 v[80:95], v[100:103], v[144:147], v[80:95]
	ds_read_b64_tr_b16 v[56:57], v182 offset:39936
	ds_read_b64_tr_b16 v[58:59], v182 offset:40448
	v_add_f32_e32 v100, v62, v116
	v_add_f32_e32 v100, v63, v100
	v_add_f32_e32 v100, 0, v100
	v_cvt_pk_bf16_f32 v130, v60, v61
	v_cvt_pk_bf16_f32 v131, v62, v63
	v_mfma_f32_32x32x16_bf16 v[64:79], v[184:187], v[144:147], v[64:79]
	v_lshl_add_u64 v[60:61], v[170:171], 0, s[40:41]
	s_mov_b32 s33, m0
	s_mov_b32 m0, s16
	s_nop 0
	global_load_lds_dwordx4 v[60:61], off
	s_mov_b32 m0, s33
	v_add_f32_e32 v172, v175, v100
	s_waitcnt lgkmcnt(14)
	v_mfma_f32_32x32x16_bf16 v[16:31], v[140:143], v[188:191], v[16:31]
	v_exp_f32_e32 v80, v80
	v_exp_f32_e32 v81, v81
	v_exp_f32_e32 v82, v82
	v_exp_f32_e32 v83, v83
	s_waitcnt lgkmcnt(12)
	v_mfma_f32_32x32x16_bf16 v[32:47], v[140:143], v[112:115], v[32:47]
	v_exp_f32_e32 v84, v84
	v_exp_f32_e32 v85, v85
	v_exp_f32_e32 v86, v86
	v_exp_f32_e32 v87, v87
	ds_read_b128 v[60:63], v234
	ds_read_b128 v[112:115], v234 offset:4096
	s_waitcnt lgkmcnt(12)
	v_mfma_f32_32x32x16_bf16 v[16:31], v[136:139], v[96:99], v[16:31]
	v_exp_f32_e32 v88, v88
	v_exp_f32_e32 v89, v89
	v_exp_f32_e32 v90, v90
	v_exp_f32_e32 v91, v91
	ds_read_b128 v[116:119], v235
	ds_read_b128 v[120:123], v235 offset:4096
	s_waitcnt lgkmcnt(12)
	v_mfma_f32_32x32x16_bf16 v[32:47], v[136:139], v[104:107], v[32:47]
	v_exp_f32_e32 v92, v92
	v_exp_f32_e32 v93, v93
	v_exp_f32_e32 v94, v94
	v_exp_f32_e32 v95, v95
	ds_read_b128 v[124:127], v236
	ds_read_b128 v[160:163], v236 offset:4096
	s_waitcnt lgkmcnt(12)
	v_mfma_f32_32x32x16_bf16 v[16:31], v[132:135], v[108:111], v[16:31]
	v_exp_f32_e32 v64, v64
	v_exp_f32_e32 v65, v65
	v_exp_f32_e32 v66, v66
	v_exp_f32_e32 v67, v67
	ds_read_b128 v[164:167], v237
	ds_read_b128 v[184:187], v237 offset:4096
	s_waitcnt lgkmcnt(12)
	v_mfma_f32_32x32x16_bf16 v[32:47], v[132:135], v[48:51], v[32:47]
	v_exp_f32_e32 v68, v68
	v_exp_f32_e32 v69, v69
	v_exp_f32_e32 v70, v70
	v_exp_f32_e32 v71, v71
	s_waitcnt lgkmcnt(10)
	v_mfma_f32_32x32x16_bf16 v[16:31], v[128:131], v[52:55], v[16:31]
	v_exp_f32_e32 v72, v72
	v_exp_f32_e32 v73, v73
	v_exp_f32_e32 v74, v74
	v_exp_f32_e32 v75, v75
	s_waitcnt lgkmcnt(8)
	v_mfma_f32_32x32x16_bf16 v[32:47], v[128:131], v[56:59], v[32:47]
	v_exp_f32_e32 v76, v76
	v_exp_f32_e32 v77, v77
	v_exp_f32_e32 v78, v78
	v_exp_f32_e32 v79, v79
	s_waitcnt vmcnt(1) lgkmcnt(0)
	s_barrier
;   #define RESC() do{ if(!NOMAX&&resc){ asm volatile("s_waitcnt lgkmcnt(0)":::"memory"); \
;       _Pragma("unroll") for(int d_=0;d_<2*VM;++d_) _Pragma("unroll") for(int r=0;r<16;++r)o[d_][r]*=wsf[crow(r,hi)]; } }while(0)
;   #define ROT() do{sl_prev=sl_cur;sl_cur=sl_next;sl_next=(sl_next==(NSLOT-1)*SLOTB)?0:sl_next+SLOTB;}while(0)
;   #define ENDW(tt) do{ if((tt)+3<NT){ if constexpr(VM==2){WAIT_BAR(3);}else{WAIT_BAR(2);} } else if((tt)+2<NT){ if constexpr(VM==2){WAIT_BAR(2);}else{WAIT_BAR(1);} } else {WAIT_BAR(0);} }while(0)
; template<int THRL,int VM,bool NOMAX> __device__ __forceinline__ void attn_unit(const bf16*Qb,const bf16*__restrict__ Kh,const bf16*__restrict__ Vh,bf16*Ob,const int NT,const int sp,float*wscr,char*shm){
;     ...
;   for(;t+1<NT;t+=2){
;     STEP(pB0,pB1,pA0,pA1,t,(t+3<NT),(t+1<NT),(t+1<NT));       ENDW(t);   RESC(); ROT();
	ds_read_b64_tr_b16 v[188:189], v182 offset:40960
	ds_read_b64_tr_b16 v[190:191], v182 offset:41472
	v_add_f32_e32 v48, v80, v81
	v_add_f32_e32 v48, v82, v48
	v_add_f32_e32 v48, v83, v48
	v_add_f32_e32 v48, v84, v48
	v_add_f32_e32 v48, v85, v48
	v_cvt_pk_bf16_f32 v140, v80, v81
	v_cvt_pk_bf16_f32 v141, v82, v83
	s_waitcnt lgkmcnt(9)
	v_mfma_f32_32x32x16_bf16 v[96:111], v[60:63], v[156:159], 0
	ds_read_b64_tr_b16 v[80:81], v182 offset:45056
	ds_read_b64_tr_b16 v[82:83], v182 offset:45568
	v_add_f32_e32 v48, v86, v48
	v_add_f32_e32 v48, v87, v48
	v_add_f32_e32 v48, v88, v48
	v_add_f32_e32 v128, v89, v48
	s_waitcnt lgkmcnt(10)
	v_mfma_f32_32x32x16_bf16 v[48:63], v[112:115], v[156:159], 0
	v_cvt_pk_bf16_f32 v142, v84, v85
	v_cvt_pk_bf16_f32 v143, v86, v87
	ds_read_b64_tr_b16 v[84:85], v182 offset:41984
	ds_read_b64_tr_b16 v[86:87], v182 offset:42496
	v_add_f32_e32 v112, v90, v128
	v_add_f32_e32 v112, v91, v112
	v_add_f32_e32 v112, v92, v112
	v_add_f32_e32 v112, v93, v112
	v_cvt_pk_bf16_f32 v136, v88, v89
	v_cvt_pk_bf16_f32 v137, v90, v91
	s_waitcnt lgkmcnt(11)
	v_mfma_f32_32x32x16_bf16 v[96:111], v[116:119], v[152:155], v[96:111]
	ds_read_b64_tr_b16 v[88:89], v182 offset:46080
	ds_read_b64_tr_b16 v[90:91], v182 offset:46592
	s_waitcnt lgkmcnt(12)
	v_mfma_f32_32x32x16_bf16 v[48:63], v[120:123], v[152:155], v[48:63]
	v_add_f32_e32 v112, v94, v112
	v_add_f32_e32 v112, v95, v112
	v_add_f32_e32 v112, v64, v112
	v_add_f32_e32 v112, v65, v112
	v_cvt_pk_bf16_f32 v138, v92, v93
	v_cvt_pk_bf16_f32 v139, v94, v95
	ds_read_b64_tr_b16 v[92:93], v182 offset:43008
	ds_read_b64_tr_b16 v[94:95], v182 offset:43520
	v_add_f32_e32 v112, v66, v112
	v_add_f32_e32 v112, v67, v112
	v_add_f32_e32 v112, v68, v112
	v_add_f32_e32 v112, v69, v112
	v_cvt_pk_bf16_f32 v132, v64, v65
	v_cvt_pk_bf16_f32 v133, v66, v67
	s_waitcnt lgkmcnt(13)
	v_mfma_f32_32x32x16_bf16 v[96:111], v[124:127], v[148:151], v[96:111]
	ds_read_b64_tr_b16 v[64:65], v182 offset:47104
	ds_read_b64_tr_b16 v[66:67], v182 offset:47616
	s_waitcnt lgkmcnt(14)
	v_mfma_f32_32x32x16_bf16 v[48:63], v[160:163], v[148:151], v[48:63]
	v_add_f32_e32 v112, v70, v112
	v_add_f32_e32 v112, v71, v112
	v_add_f32_e32 v112, v72, v112
	v_add_f32_e32 v112, v73, v112
	v_cvt_pk_bf16_f32 v134, v68, v69
	v_cvt_pk_bf16_f32 v135, v70, v71
	ds_read_b64_tr_b16 v[68:69], v182 offset:44032
	ds_read_b64_tr_b16 v[70:71], v182 offset:44544
	v_add_f32_e32 v112, v74, v112
	v_add_f32_e32 v112, v75, v112
	v_add_f32_e32 v112, v76, v112
	v_add_f32_e32 v112, v77, v112
	v_cvt_pk_bf16_f32 v128, v72, v73
	v_cvt_pk_bf16_f32 v129, v74, v75
	s_waitcnt lgkmcnt(14)
	v_mfma_f32_32x32x16_bf16 v[96:111], v[164:167], v[144:147], v[96:111]
	ds_read_b64_tr_b16 v[72:73], v182 offset:48128
	ds_read_b64_tr_b16 v[74:75], v182 offset:48640
	v_mfma_f32_32x32x16_bf16 v[48:63], v[184:187], v[144:147], v[48:63]
	v_add_f32_e32 v112, v78, v112
	v_add_f32_e32 v112, v79, v112
	v_add_f32_e32 v112, 0, v112
	v_cvt_pk_bf16_f32 v130, v76, v77
	v_cvt_pk_bf16_f32 v131, v78, v79
	v_lshl_add_u64 v[76:77], v[170:171], 0, s[44:45]
	s_mov_b32 s16, m0
	s_mov_b32 m0, s17
	s_nop 0
	global_load_lds_dwordx4 v[76:77], off
	s_mov_b32 m0, s16
	v_add_f32_e32 v120, v172, v112
	s_waitcnt lgkmcnt(14)
	v_mfma_f32_32x32x16_bf16 v[16:31], v[140:143], v[188:191], v[16:31]
	v_exp_f32_e32 v96, v96
	v_exp_f32_e32 v97, v97
	v_exp_f32_e32 v98, v98
	v_exp_f32_e32 v99, v99
	s_waitcnt lgkmcnt(12)
	v_mfma_f32_32x32x16_bf16 v[32:47], v[140:143], v[80:83], v[32:47]
	v_exp_f32_e32 v100, v100
	v_exp_f32_e32 v101, v101
	v_exp_f32_e32 v102, v102
	v_exp_f32_e32 v103, v103
	ds_read_b128 v[76:79], v234 offset:8192
	ds_read_b128 v[80:83], v234 offset:12288
	s_waitcnt lgkmcnt(12)
	v_mfma_f32_32x32x16_bf16 v[16:31], v[136:139], v[84:87], v[16:31]
	v_exp_f32_e32 v104, v104
	v_exp_f32_e32 v105, v105
	v_exp_f32_e32 v106, v106
	v_exp_f32_e32 v107, v107
	ds_read_b128 v[122:125], v235 offset:8192
	ds_read_b128 v[160:163], v235 offset:12288
	s_waitcnt lgkmcnt(12)
	v_mfma_f32_32x32x16_bf16 v[32:47], v[136:139], v[88:91], v[32:47]
	v_exp_f32_e32 v108, v108
	v_exp_f32_e32 v109, v109
	v_exp_f32_e32 v110, v110
	v_exp_f32_e32 v111, v111
	ds_read_b128 v[164:167], v236 offset:8192
	ds_read_b128 v[170:173], v236 offset:12288
	s_waitcnt lgkmcnt(12)
	v_mfma_f32_32x32x16_bf16 v[16:31], v[132:135], v[92:95], v[16:31]
	v_exp_f32_e32 v48, v48
	v_exp_f32_e32 v49, v49
	v_exp_f32_e32 v50, v50
	v_exp_f32_e32 v51, v51
	ds_read_b128 v[184:187], v237 offset:8192
	ds_read_b128 v[188:191], v237 offset:12288
	s_waitcnt lgkmcnt(12)
	v_mfma_f32_32x32x16_bf16 v[32:47], v[132:135], v[64:67], v[32:47]
	v_exp_f32_e32 v52, v52
	v_exp_f32_e32 v53, v53
	v_exp_f32_e32 v54, v54
	v_exp_f32_e32 v55, v55
	s_waitcnt lgkmcnt(10)
	v_mfma_f32_32x32x16_bf16 v[16:31], v[128:131], v[68:71], v[16:31]
	v_exp_f32_e32 v56, v56
	v_exp_f32_e32 v57, v57
	v_exp_f32_e32 v58, v58
	v_exp_f32_e32 v59, v59
	s_waitcnt lgkmcnt(8)
	v_mfma_f32_32x32x16_bf16 v[32:47], v[128:131], v[72:75], v[32:47]
	v_exp_f32_e32 v60, v60
	v_exp_f32_e32 v61, v61
	v_exp_f32_e32 v62, v62
	v_exp_f32_e32 v63, v63
	s_waitcnt vmcnt(0) lgkmcnt(0)
	s_barrier
;   #define RESC() do{ if(!NOMAX&&resc){ asm volatile("s_waitcnt lgkmcnt(0)":::"memory"); \
;       _Pragma("unroll") for(int d_=0;d_<2*VM;++d_) _Pragma("unroll") for(int r=0;r<16;++r)o[d_][r]*=wsf[crow(r,hi)]; } }while(0)
; template<int THRL,int VM,bool NOMAX> __device__ __forceinline__ void attn_unit(const bf16*Qb,const bf16*__restrict__ Kh,const bf16*__restrict__ Vh,bf16*Ob,const int NT,const int sp,float*wscr,char*shm){
;     ...
;   STEP(pB0,pB1,pA0,pA1,NT-1,false,false,false); RESC();
	ds_read_b64_tr_b16 v[112:113], v182 offset:24576
	ds_read_b64_tr_b16 v[114:115], v182 offset:25088
	v_add_f32_e32 v64, v96, v97
	v_add_f32_e32 v64, v98, v64
	v_add_f32_e32 v64, v99, v64
	v_add_f32_e32 v64, v100, v64
	v_add_f32_e32 v84, v101, v64
	v_cvt_pk_bf16_f32 v140, v96, v97
	v_cvt_pk_bf16_f32 v141, v98, v99
	s_waitcnt lgkmcnt(9)
	v_mfma_f32_32x32x16_bf16 v[64:79], v[76:79], v[156:159], 0
	ds_read_b64_tr_b16 v[96:97], v182 offset:28672
	ds_read_b64_tr_b16 v[98:99], v182 offset:29184
	v_add_f32_e32 v84, v102, v84
	v_add_f32_e32 v84, v103, v84
	v_add_f32_e32 v84, v104, v84
	v_add_f32_e32 v121, v105, v84
	v_cvt_pk_bf16_f32 v142, v100, v101
	v_cvt_pk_bf16_f32 v143, v102, v103
	s_waitcnt lgkmcnt(10)
	v_mfma_f32_32x32x16_bf16 v[80:95], v[80:83], v[156:159], 0
	ds_read_b64_tr_b16 v[116:117], v182 offset:25600
	ds_read_b64_tr_b16 v[118:119], v182 offset:26112
	v_add_f32_e32 v100, v106, v121
	v_add_f32_e32 v100, v107, v100
	v_add_f32_e32 v100, v108, v100
	v_add_f32_e32 v121, v109, v100
	v_cvt_pk_bf16_f32 v136, v104, v105
	v_cvt_pk_bf16_f32 v137, v106, v107
	s_waitcnt lgkmcnt(11)
	v_mfma_f32_32x32x16_bf16 v[64:79], v[122:125], v[152:155], v[64:79]
	ds_read_b64_tr_b16 v[100:101], v182 offset:29696
	ds_read_b64_tr_b16 v[102:103], v182 offset:30208
	v_add_f32_e32 v104, v110, v121
	v_add_f32_e32 v104, v111, v104
	v_add_f32_e32 v104, v48, v104
	v_add_f32_e32 v121, v49, v104
	v_cvt_pk_bf16_f32 v138, v108, v109
	v_cvt_pk_bf16_f32 v139, v110, v111
	s_waitcnt lgkmcnt(12)
	v_mfma_f32_32x32x16_bf16 v[80:95], v[160:163], v[152:155], v[80:95]
	ds_read_b64_tr_b16 v[104:105], v182 offset:26624
	ds_read_b64_tr_b16 v[106:107], v182 offset:27136
	v_add_f32_e32 v108, v50, v121
	v_add_f32_e32 v108, v51, v108
	v_add_f32_e32 v108, v52, v108
	v_add_f32_e32 v108, v53, v108
	v_cvt_pk_bf16_f32 v132, v48, v49
	v_cvt_pk_bf16_f32 v133, v50, v51
	s_waitcnt lgkmcnt(13)
	v_mfma_f32_32x32x16_bf16 v[64:79], v[164:167], v[148:151], v[64:79]
	ds_read_b64_tr_b16 v[48:49], v182 offset:30720
	ds_read_b64_tr_b16 v[50:51], v182 offset:31232
	v_add_f32_e32 v108, v54, v108
	v_add_f32_e32 v108, v55, v108
	v_add_f32_e32 v108, v56, v108
	v_add_f32_e32 v121, v57, v108
	v_cvt_pk_bf16_f32 v134, v52, v53
	v_cvt_pk_bf16_f32 v135, v54, v55
	s_waitcnt lgkmcnt(14)
	v_mfma_f32_32x32x16_bf16 v[80:95], v[170:173], v[148:151], v[80:95]
	ds_read_b64_tr_b16 v[108:109], v182 offset:27648
	ds_read_b64_tr_b16 v[110:111], v182 offset:28160
	v_add_f32_e32 v52, v58, v121
	v_add_f32_e32 v52, v59, v52
	v_add_f32_e32 v52, v60, v52
	v_add_f32_e32 v121, v61, v52
	v_cvt_pk_bf16_f32 v128, v56, v57
	v_cvt_pk_bf16_f32 v129, v58, v59
	s_waitcnt lgkmcnt(14)
	v_mfma_f32_32x32x16_bf16 v[64:79], v[184:187], v[144:147], v[64:79]
	ds_read_b64_tr_b16 v[52:53], v182 offset:31744
	ds_read_b64_tr_b16 v[54:55], v182 offset:32256
	v_add_f32_e32 v56, v62, v121
	v_add_f32_e32 v56, v63, v56
	v_add_f32_e32 v56, 0, v56
	v_cvt_pk_bf16_f32 v130, v60, v61
	v_cvt_pk_bf16_f32 v131, v62, v63
	v_mfma_f32_32x32x16_bf16 v[80:95], v[188:191], v[144:147], v[80:95]
	s_nop 3
	v_exp_f32_e32 v64, v64
	v_exp_f32_e32 v65, v65
	v_exp_f32_e32 v66, v66
	v_exp_f32_e32 v67, v67
	s_nop 0
	v_exp_f32_e32 v68, v68
	v_exp_f32_e32 v69, v69
	v_exp_f32_e32 v70, v70
	v_exp_f32_e32 v71, v71
	s_nop 0
	v_exp_f32_e32 v72, v72
	v_exp_f32_e32 v73, v73
	v_exp_f32_e32 v74, v74
	v_exp_f32_e32 v75, v75
	s_nop 0
	v_exp_f32_e32 v76, v76
	v_exp_f32_e32 v77, v77
	v_exp_f32_e32 v78, v78
	v_exp_f32_e32 v79, v79
	v_exp_f32_e32 v80, v80
	v_exp_f32_e32 v81, v81
	v_exp_f32_e32 v82, v82
	v_exp_f32_e32 v83, v83
	s_nop 0
	v_exp_f32_e32 v84, v84
	v_exp_f32_e32 v85, v85
	v_exp_f32_e32 v86, v86
	v_exp_f32_e32 v87, v87
	s_nop 0
	v_exp_f32_e32 v88, v88
	v_exp_f32_e32 v89, v89
	v_exp_f32_e32 v90, v90
	v_exp_f32_e32 v91, v91
	s_nop 0
	v_exp_f32_e32 v92, v92
	v_exp_f32_e32 v93, v93
	v_exp_f32_e32 v94, v94
	v_exp_f32_e32 v95, v95
	s_waitcnt lgkmcnt(14)
; #define SBAR() __builtin_amdgcn_sched_barrier(0)
;   #define PKW(P,B) cvtpk_s(P[B],P[B+1])
; __device__ __forceinline__ void pv(f32x16*o,int vb,bf16x8 pa0,bf16x8 pa1,bf16x8 pa2,bf16x8 pa3){
;   #pragma unroll
;   for(int d0=0;d0<2;++d0){s16x4 lo[4],hi[4];
;     #pragma unroll
;     for(int ks=0;ks<4;++ks){
;       asm volatile("ds_read_b64_tr_b16 %0,%1 offset:%c2":"=&v"(lo[ks]):"v"(vb),"i"(d0*4096+ks*1024):"memory");
;       asm volatile("ds_read_b64_tr_b16 %0,%1 offset:%c2":"=&v"(hi[ks]):"v"(vb),"i"(d0*4096+ks*1024+512):"memory");}
;     asm volatile("s_waitcnt lgkmcnt(0)":::"memory");SBAR();
;     ...
;     o[d0]=__builtin_amdgcn_mfma_f32_32x32x16_bf16(pa0,PK(0),o[d0],0,0,0);
;     o[d0]=__builtin_amdgcn_mfma_f32_32x32x16_bf16(pa1,PK(1),o[d0],0,0,0);
;     o[d0]=__builtin_amdgcn_mfma_f32_32x32x16_bf16(pa2,PK(2),o[d0],0,0,0);
;     o[d0]=__builtin_amdgcn_mfma_f32_32x32x16_bf16(pa3,PK(3),o[d0],0,0,0);
;     ...
;   }
; }
; template<int THRL,int VM,bool NOMAX> __device__ __forceinline__ void attn_unit(const bf16*Qb,const bf16*__restrict__ Kh,const bf16*__restrict__ Vh,bf16*Ob,const int NT,const int sp,float*wscr,char*shm){
;     ...
;   { float sacc=pB0[0]+pB0[1]; _Pragma("unroll") for(int r=2;r<16;++r)sacc+=pB0[r]; _Pragma("unroll") for(int r=0;r<16;++r)sacc+=pB1[r]; l_reg+=sacc;
;     pw0=(u32x4){PKW(pB0,0),PKW(pB0,2),PKW(pB0,4),PKW(pB0,6)};pw1=(u32x4){PKW(pB0,8),PKW(pB0,10),PKW(pB0,12),PKW(pB0,14)};pw2=(u32x4){PKW(pB1,0),PKW(pB1,2),PKW(pB1,4),PKW(pB1,6)};pw3=(u32x4){PKW(pB1,8),PKW(pB1,10),PKW(pB1,12),PKW(pB1,14)};
;     SBAR(); pv(o,vb0+VM*sl_cur,PAF(0),PAF(1),PAF(2),PAF(3)); if constexpr(VM==2) pv(o+2,vb0+VM*sl_cur+8192,PAF(0),PAF(1),PAF(2),PAF(3)); }
;     ...
;   {auto rr=__builtin_amdgcn_permlane32_swap(__float_as_uint(l_reg),__float_as_uint(l_reg),false,false);l_reg=__uint_as_float(rr[0])+__uint_as_float(rr[1]);}
;   if(hi==0)wsf[32+r32]=l_reg;asm volatile("s_waitcnt lgkmcnt(0)":::"memory");
	v_mfma_f32_32x32x16_bf16 v[16:31], v[140:143], v[112:115], v[16:31]
	v_add_f32_e32 v57, v64, v65
	v_add_f32_e32 v57, v66, v57
	v_add_f32_e32 v57, v67, v57
	v_add_f32_e32 v57, v68, v57
	v_add_f32_e32 v57, v69, v57
	v_add_f32_e32 v57, v70, v57
	v_add_f32_e32 v57, v71, v57
	s_waitcnt lgkmcnt(12)
	v_mfma_f32_32x32x16_bf16 v[32:47], v[140:143], v[96:99], v[32:47]
	v_add_f32_e32 v57, v72, v57
	v_add_f32_e32 v57, v73, v57
	v_add_f32_e32 v57, v74, v57
	v_add_f32_e32 v57, v75, v57
	v_add_f32_e32 v57, v76, v57
	v_add_f32_e32 v57, v77, v57
	v_add_f32_e32 v57, v78, v57
	s_waitcnt lgkmcnt(10)
	v_mfma_f32_32x32x16_bf16 v[16:31], v[136:139], v[116:119], v[16:31]
	v_add_f32_e32 v57, v79, v57
	v_add_f32_e32 v57, v80, v57
	v_add_f32_e32 v57, v81, v57
	v_add_f32_e32 v57, v82, v57
	v_add_f32_e32 v57, v83, v57
	v_add_f32_e32 v57, v84, v57
	v_add_f32_e32 v57, v85, v57
	s_waitcnt lgkmcnt(8)
	v_mfma_f32_32x32x16_bf16 v[32:47], v[136:139], v[100:103], v[32:47]
	v_add_f32_e32 v57, v86, v57
	v_add_f32_e32 v57, v87, v57
	v_add_f32_e32 v57, v88, v57
	v_add_f32_e32 v57, v89, v57
	v_add_f32_e32 v57, v90, v57
	v_add_f32_e32 v57, v91, v57
	v_add_f32_e32 v57, v92, v57
	s_waitcnt lgkmcnt(6)
	v_mfma_f32_32x32x16_bf16 v[16:31], v[132:135], v[104:107], v[16:31]
	v_add_f32_e32 v57, v93, v57
	v_add_f32_e32 v57, v94, v57
	v_add_f32_e32 v57, v95, v57
	v_add_f32_e32 v56, v120, v56
	v_add_f32_e32 v56, v56, v57
	v_cvt_pk_bf16_f32 v58, v64, v65
	v_cvt_pk_bf16_f32 v59, v66, v67
	s_waitcnt lgkmcnt(4)
	v_mfma_f32_32x32x16_bf16 v[32:47], v[132:135], v[48:51], v[32:47]
	v_cvt_pk_bf16_f32 v48, v80, v81
	v_cvt_pk_bf16_f32 v60, v68, v69
	v_cvt_pk_bf16_f32 v61, v70, v71
	v_cvt_pk_bf16_f32 v62, v72, v73
	v_cvt_pk_bf16_f32 v63, v74, v75
	v_cvt_pk_bf16_f32 v64, v76, v77
	v_cvt_pk_bf16_f32 v65, v78, v79
	s_waitcnt lgkmcnt(2)
	v_mfma_f32_32x32x16_bf16 v[16:31], v[128:131], v[108:111], v[16:31]
	v_cvt_pk_bf16_f32 v49, v82, v83
	v_cvt_pk_bf16_f32 v50, v84, v85
	v_cvt_pk_bf16_f32 v51, v86, v87
	v_cvt_pk_bf16_f32 v66, v88, v89
	v_cvt_pk_bf16_f32 v67, v90, v91
	v_cvt_pk_bf16_f32 v68, v92, v93
	v_cvt_pk_bf16_f32 v69, v94, v95
	s_waitcnt lgkmcnt(0)
	v_mfma_f32_32x32x16_bf16 v[32:47], v[128:131], v[52:55], v[32:47]
	v_add3_u32 v57, v174, v168, s18
	ds_read_b64_tr_b16 v[52:53],v57 offset:0
	ds_read_b64_tr_b16 v[54:55],v57 offset:512
	ds_read_b64_tr_b16 v[70:71],v57 offset:1024
	ds_read_b64_tr_b16 v[72:73],v57 offset:1536
	ds_read_b64_tr_b16 v[74:75],v57 offset:2048
	ds_read_b64_tr_b16 v[76:77],v57 offset:2560
	ds_read_b64_tr_b16 v[78:79],v57 offset:3072
	ds_read_b64_tr_b16 v[80:81],v57 offset:3584
	s_waitcnt lgkmcnt(0)
	s_nop 0
	v_mfma_f32_32x32x16_bf16 v[16:31], v[58:61], v[52:55], v[16:31]
	ds_read_b64_tr_b16 v[52:53],v57 offset:4096
	ds_read_b64_tr_b16 v[54:55],v57 offset:4608
	v_mfma_f32_32x32x16_bf16 v[16:31], v[62:65], v[70:73], v[16:31]
	ds_read_b64_tr_b16 v[70:71],v57 offset:5120
	ds_read_b64_tr_b16 v[72:73],v57 offset:5632
	v_mfma_f32_32x32x16_bf16 v[16:31], v[48:51], v[74:77], v[16:31]
	ds_read_b64_tr_b16 v[74:75],v57 offset:6144
	ds_read_b64_tr_b16 v[76:77],v57 offset:6656
	ds_read_b64_tr_b16 v[82:83],v57 offset:7168
	ds_read_b64_tr_b16 v[84:85],v57 offset:7680
	s_waitcnt lgkmcnt(0)
	v_mfma_f32_32x32x16_bf16 v[16:31], v[66:69], v[78:81], v[16:31]
	v_mfma_f32_32x32x16_bf16 v[32:47], v[58:61], v[52:55], v[32:47]
	v_cmp_gt_u32_e32 vcc, 32, v178
	v_mfma_f32_32x32x16_bf16 v[32:47], v[62:65], v[70:73], v[32:47]
	v_mfma_f32_32x32x16_bf16 v[32:47], v[48:51], v[74:77], v[32:47]
	v_mov_b32_e32 v48, v56
	s_nop 1
	v_permlane32_swap_b32_e32 v56, v48
	v_mfma_f32_32x32x16_bf16 v[32:47], v[66:69], v[82:85], v[32:47]
	s_and_saveexec_b64 s[16:17], vcc
	s_cbranch_execz .LBB0_878
	v_add_f32_e32 v48, v56, v48
	v_lshl_add_u32 v49, v180, 2, s29
	ds_write_b32 v49, v48 offset:49280
	s_branch .LBB0_878

; #define WAIT_BAR(N) asm volatile("s_waitcnt vmcnt(" #N ") lgkmcnt(0)\n\ts_barrier":::"memory")
;   #define RESC() do{ if(!NOMAX&&resc){ asm volatile("s_waitcnt lgkmcnt(0)":::"memory"); \
;       _Pragma("unroll") for(int d_=0;d_<2*VM;++d_) _Pragma("unroll") for(int r=0;r<16;++r)o[d_][r]*=wsf[crow(r,hi)]; } }while(0)
;   #define ROT() do{sl_prev=sl_cur;sl_cur=sl_next;sl_next=(sl_next==(NSLOT-1)*SLOTB)?0:sl_next+SLOTB;}while(0)
; template<int THRL,int VM,bool NOMAX> __device__ __forceinline__ void attn_unit(const bf16*Qb,const bf16*__restrict__ Kh,const bf16*__restrict__ Vh,bf16*Ob,const int NT,const int sp,float*wscr,char*shm){
;     ...
;   int t=1;
;   for(;t+5<NT;t+=2){
;     STEP(pB0,pB1,pA0,pA1,t,true,true,true);     if constexpr(VM==2){WAIT_BAR(3);}else{WAIT_BAR(2);} RESC(); ROT();
;     STEP(pA0,pA1,pB0,pB1,t+1,true,true,true);   if constexpr(VM==2){WAIT_BAR(3);}else{WAIT_BAR(2);} RESC(); ROT();
;   }
.LBB0_891:
	v_mfma_f32_32x32x16_bf16 v[96:111], v[84:87], v[156:159], 0
	v_add_u32_e32 v187, s52, v168
	v_lshl_add_u64 v[238:239], v[176:177], 0, s[38:39]
	s_add_i32 s35, s34, s17
	s_mov_b32 s52, m0
	s_mov_b32 m0, s35
	s_nop 0
	global_load_lds_dwordx4 v[238:239], off
	s_mov_b32 m0, s52
	v_lshl_add_u64 v[238:239], v[174:175], 0, s[38:39]
	s_add_i32 s35, s33, s16
	s_mov_b32 s52, m0
	s_mov_b32 m0, s35
	s_nop 0
	global_load_lds_dwordx4 v[238:239], off
	s_mov_b32 m0, s52
	ds_read_b64_tr_b16 v[188:189], v187 offset:24576
	ds_read_b64_tr_b16 v[190:191], v187 offset:25088
	v_add_f32_e32 v88, v64, v65
	v_add_f32_e32 v88, v66, v88
	v_add_f32_e32 v88, v67, v88
	v_add_f32_e32 v88, v68, v88
	v_add_f32_e32 v88, v69, v88
	v_cvt_pk_bf16_f32 v140, v64, v65
	v_cvt_pk_bf16_f32 v141, v66, v67
	ds_read_b64_tr_b16 v[64:65], v187 offset:28672
	ds_read_b64_tr_b16 v[66:67], v187 offset:29184
	v_add_f32_e32 v84, v70, v88
	v_add_f32_e32 v84, v71, v84
	v_add_f32_e32 v84, v72, v84
	v_add_f32_e32 v128, v73, v84
	s_waitcnt lgkmcnt(10)
	v_mfma_f32_32x32x16_bf16 v[80:95], v[80:83], v[156:159], 0
	v_cvt_pk_bf16_f32 v142, v68, v69
	v_cvt_pk_bf16_f32 v143, v70, v71
	ds_read_b64_tr_b16 v[68:69], v187 offset:25600
	ds_read_b64_tr_b16 v[70:71], v187 offset:26112
	v_add_f32_e32 v128, v74, v128
	v_add_f32_e32 v128, v75, v128
	v_add_f32_e32 v128, v76, v128
	v_add_f32_e32 v128, v77, v128
	v_cvt_pk_bf16_f32 v136, v72, v73
	v_cvt_pk_bf16_f32 v137, v74, v75
	s_waitcnt lgkmcnt(11)
	v_mfma_f32_32x32x16_bf16 v[96:111], v[164:167], v[152:155], v[96:111]
	ds_read_b64_tr_b16 v[72:73], v187 offset:29696
	ds_read_b64_tr_b16 v[74:75], v187 offset:30208
	s_waitcnt lgkmcnt(12)
	v_mfma_f32_32x32x16_bf16 v[80:95], v[160:163], v[152:155], v[80:95]
	v_add_f32_e32 v128, v78, v128
	v_add_f32_e32 v128, v79, v128
	v_add_f32_e32 v128, v48, v128
	v_add_f32_e32 v128, v49, v128
	v_cvt_pk_bf16_f32 v138, v76, v77
	v_cvt_pk_bf16_f32 v139, v78, v79
	ds_read_b64_tr_b16 v[76:77], v187 offset:26624
	ds_read_b64_tr_b16 v[78:79], v187 offset:27136
	v_add_f32_e32 v128, v50, v128
	v_add_f32_e32 v128, v51, v128
	v_add_f32_e32 v128, v52, v128
	v_add_f32_e32 v128, v53, v128
	v_cvt_pk_bf16_f32 v132, v48, v49
	v_cvt_pk_bf16_f32 v133, v50, v51
	s_waitcnt lgkmcnt(13)
	v_mfma_f32_32x32x16_bf16 v[96:111], v[124:127], v[148:151], v[96:111]
	ds_read_b64_tr_b16 v[48:49], v187 offset:30720
	ds_read_b64_tr_b16 v[50:51], v187 offset:31232
	s_waitcnt lgkmcnt(14)
	v_mfma_f32_32x32x16_bf16 v[80:95], v[120:123], v[148:151], v[80:95]
	v_add_f32_e32 v124, v54, v128
	v_add_f32_e32 v124, v55, v124
	v_add_f32_e32 v124, v56, v124
	v_add_f32_e32 v124, v57, v124
	v_cvt_pk_bf16_f32 v134, v52, v53
	v_cvt_pk_bf16_f32 v135, v54, v55
	ds_read_b64_tr_b16 v[52:53], v187 offset:27648
	ds_read_b64_tr_b16 v[54:55], v187 offset:28160
	v_add_f32_e32 v120, v58, v124
	v_add_f32_e32 v120, v59, v120
	v_add_f32_e32 v120, v60, v120
	v_add_f32_e32 v120, v61, v120
	v_cvt_pk_bf16_f32 v128, v56, v57
	v_cvt_pk_bf16_f32 v129, v58, v59
	s_waitcnt lgkmcnt(14)
	v_mfma_f32_32x32x16_bf16 v[96:111], v[116:119], v[144:147], v[96:111]
	ds_read_b64_tr_b16 v[56:57], v187 offset:31744
	ds_read_b64_tr_b16 v[58:59], v187 offset:32256
	v_mfma_f32_32x32x16_bf16 v[80:95], v[112:115], v[144:147], v[80:95]
	v_add_f32_e32 v116, v62, v120
	v_add_f32_e32 v116, v63, v116
	v_add_f32_e32 v116, 0, v116
	v_cvt_pk_bf16_f32 v130, v60, v61
	v_cvt_pk_bf16_f32 v131, v62, v63
	v_add_f32_e32 v202, v186, v116
	s_waitcnt lgkmcnt(14)
	v_mfma_f32_32x32x16_bf16 v[16:31], v[140:143], v[188:191], v[16:31]
	v_exp_f32_e32 v96, v96
	v_exp_f32_e32 v97, v97
	v_exp_f32_e32 v98, v98
	v_exp_f32_e32 v99, v99
	s_waitcnt lgkmcnt(12)
	v_mfma_f32_32x32x16_bf16 v[32:47], v[140:143], v[64:67], v[32:47]
	v_exp_f32_e32 v100, v100
	v_exp_f32_e32 v101, v101
	v_exp_f32_e32 v102, v102
	v_exp_f32_e32 v103, v103
	v_add_u32_e32 v242, s33, v234
	v_add_u32_e32 v243, s33, v235
	v_add_u32_e32 v244, s33, v236
	v_add_u32_e32 v245, s33, v237
	ds_read_b128 v[60:63], v242
	ds_read_b128 v[112:115], v242 offset:4096
	s_waitcnt lgkmcnt(12)
	v_mfma_f32_32x32x16_bf16 v[16:31], v[136:139], v[68:71], v[16:31]
	v_exp_f32_e32 v104, v104
	v_exp_f32_e32 v105, v105
	v_exp_f32_e32 v106, v106
	v_exp_f32_e32 v107, v107
	ds_read_b128 v[116:119], v243
	ds_read_b128 v[120:123], v243 offset:4096
	s_waitcnt lgkmcnt(12)
	v_mfma_f32_32x32x16_bf16 v[32:47], v[136:139], v[72:75], v[32:47]
	v_exp_f32_e32 v108, v108
	v_exp_f32_e32 v109, v109
	v_exp_f32_e32 v110, v110
	v_exp_f32_e32 v111, v111
	ds_read_b128 v[124:127], v244
	ds_read_b128 v[160:163], v244 offset:4096
	s_waitcnt lgkmcnt(12)
	v_mfma_f32_32x32x16_bf16 v[16:31], v[132:135], v[76:79], v[16:31]
	v_exp_f32_e32 v80, v80
	v_exp_f32_e32 v81, v81
	v_exp_f32_e32 v82, v82
	v_exp_f32_e32 v83, v83
	ds_read_b128 v[164:167], v245
	ds_read_b128 v[186:189], v245 offset:4096
	s_waitcnt lgkmcnt(12)
	v_mfma_f32_32x32x16_bf16 v[32:47], v[132:135], v[48:51], v[32:47]
	v_exp_f32_e32 v84, v84
	v_exp_f32_e32 v85, v85
	v_exp_f32_e32 v86, v86
	v_exp_f32_e32 v87, v87
	s_waitcnt lgkmcnt(10)
	v_mfma_f32_32x32x16_bf16 v[16:31], v[128:131], v[52:55], v[16:31]
	v_exp_f32_e32 v88, v88
	v_exp_f32_e32 v89, v89
	v_exp_f32_e32 v90, v90
	v_exp_f32_e32 v91, v91
	s_waitcnt lgkmcnt(8)
	v_mfma_f32_32x32x16_bf16 v[32:47], v[128:131], v[56:59], v[32:47]
	v_exp_f32_e32 v92, v92
	v_exp_f32_e32 v93, v93
	v_exp_f32_e32 v94, v94
	v_exp_f32_e32 v95, v95
	s_waitcnt vmcnt(2) lgkmcnt(0)
	s_barrier
; #define WAIT_BAR(N) asm volatile("s_waitcnt vmcnt(" #N ") lgkmcnt(0)\n\ts_barrier":::"memory")
;   #define RESC() do{ if(!NOMAX&&resc){ asm volatile("s_waitcnt lgkmcnt(0)":::"memory"); \
;       _Pragma("unroll") for(int d_=0;d_<2*VM;++d_) _Pragma("unroll") for(int r=0;r<16;++r)o[d_][r]*=wsf[crow(r,hi)]; } }while(0)
;   #define ROT() do{sl_prev=sl_cur;sl_cur=sl_next;sl_next=(sl_next==(NSLOT-1)*SLOTB)?0:sl_next+SLOTB;}while(0)
; template<int THRL,int VM,bool NOMAX> __device__ __forceinline__ void attn_unit(const bf16*Qb,const bf16*__restrict__ Kh,const bf16*__restrict__ Vh,bf16*Ob,const int NT,const int sp,float*wscr,char*shm){
;     ...
;   int t=1;
;   for(;t+5<NT;t+=2){
;     STEP(pB0,pB1,pA0,pA1,t,true,true,true);     if constexpr(VM==2){WAIT_BAR(3);}else{WAIT_BAR(2);} RESC(); ROT();
;     STEP(pA0,pA1,pB0,pB1,t+1,true,true,true);   if constexpr(VM==2){WAIT_BAR(3);}else{WAIT_BAR(2);} RESC(); ROT();
;   }
	v_mfma_f32_32x32x16_bf16 v[64:79], v[60:63], v[156:159], 0
	s_add_i32 s35, s33, 0x2000
	s_cmpk_lg_i32 s33, 0x4000
	s_cselect_b32 s35, s35, 0
	v_add_u32_e32 v203, s34, v168
	s_add_i32 s34, s33, s17
	s_mov_b32 s52, m0
	s_mov_b32 m0, s34
	s_nop 0
	global_load_lds_dwordx4 v[176:177], off
	s_mov_b32 m0, s52
	s_add_i32 s34, s35, s16
	s_mov_b32 s52, m0
	s_mov_b32 m0, s34
	s_nop 0
	global_load_lds_dwordx4 v[174:175], off
	s_mov_b32 m0, s52
	ds_read_b64_tr_b16 v[190:191], v203 offset:24576
	ds_read_b64_tr_b16 v[192:193], v203 offset:25088
	v_add_f32_e32 v48, v96, v97
	v_add_f32_e32 v48, v98, v48
	v_add_f32_e32 v48, v99, v48
	v_add_f32_e32 v48, v100, v48
	v_add_f32_e32 v48, v101, v48
	v_cvt_pk_bf16_f32 v140, v96, v97
	v_cvt_pk_bf16_f32 v141, v98, v99
	ds_read_b64_tr_b16 v[96:97], v203 offset:28672
	ds_read_b64_tr_b16 v[98:99], v203 offset:29184
	v_add_f32_e32 v48, v102, v48
	v_add_f32_e32 v48, v103, v48
	v_add_f32_e32 v48, v104, v48
	v_add_f32_e32 v128, v105, v48
	s_waitcnt lgkmcnt(10)
	v_mfma_f32_32x32x16_bf16 v[48:63], v[112:115], v[156:159], 0
	v_cvt_pk_bf16_f32 v142, v100, v101
	v_cvt_pk_bf16_f32 v143, v102, v103
	ds_read_b64_tr_b16 v[100:101], v203 offset:25600
	ds_read_b64_tr_b16 v[102:103], v203 offset:26112
	s_waitcnt lgkmcnt(11)
	v_mfma_f32_32x32x16_bf16 v[64:79], v[116:119], v[152:155], v[64:79]
	v_add_f32_e32 v112, v106, v128
	v_add_f32_e32 v112, v107, v112
	v_add_f32_e32 v112, v108, v112
	v_add_f32_e32 v112, v109, v112
	v_cvt_pk_bf16_f32 v136, v104, v105
	v_cvt_pk_bf16_f32 v137, v106, v107
	ds_read_b64_tr_b16 v[104:105], v203 offset:29696
	ds_read_b64_tr_b16 v[106:107], v203 offset:30208
	s_waitcnt lgkmcnt(12)
	v_mfma_f32_32x32x16_bf16 v[48:63], v[120:123], v[152:155], v[48:63]
	v_add_f32_e32 v112, v110, v112
	v_add_f32_e32 v112, v111, v112
	v_add_f32_e32 v112, v80, v112
	v_add_f32_e32 v112, v81, v112
	v_cvt_pk_bf16_f32 v138, v108, v109
	v_cvt_pk_bf16_f32 v139, v110, v111
	ds_read_b64_tr_b16 v[108:109], v203 offset:26624
	ds_read_b64_tr_b16 v[110:111], v203 offset:27136
	s_waitcnt lgkmcnt(13)
	v_mfma_f32_32x32x16_bf16 v[64:79], v[124:127], v[148:151], v[64:79]
	v_add_f32_e32 v112, v82, v112
	v_add_f32_e32 v112, v83, v112
	v_add_f32_e32 v112, v84, v112
	v_add_f32_e32 v112, v85, v112
	v_cvt_pk_bf16_f32 v132, v80, v81
	v_cvt_pk_bf16_f32 v133, v82, v83
	ds_read_b64_tr_b16 v[194:195], v203 offset:30720
	ds_read_b64_tr_b16 v[196:197], v203 offset:31232
	s_waitcnt lgkmcnt(14)
	v_mfma_f32_32x32x16_bf16 v[48:63], v[160:163], v[148:151], v[48:63]
	v_add_f32_e32 v80, v86, v112
	v_add_f32_e32 v80, v87, v80
	v_add_f32_e32 v80, v88, v80
	v_add_f32_e32 v80, v89, v80
	v_cvt_pk_bf16_f32 v134, v84, v85
	v_cvt_pk_bf16_f32 v135, v86, v87
	ds_read_b64_tr_b16 v[198:199], v203 offset:27648
	ds_read_b64_tr_b16 v[200:201], v203 offset:28160
	s_waitcnt lgkmcnt(14)
	v_mfma_f32_32x32x16_bf16 v[64:79], v[164:167], v[144:147], v[64:79]
	v_add_f32_e32 v80, v90, v80
	v_add_f32_e32 v80, v91, v80
	v_add_f32_e32 v80, v92, v80
	v_add_f32_e32 v80, v93, v80
	v_cvt_pk_bf16_f32 v128, v88, v89
	v_cvt_pk_bf16_f32 v129, v90, v91
	ds_read_b64_tr_b16 v[88:89], v203 offset:31744
	ds_read_b64_tr_b16 v[90:91], v203 offset:32256
	v_mfma_f32_32x32x16_bf16 v[48:63], v[186:189], v[144:147], v[48:63]
	v_add_f32_e32 v80, v94, v80
	v_add_f32_e32 v80, v95, v80
	v_add_f32_e32 v80, 0, v80
	v_cvt_pk_bf16_f32 v130, v92, v93
	v_cvt_pk_bf16_f32 v131, v94, v95
	v_add_f32_e32 v186, v202, v80
	s_waitcnt lgkmcnt(14)
	v_mfma_f32_32x32x16_bf16 v[16:31], v[140:143], v[190:193], v[16:31]
	v_exp_f32_e32 v64, v64
	v_exp_f32_e32 v65, v65
	v_exp_f32_e32 v66, v66
	v_exp_f32_e32 v67, v67
	s_waitcnt lgkmcnt(12)
	v_mfma_f32_32x32x16_bf16 v[32:47], v[140:143], v[96:99], v[32:47]
	v_exp_f32_e32 v68, v68
	v_exp_f32_e32 v69, v69
	v_exp_f32_e32 v70, v70
	v_exp_f32_e32 v71, v71
	v_add_u32_e32 v242, s35, v234
	v_add_u32_e32 v243, s35, v235
	v_add_u32_e32 v244, s35, v236
	v_add_u32_e32 v245, s35, v237
	ds_read_b128 v[84:87], v242
	ds_read_b128 v[80:83], v242 offset:4096
	s_waitcnt lgkmcnt(12)
	v_mfma_f32_32x32x16_bf16 v[16:31], v[136:139], v[100:103], v[16:31]
	v_exp_f32_e32 v72, v72
	v_exp_f32_e32 v73, v73
	v_exp_f32_e32 v74, v74
	v_exp_f32_e32 v75, v75
	ds_read_b128 v[164:167], v243
	ds_read_b128 v[160:163], v243 offset:4096
	s_waitcnt lgkmcnt(12)
	v_mfma_f32_32x32x16_bf16 v[32:47], v[136:139], v[104:107], v[32:47]
	v_exp_f32_e32 v76, v76
	v_exp_f32_e32 v77, v77
	v_exp_f32_e32 v78, v78
	v_exp_f32_e32 v79, v79
	ds_read_b128 v[124:127], v244
	ds_read_b128 v[120:123], v244 offset:4096
	s_waitcnt lgkmcnt(12)
	v_mfma_f32_32x32x16_bf16 v[16:31], v[132:135], v[108:111], v[16:31]
	v_exp_f32_e32 v48, v48
	v_exp_f32_e32 v49, v49
	v_exp_f32_e32 v50, v50
	v_exp_f32_e32 v51, v51
	ds_read_b128 v[116:119], v245
	ds_read_b128 v[112:115], v245 offset:4096
	s_waitcnt lgkmcnt(12)
	v_mfma_f32_32x32x16_bf16 v[32:47], v[132:135], v[194:197], v[32:47]
	v_exp_f32_e32 v52, v52
	v_exp_f32_e32 v53, v53
	v_exp_f32_e32 v54, v54
	v_exp_f32_e32 v55, v55
	s_waitcnt lgkmcnt(10)
	v_mfma_f32_32x32x16_bf16 v[16:31], v[128:131], v[198:201], v[16:31]
	v_exp_f32_e32 v56, v56
	v_exp_f32_e32 v57, v57
	v_exp_f32_e32 v58, v58
	v_exp_f32_e32 v59, v59
	s_waitcnt lgkmcnt(8)
	v_mfma_f32_32x32x16_bf16 v[32:47], v[128:131], v[88:91], v[32:47]
	v_exp_f32_e32 v60, v60
	v_exp_f32_e32 v61, v61
	v_exp_f32_e32 v62, v62
	v_exp_f32_e32 v63, v63
	s_add_i32 s53, s35, 0x2000
	s_waitcnt vmcnt(2) lgkmcnt(0)
	s_barrier
	s_cmpk_lg_i32 s35, 0x4000
	s_mov_b32 s52, s33
	s_cselect_b32 s33, s53, 0
	s_add_i32 s29, s29, 2
	v_lshl_add_u64 v[174:175], v[174:175], 0, s[8:9]
	v_lshl_add_u64 v[176:177], v[176:177], 0, s[8:9]
	s_mov_b32 s34, s35
	s_cmp_lt_u32 s29, 57
	s_cbranch_scc1 .LBB0_891
; #define WAIT_BAR(N) asm volatile("s_waitcnt vmcnt(" #N ") lgkmcnt(0)\n\ts_barrier":::"memory")
;   #define RESC() do{ if(!NOMAX&&resc){ asm volatile("s_waitcnt lgkmcnt(0)":::"memory"); \
;       _Pragma("unroll") for(int d_=0;d_<2*VM;++d_) _Pragma("unroll") for(int r=0;r<16;++r)o[d_][r]*=wsf[crow(r,hi)]; } }while(0)
;   #define ROT() do{sl_prev=sl_cur;sl_cur=sl_next;sl_next=(sl_next==(NSLOT-1)*SLOTB)?0:sl_next+SLOTB;}while(0)
;   #define ENDW(tt) do{ if((tt)+3<NT){ if constexpr(VM==2){WAIT_BAR(3);}else{WAIT_BAR(2);} } else if((tt)+2<NT){ if constexpr(VM==2){WAIT_BAR(2);}else{WAIT_BAR(1);} } else {WAIT_BAR(0);} }while(0)
; template<int THRL,int VM,bool NOMAX> __device__ __forceinline__ void attn_unit(const bf16*Qb,const bf16*__restrict__ Kh,const bf16*__restrict__ Vh,bf16*Ob,const int NT,const int sp,float*wscr,char*shm){
;     ...
;   int t=1;
;   for(;t+5<NT;t+=2){
;     STEP(pB0,pB1,pA0,pA1,t,true,true,true);     if constexpr(VM==2){WAIT_BAR(3);}else{WAIT_BAR(2);} RESC(); ROT();
;     STEP(pA0,pA1,pB0,pB1,t+1,true,true,true);   if constexpr(VM==2){WAIT_BAR(3);}else{WAIT_BAR(2);} RESC(); ROT();
;   }
;     ...
;   for(;t+1<NT;t+=2){
;     STEP(pB0,pB1,pA0,pA1,t,(t+3<NT),(t+1<NT),(t+1<NT));       ENDW(t);   RESC(); ROT();
;     STEP(pA0,pA1,pB0,pB1,t+1,(t+4<NT),(t+2<NT),(t+2<NT));     ENDW(t+1); RESC(); ROT();
;   }
	s_and_b32 s19, s19, 0x3fffffc0
	s_lshl_b32 s19, s19, 2
	s_add_i32 s19, s19, 0
	s_cmp_lg_u32 0, -1
	s_cselect_b32 s29, 0, 0
	s_add_i32 s33, s29, 0x6000
	v_add_u32_e32 v88, s33, v184
	v_add3_u32 v174, v88, v183, v185
	ds_read_b64_tr_b16 v[188:189], v168 offset:32768
	ds_read_b64_tr_b16 v[190:191], v168 offset:33280
	v_add_f32_e32 v88, v64, v65
	v_add_f32_e32 v88, v66, v88
	v_add_f32_e32 v88, v67, v88
	v_add_f32_e32 v88, v68, v88
	v_add_f32_e32 v88, v69, v88
	v_cvt_pk_bf16_f32 v140, v64, v65
	v_cvt_pk_bf16_f32 v141, v66, v67
	s_waitcnt lgkmcnt(9)
	v_mfma_f32_32x32x16_bf16 v[96:111], v[84:87], v[156:159], 0
	ds_read_b64_tr_b16 v[64:65], v168 offset:36864
	ds_read_b64_tr_b16 v[66:67], v168 offset:37376
	v_add_f32_e32 v84, v70, v88
	v_add_f32_e32 v84, v71, v84
	v_add_f32_e32 v84, v72, v84
	v_add_f32_e32 v128, v73, v84
	v_cvt_pk_bf16_f32 v142, v68, v69
	v_cvt_pk_bf16_f32 v143, v70, v71
	s_waitcnt lgkmcnt(10)
	v_mfma_f32_32x32x16_bf16 v[80:95], v[80:83], v[156:159], 0
	ds_read_b64_tr_b16 v[68:69], v168 offset:33792
	ds_read_b64_tr_b16 v[70:71], v168 offset:34304
	v_add_f32_e32 v128, v74, v128
	v_add_f32_e32 v128, v75, v128
	v_add_f32_e32 v128, v76, v128
	v_add_f32_e32 v128, v77, v128
	v_cvt_pk_bf16_f32 v136, v72, v73
	v_cvt_pk_bf16_f32 v137, v74, v75
	s_waitcnt lgkmcnt(11)
	v_mfma_f32_32x32x16_bf16 v[96:111], v[164:167], v[152:155], v[96:111]
	ds_read_b64_tr_b16 v[72:73], v168 offset:37888
	ds_read_b64_tr_b16 v[74:75], v168 offset:38400
	v_add_f32_e32 v128, v78, v128
	v_add_f32_e32 v128, v79, v128
	v_add_f32_e32 v128, v48, v128
	v_add_f32_e32 v128, v49, v128
	v_cvt_pk_bf16_f32 v138, v76, v77
	v_cvt_pk_bf16_f32 v139, v78, v79
	s_waitcnt lgkmcnt(12)
	v_mfma_f32_32x32x16_bf16 v[80:95], v[160:163], v[152:155], v[80:95]
	ds_read_b64_tr_b16 v[76:77], v168 offset:34816
	ds_read_b64_tr_b16 v[78:79], v168 offset:35328
	v_add_f32_e32 v128, v50, v128
	v_add_f32_e32 v128, v51, v128
	v_add_f32_e32 v128, v52, v128
	v_add_f32_e32 v128, v53, v128
	v_cvt_pk_bf16_f32 v132, v48, v49
	v_cvt_pk_bf16_f32 v133, v50, v51
	s_waitcnt lgkmcnt(13)
	v_mfma_f32_32x32x16_bf16 v[96:111], v[124:127], v[148:151], v[96:111]
	ds_read_b64_tr_b16 v[48:49], v168 offset:38912
	ds_read_b64_tr_b16 v[50:51], v168 offset:39424
	v_add_f32_e32 v124, v54, v128
	v_add_f32_e32 v124, v55, v124
	v_add_f32_e32 v124, v56, v124
	v_add_f32_e32 v124, v57, v124
	v_cvt_pk_bf16_f32 v134, v52, v53
	v_cvt_pk_bf16_f32 v135, v54, v55
	s_waitcnt lgkmcnt(14)
	v_mfma_f32_32x32x16_bf16 v[80:95], v[120:123], v[148:151], v[80:95]
	ds_read_b64_tr_b16 v[52:53], v168 offset:35840
	ds_read_b64_tr_b16 v[54:55], v168 offset:36352
	v_add_f32_e32 v120, v58, v124
	v_add_f32_e32 v120, v59, v120
	v_add_f32_e32 v120, v60, v120
	v_add_f32_e32 v120, v61, v120
	v_cvt_pk_bf16_f32 v128, v56, v57
	v_cvt_pk_bf16_f32 v129, v58, v59
	s_waitcnt lgkmcnt(14)
	v_mfma_f32_32x32x16_bf16 v[96:111], v[116:119], v[144:147], v[96:111]
	ds_read_b64_tr_b16 v[56:57], v168 offset:39936
	ds_read_b64_tr_b16 v[58:59], v168 offset:40448
	v_add_f32_e32 v116, v62, v120
	v_add_f32_e32 v116, v63, v116
	v_add_f32_e32 v116, 0, v116
	v_cvt_pk_bf16_f32 v130, v60, v61
	v_cvt_pk_bf16_f32 v131, v62, v63
	v_mfma_f32_32x32x16_bf16 v[80:95], v[112:115], v[144:147], v[80:95]
	s_add_i32 s28, s29, s28
	v_lshl_add_u64 v[60:61], v[172:173], 0, s[40:41]
	s_add_i32 s29, s28, 0x4000
	s_mov_b32 s33, m0
	s_mov_b32 m0, s29
	s_nop 0
	global_load_lds_dwordx4 v[60:61], off
	s_mov_b32 m0, s33
	v_lshl_add_u64 v[60:61], v[170:171], 0, s[42:43]
	s_mov_b32 s29, m0
	s_mov_b32 m0, s16
	s_nop 0
	global_load_lds_dwordx4 v[60:61], off
	s_mov_b32 m0, s29
	v_add_f32_e32 v175, v186, v116
	s_waitcnt lgkmcnt(14)
	v_mfma_f32_32x32x16_bf16 v[16:31], v[140:143], v[188:191], v[16:31]
	v_exp_f32_e32 v96, v96
	v_exp_f32_e32 v97, v97
	v_exp_f32_e32 v98, v98
	v_exp_f32_e32 v99, v99
	s_waitcnt lgkmcnt(12)
	v_mfma_f32_32x32x16_bf16 v[32:47], v[140:143], v[64:67], v[32:47]
	v_exp_f32_e32 v100, v100
	v_exp_f32_e32 v101, v101
	v_exp_f32_e32 v102, v102
	v_exp_f32_e32 v103, v103
	ds_read_b128 v[60:63], v234
	ds_read_b128 v[64:67], v234 offset:4096
	s_waitcnt lgkmcnt(12)
	v_mfma_f32_32x32x16_bf16 v[16:31], v[136:139], v[68:71], v[16:31]
	v_exp_f32_e32 v104, v104
	v_exp_f32_e32 v105, v105
	v_exp_f32_e32 v106, v106
	v_exp_f32_e32 v107, v107
	ds_read_b128 v[68:71], v235
	ds_read_b128 v[160:163], v235 offset:4096
	s_waitcnt lgkmcnt(12)
	v_mfma_f32_32x32x16_bf16 v[32:47], v[136:139], v[72:75], v[32:47]
	v_exp_f32_e32 v108, v108
	v_exp_f32_e32 v109, v109
	v_exp_f32_e32 v110, v110
	v_exp_f32_e32 v111, v111
	ds_read_b128 v[72:75], v236
	ds_read_b128 v[164:167], v236 offset:4096
	s_waitcnt lgkmcnt(12)
	v_mfma_f32_32x32x16_bf16 v[16:31], v[132:135], v[76:79], v[16:31]
	v_exp_f32_e32 v80, v80
	v_exp_f32_e32 v81, v81
	v_exp_f32_e32 v82, v82
	v_exp_f32_e32 v83, v83
	ds_read_b128 v[76:79], v237
	ds_read_b128 v[184:187], v237 offset:4096
	s_waitcnt lgkmcnt(12)
	v_mfma_f32_32x32x16_bf16 v[32:47], v[132:135], v[48:51], v[32:47]
	v_exp_f32_e32 v84, v84
	v_exp_f32_e32 v85, v85
	v_exp_f32_e32 v86, v86
	v_exp_f32_e32 v87, v87
	s_waitcnt lgkmcnt(10)
	v_mfma_f32_32x32x16_bf16 v[16:31], v[128:131], v[52:55], v[16:31]
	v_exp_f32_e32 v88, v88
	v_exp_f32_e32 v89, v89
	v_exp_f32_e32 v90, v90
	v_exp_f32_e32 v91, v91
	s_waitcnt lgkmcnt(8)
	v_mfma_f32_32x32x16_bf16 v[32:47], v[128:131], v[56:59], v[32:47]
	v_exp_f32_e32 v92, v92
	v_exp_f32_e32 v93, v93
	v_exp_f32_e32 v94, v94
	v_exp_f32_e32 v95, v95
	s_waitcnt vmcnt(2) lgkmcnt(0)
	s_barrier
; #define WAIT_BAR(N) asm volatile("s_waitcnt vmcnt(" #N ") lgkmcnt(0)\n\ts_barrier":::"memory")
;   #define RESC() do{ if(!NOMAX&&resc){ asm volatile("s_waitcnt lgkmcnt(0)":::"memory"); \
;       _Pragma("unroll") for(int d_=0;d_<2*VM;++d_) _Pragma("unroll") for(int r=0;r<16;++r)o[d_][r]*=wsf[crow(r,hi)]; } }while(0)
;   #define ROT() do{sl_prev=sl_cur;sl_cur=sl_next;sl_next=(sl_next==(NSLOT-1)*SLOTB)?0:sl_next+SLOTB;}while(0)
;   #define ENDW(tt) do{ if((tt)+3<NT){ if constexpr(VM==2){WAIT_BAR(3);}else{WAIT_BAR(2);} } else if((tt)+2<NT){ if constexpr(VM==2){WAIT_BAR(2);}else{WAIT_BAR(1);} } else {WAIT_BAR(0);} }while(0)
; template<int THRL,int VM,bool NOMAX> __device__ __forceinline__ void attn_unit(const bf16*Qb,const bf16*__restrict__ Kh,const bf16*__restrict__ Vh,bf16*Ob,const int NT,const int sp,float*wscr,char*shm){
;     ...
;   int t=1;
;   for(;t+5<NT;t+=2){
;     STEP(pB0,pB1,pA0,pA1,t,true,true,true);     if constexpr(VM==2){WAIT_BAR(3);}else{WAIT_BAR(2);} RESC(); ROT();
;     STEP(pA0,pA1,pB0,pB1,t+1,true,true,true);   if constexpr(VM==2){WAIT_BAR(3);}else{WAIT_BAR(2);} RESC(); ROT();
;   }
;     ...
;   for(;t+1<NT;t+=2){
;     STEP(pB0,pB1,pA0,pA1,t,(t+3<NT),(t+1<NT),(t+1<NT));       ENDW(t);   RESC(); ROT();
;     STEP(pA0,pA1,pB0,pB1,t+1,(t+4<NT),(t+2<NT),(t+2<NT));     ENDW(t+1); RESC(); ROT();
;   }
	ds_read_b64_tr_b16 v[188:189], v168 offset:40960
	ds_read_b64_tr_b16 v[190:191], v168 offset:41472
	v_add_f32_e32 v48, v96, v97
	v_add_f32_e32 v48, v98, v48
	v_add_f32_e32 v48, v99, v48
	v_add_f32_e32 v48, v100, v48
	v_add_f32_e32 v48, v101, v48
	v_cvt_pk_bf16_f32 v140, v96, v97
	v_cvt_pk_bf16_f32 v141, v98, v99
	s_waitcnt lgkmcnt(9)
	v_mfma_f32_32x32x16_bf16 v[112:127], v[60:63], v[156:159], 0
	ds_read_b64_tr_b16 v[96:97], v168 offset:45056
	ds_read_b64_tr_b16 v[98:99], v168 offset:45568
	v_add_f32_e32 v48, v102, v48
	v_add_f32_e32 v48, v103, v48
	v_add_f32_e32 v48, v104, v48
	v_add_f32_e32 v128, v105, v48
	s_waitcnt lgkmcnt(10)
	v_mfma_f32_32x32x16_bf16 v[48:63], v[64:67], v[156:159], 0
	v_cvt_pk_bf16_f32 v142, v100, v101
	v_cvt_pk_bf16_f32 v143, v102, v103
	ds_read_b64_tr_b16 v[64:65], v168 offset:41984
	ds_read_b64_tr_b16 v[66:67], v168 offset:42496
	v_add_f32_e32 v100, v106, v128
	v_add_f32_e32 v100, v107, v100
	v_add_f32_e32 v100, v108, v100
	v_add_f32_e32 v100, v109, v100
	v_cvt_pk_bf16_f32 v136, v104, v105
	v_cvt_pk_bf16_f32 v137, v106, v107
	s_waitcnt lgkmcnt(11)
	v_mfma_f32_32x32x16_bf16 v[112:127], v[68:71], v[152:155], v[112:127]
	ds_read_b64_tr_b16 v[68:69], v168 offset:46080
	ds_read_b64_tr_b16 v[70:71], v168 offset:46592
	s_waitcnt lgkmcnt(12)
	v_mfma_f32_32x32x16_bf16 v[48:63], v[160:163], v[152:155], v[48:63]
	v_add_f32_e32 v100, v110, v100
	v_add_f32_e32 v100, v111, v100
	v_add_f32_e32 v100, v80, v100
	v_add_f32_e32 v104, v81, v100
	v_cvt_pk_bf16_f32 v138, v108, v109
	v_cvt_pk_bf16_f32 v139, v110, v111
	ds_read_b64_tr_b16 v[100:101], v168 offset:43008
	ds_read_b64_tr_b16 v[102:103], v168 offset:43520
	v_add_f32_e32 v104, v82, v104
	v_add_f32_e32 v104, v83, v104
	v_add_f32_e32 v104, v84, v104
	v_add_f32_e32 v104, v85, v104
	v_cvt_pk_bf16_f32 v132, v80, v81
	v_cvt_pk_bf16_f32 v133, v82, v83
	s_waitcnt lgkmcnt(13)
	v_mfma_f32_32x32x16_bf16 v[112:127], v[72:75], v[148:151], v[112:127]
	ds_read_b64_tr_b16 v[72:73], v168 offset:47104
	ds_read_b64_tr_b16 v[74:75], v168 offset:47616
	s_waitcnt lgkmcnt(14)
	v_mfma_f32_32x32x16_bf16 v[48:63], v[164:167], v[148:151], v[48:63]
	v_add_f32_e32 v80, v86, v104
	v_add_f32_e32 v80, v87, v80
	v_add_f32_e32 v80, v88, v80
	v_add_f32_e32 v104, v89, v80
	v_cvt_pk_bf16_f32 v134, v84, v85
	v_cvt_pk_bf16_f32 v135, v86, v87
	ds_read_b64_tr_b16 v[80:81], v168 offset:44032
	ds_read_b64_tr_b16 v[82:83], v168 offset:44544
	v_add_f32_e32 v84, v90, v104
	v_add_f32_e32 v84, v91, v84
	v_add_f32_e32 v84, v92, v84
	v_add_f32_e32 v84, v93, v84
	v_cvt_pk_bf16_f32 v128, v88, v89
	v_cvt_pk_bf16_f32 v129, v90, v91
	s_waitcnt lgkmcnt(14)
	v_mfma_f32_32x32x16_bf16 v[112:127], v[76:79], v[144:147], v[112:127]
	ds_read_b64_tr_b16 v[76:77], v168 offset:48128
	ds_read_b64_tr_b16 v[78:79], v168 offset:48640
	v_mfma_f32_32x32x16_bf16 v[48:63], v[184:187], v[144:147], v[48:63]
	v_add_f32_e32 v84, v94, v84
	v_add_f32_e32 v84, v95, v84
	v_add_f32_e32 v84, 0, v84
	v_cvt_pk_bf16_f32 v130, v92, v93
	v_cvt_pk_bf16_f32 v131, v94, v95
	s_nop 0
	v_add_f32_e32 v175, v175, v84
	v_lshl_add_u64 v[84:85], v[172:173], 0, s[44:45]
	s_mov_b32 s29, m0
	s_mov_b32 m0, s17
	s_nop 0
	global_load_lds_dwordx4 v[84:85], off
	s_mov_b32 m0, s29
	v_lshl_add_u64 v[84:85], v[170:171], 0, s[48:49]
	s_add_i32 s17, s28, 0x8000
	s_mov_b32 s29, m0
	s_mov_b32 m0, s17
	s_nop 0
	global_load_lds_dwordx4 v[84:85], off
	s_mov_b32 m0, s29
	s_waitcnt lgkmcnt(14)
	v_mfma_f32_32x32x16_bf16 v[16:31], v[140:143], v[188:191], v[16:31]
	v_exp_f32_e32 v112, v112
	v_exp_f32_e32 v113, v113
	v_exp_f32_e32 v114, v114
	v_exp_f32_e32 v115, v115
	s_waitcnt lgkmcnt(12)
	v_mfma_f32_32x32x16_bf16 v[32:47], v[140:143], v[96:99], v[32:47]
	v_exp_f32_e32 v116, v116
	v_exp_f32_e32 v117, v117
	v_exp_f32_e32 v118, v118
	v_exp_f32_e32 v119, v119
	ds_read_b128 v[84:87], v234 offset:8192
	ds_read_b128 v[96:99], v234 offset:12288
	s_waitcnt lgkmcnt(12)
	v_mfma_f32_32x32x16_bf16 v[16:31], v[136:139], v[64:67], v[16:31]
	v_exp_f32_e32 v120, v120
	v_exp_f32_e32 v121, v121
	v_exp_f32_e32 v122, v122
	v_exp_f32_e32 v123, v123
	ds_read_b128 v[104:107], v235 offset:8192
	ds_read_b128 v[108:111], v235 offset:12288
	s_waitcnt lgkmcnt(12)
	v_mfma_f32_32x32x16_bf16 v[32:47], v[136:139], v[68:71], v[32:47]
	v_exp_f32_e32 v124, v124
	v_exp_f32_e32 v125, v125
	v_exp_f32_e32 v126, v126
	v_exp_f32_e32 v127, v127
	ds_read_b128 v[160:163], v236 offset:8192
	ds_read_b128 v[164:167], v236 offset:12288
	s_waitcnt lgkmcnt(12)
	v_mfma_f32_32x32x16_bf16 v[16:31], v[132:135], v[100:103], v[16:31]
	v_exp_f32_e32 v48, v48
	v_exp_f32_e32 v49, v49
	v_exp_f32_e32 v50, v50
	v_exp_f32_e32 v51, v51
	ds_read_b128 v[100:103], v237 offset:8192
	ds_read_b128 v[184:187], v237 offset:12288
	s_waitcnt lgkmcnt(12)
	v_mfma_f32_32x32x16_bf16 v[32:47], v[132:135], v[72:75], v[32:47]
	v_exp_f32_e32 v52, v52
	v_exp_f32_e32 v53, v53
	v_exp_f32_e32 v54, v54
	v_exp_f32_e32 v55, v55
	s_waitcnt lgkmcnt(10)
	v_mfma_f32_32x32x16_bf16 v[16:31], v[128:131], v[80:83], v[16:31]
	v_exp_f32_e32 v56, v56
	v_exp_f32_e32 v57, v57
	v_exp_f32_e32 v58, v58
	v_exp_f32_e32 v59, v59
	s_waitcnt lgkmcnt(8)
	v_mfma_f32_32x32x16_bf16 v[32:47], v[128:131], v[76:79], v[32:47]
	v_exp_f32_e32 v60, v60
	v_exp_f32_e32 v61, v61
	v_exp_f32_e32 v62, v62
	v_exp_f32_e32 v63, v63
	s_waitcnt vmcnt(2) lgkmcnt(0)
	s_barrier
; #define WAIT_BAR(N) asm volatile("s_waitcnt vmcnt(" #N ") lgkmcnt(0)\n\ts_barrier":::"memory")
;   #define RESC() do{ if(!NOMAX&&resc){ asm volatile("s_waitcnt lgkmcnt(0)":::"memory"); \
;       _Pragma("unroll") for(int d_=0;d_<2*VM;++d_) _Pragma("unroll") for(int r=0;r<16;++r)o[d_][r]*=wsf[crow(r,hi)]; } }while(0)
;   #define ROT() do{sl_prev=sl_cur;sl_cur=sl_next;sl_next=(sl_next==(NSLOT-1)*SLOTB)?0:sl_next+SLOTB;}while(0)
;   #define ENDW(tt) do{ if((tt)+3<NT){ if constexpr(VM==2){WAIT_BAR(3);}else{WAIT_BAR(2);} } else if((tt)+2<NT){ if constexpr(VM==2){WAIT_BAR(2);}else{WAIT_BAR(1);} } else {WAIT_BAR(0);} }while(0)
; template<int THRL,int VM,bool NOMAX> __device__ __forceinline__ void attn_unit(const bf16*Qb,const bf16*__restrict__ Kh,const bf16*__restrict__ Vh,bf16*Ob,const int NT,const int sp,float*wscr,char*shm){
;     ...
;   int t=1;
;   for(;t+5<NT;t+=2){
;     STEP(pB0,pB1,pA0,pA1,t,true,true,true);     if constexpr(VM==2){WAIT_BAR(3);}else{WAIT_BAR(2);} RESC(); ROT();
;     STEP(pA0,pA1,pB0,pB1,t+1,true,true,true);   if constexpr(VM==2){WAIT_BAR(3);}else{WAIT_BAR(2);} RESC(); ROT();
;   }
;     ...
;   for(;t+1<NT;t+=2){
;     STEP(pB0,pB1,pA0,pA1,t,(t+3<NT),(t+1<NT),(t+1<NT));       ENDW(t);   RESC(); ROT();
;     STEP(pA0,pA1,pB0,pB1,t+1,(t+4<NT),(t+2<NT),(t+2<NT));     ENDW(t+1); RESC(); ROT();
;   }
	ds_read_b64_tr_b16 v[188:189], v168 offset:24576
	ds_read_b64_tr_b16 v[190:191], v168 offset:25088
	v_add_f32_e32 v64, v112, v113
	v_add_f32_e32 v64, v114, v64
	v_add_f32_e32 v64, v115, v64
	v_add_f32_e32 v64, v116, v64
	v_add_f32_e32 v64, v117, v64
	v_cvt_pk_bf16_f32 v140, v112, v113
	v_cvt_pk_bf16_f32 v141, v114, v115
	s_waitcnt lgkmcnt(9)
	v_mfma_f32_32x32x16_bf16 v[80:95], v[84:87], v[156:159], 0
	ds_read_b64_tr_b16 v[112:113], v168 offset:28672
	ds_read_b64_tr_b16 v[114:115], v168 offset:29184
	v_add_f32_e32 v64, v118, v64
	v_add_f32_e32 v64, v119, v64
	v_add_f32_e32 v64, v120, v64
	v_add_f32_e32 v128, v121, v64
	v_cvt_pk_bf16_f32 v142, v116, v117
	v_cvt_pk_bf16_f32 v143, v118, v119
	s_waitcnt lgkmcnt(10)
	v_mfma_f32_32x32x16_bf16 v[64:79], v[96:99], v[156:159], 0
	ds_read_b64_tr_b16 v[96:97], v168 offset:25600
	ds_read_b64_tr_b16 v[98:99], v168 offset:26112
	v_add_f32_e32 v116, v122, v128
	v_add_f32_e32 v116, v123, v116
	v_add_f32_e32 v116, v124, v116
	v_add_f32_e32 v116, v125, v116
	v_cvt_pk_bf16_f32 v136, v120, v121
	v_cvt_pk_bf16_f32 v137, v122, v123
	s_waitcnt lgkmcnt(11)
	v_mfma_f32_32x32x16_bf16 v[80:95], v[104:107], v[152:155], v[80:95]
	ds_read_b64_tr_b16 v[104:105], v168 offset:29696
	ds_read_b64_tr_b16 v[106:107], v168 offset:30208
	v_add_f32_e32 v116, v126, v116
	v_add_f32_e32 v116, v127, v116
	v_add_f32_e32 v116, v48, v116
	v_add_f32_e32 v116, v49, v116
	v_cvt_pk_bf16_f32 v138, v124, v125
	v_cvt_pk_bf16_f32 v139, v126, v127
	s_waitcnt lgkmcnt(12)
	v_mfma_f32_32x32x16_bf16 v[64:79], v[108:111], v[152:155], v[64:79]
	ds_read_b64_tr_b16 v[108:109], v168 offset:26624
	ds_read_b64_tr_b16 v[110:111], v168 offset:27136
	v_add_f32_e32 v116, v50, v116
	v_add_f32_e32 v116, v51, v116
	v_add_f32_e32 v116, v52, v116
	v_add_f32_e32 v116, v53, v116
	v_cvt_pk_bf16_f32 v132, v48, v49
	v_cvt_pk_bf16_f32 v133, v50, v51
	s_waitcnt lgkmcnt(13)
	v_mfma_f32_32x32x16_bf16 v[80:95], v[160:163], v[148:151], v[80:95]
	ds_read_b64_tr_b16 v[48:49], v168 offset:30720
	ds_read_b64_tr_b16 v[50:51], v168 offset:31232
	v_add_f32_e32 v116, v54, v116
	v_add_f32_e32 v116, v55, v116
	v_add_f32_e32 v116, v56, v116
	v_add_f32_e32 v116, v57, v116
	v_cvt_pk_bf16_f32 v134, v52, v53
	v_cvt_pk_bf16_f32 v135, v54, v55
	s_waitcnt lgkmcnt(14)
	v_mfma_f32_32x32x16_bf16 v[64:79], v[164:167], v[148:151], v[64:79]
	ds_read_b64_tr_b16 v[52:53], v168 offset:27648
	ds_read_b64_tr_b16 v[54:55], v168 offset:28160
	v_add_f32_e32 v116, v58, v116
	v_add_f32_e32 v116, v59, v116
	v_add_f32_e32 v116, v60, v116
	v_add_f32_e32 v116, v61, v116
	v_cvt_pk_bf16_f32 v128, v56, v57
	v_cvt_pk_bf16_f32 v129, v58, v59
	s_waitcnt lgkmcnt(14)
	v_mfma_f32_32x32x16_bf16 v[80:95], v[100:103], v[144:147], v[80:95]
	ds_read_b64_tr_b16 v[56:57], v168 offset:31744
	ds_read_b64_tr_b16 v[58:59], v168 offset:32256
	v_add_f32_e32 v100, v62, v116
	v_add_f32_e32 v100, v63, v100
	v_add_f32_e32 v100, 0, v100
	v_cvt_pk_bf16_f32 v130, v60, v61
	v_cvt_pk_bf16_f32 v131, v62, v63
	v_mfma_f32_32x32x16_bf16 v[64:79], v[184:187], v[144:147], v[64:79]
	v_lshl_add_u64 v[60:61], v[170:171], 0, s[40:41]
	s_add_i32 s28, s28, 0xa000
	s_mov_b32 s17, m0
	s_mov_b32 m0, s28
	s_nop 0
	global_load_lds_dwordx4 v[60:61], off
	s_mov_b32 m0, s17
	v_add_f32_e32 v172, v175, v100
	s_waitcnt lgkmcnt(14)
	v_mfma_f32_32x32x16_bf16 v[16:31], v[140:143], v[188:191], v[16:31]
	v_exp_f32_e32 v80, v80
	v_exp_f32_e32 v81, v81
	v_exp_f32_e32 v82, v82
	v_exp_f32_e32 v83, v83
	s_waitcnt lgkmcnt(12)
	v_mfma_f32_32x32x16_bf16 v[32:47], v[140:143], v[112:115], v[32:47]
	v_exp_f32_e32 v84, v84
	v_exp_f32_e32 v85, v85
	v_exp_f32_e32 v86, v86
	v_exp_f32_e32 v87, v87
	ds_read_b128 v[60:63], v234 offset:16384
	ds_read_b128 v[112:115], v234 offset:20480
	s_waitcnt lgkmcnt(12)
	v_mfma_f32_32x32x16_bf16 v[16:31], v[136:139], v[96:99], v[16:31]
	v_exp_f32_e32 v88, v88
	v_exp_f32_e32 v89, v89
	v_exp_f32_e32 v90, v90
	v_exp_f32_e32 v91, v91
	ds_read_b128 v[116:119], v235 offset:16384
	ds_read_b128 v[120:123], v235 offset:20480
	s_waitcnt lgkmcnt(12)
	v_mfma_f32_32x32x16_bf16 v[32:47], v[136:139], v[104:107], v[32:47]
	v_exp_f32_e32 v92, v92
	v_exp_f32_e32 v93, v93
	v_exp_f32_e32 v94, v94
	v_exp_f32_e32 v95, v95
	ds_read_b128 v[124:127], v236 offset:16384
	ds_read_b128 v[160:163], v236 offset:20480
	s_waitcnt lgkmcnt(12)
	v_mfma_f32_32x32x16_bf16 v[16:31], v[132:135], v[108:111], v[16:31]
	v_exp_f32_e32 v64, v64
	v_exp_f32_e32 v65, v65
	v_exp_f32_e32 v66, v66
	v_exp_f32_e32 v67, v67
	ds_read_b128 v[164:167], v237 offset:16384
	ds_read_b128 v[184:187], v237 offset:20480
	s_waitcnt lgkmcnt(12)
	v_mfma_f32_32x32x16_bf16 v[32:47], v[132:135], v[48:51], v[32:47]
	v_exp_f32_e32 v68, v68
	v_exp_f32_e32 v69, v69
	v_exp_f32_e32 v70, v70
	v_exp_f32_e32 v71, v71
	s_waitcnt lgkmcnt(10)
	v_mfma_f32_32x32x16_bf16 v[16:31], v[128:131], v[52:55], v[16:31]
	v_exp_f32_e32 v72, v72
	v_exp_f32_e32 v73, v73
	v_exp_f32_e32 v74, v74
	v_exp_f32_e32 v75, v75
	s_waitcnt lgkmcnt(8)
	v_mfma_f32_32x32x16_bf16 v[32:47], v[128:131], v[56:59], v[32:47]
	v_exp_f32_e32 v76, v76
	v_exp_f32_e32 v77, v77
	v_exp_f32_e32 v78, v78
	v_exp_f32_e32 v79, v79
	s_waitcnt vmcnt(1) lgkmcnt(0)
	s_barrier
; #define WAIT_BAR(N) asm volatile("s_waitcnt vmcnt(" #N ") lgkmcnt(0)\n\ts_barrier":::"memory")
;   #define RESC() do{ if(!NOMAX&&resc){ asm volatile("s_waitcnt lgkmcnt(0)":::"memory"); \
;       _Pragma("unroll") for(int d_=0;d_<2*VM;++d_) _Pragma("unroll") for(int r=0;r<16;++r)o[d_][r]*=wsf[crow(r,hi)]; } }while(0)
;   #define ROT() do{sl_prev=sl_cur;sl_cur=sl_next;sl_next=(sl_next==(NSLOT-1)*SLOTB)?0:sl_next+SLOTB;}while(0)
;   #define ENDW(tt) do{ if((tt)+3<NT){ if constexpr(VM==2){WAIT_BAR(3);}else{WAIT_BAR(2);} } else if((tt)+2<NT){ if constexpr(VM==2){WAIT_BAR(2);}else{WAIT_BAR(1);} } else {WAIT_BAR(0);} }while(0)
; template<int THRL,int VM,bool NOMAX> __device__ __forceinline__ void attn_unit(const bf16*Qb,const bf16*__restrict__ Kh,const bf16*__restrict__ Vh,bf16*Ob,const int NT,const int sp,float*wscr,char*shm){
;     ...
;   int t=1;
;   for(;t+5<NT;t+=2){
;     STEP(pB0,pB1,pA0,pA1,t,true,true,true);     if constexpr(VM==2){WAIT_BAR(3);}else{WAIT_BAR(2);} RESC(); ROT();
;     STEP(pA0,pA1,pB0,pB1,t+1,true,true,true);   if constexpr(VM==2){WAIT_BAR(3);}else{WAIT_BAR(2);} RESC(); ROT();
;   }
;     ...
;   for(;t+1<NT;t+=2){
;     STEP(pB0,pB1,pA0,pA1,t,(t+3<NT),(t+1<NT),(t+1<NT));       ENDW(t);   RESC(); ROT();
;     STEP(pA0,pA1,pB0,pB1,t+1,(t+4<NT),(t+2<NT),(t+2<NT));     ENDW(t+1); RESC(); ROT();
;   }
	ds_read_b64_tr_b16 v[188:189], v168 offset:32768
	ds_read_b64_tr_b16 v[190:191], v168 offset:33280
	v_add_f32_e32 v48, v80, v81
	v_add_f32_e32 v48, v82, v48
	v_add_f32_e32 v48, v83, v48
	v_add_f32_e32 v48, v84, v48
	v_add_f32_e32 v48, v85, v48
	v_cvt_pk_bf16_f32 v140, v80, v81
	v_cvt_pk_bf16_f32 v141, v82, v83
	s_waitcnt lgkmcnt(9)
	v_mfma_f32_32x32x16_bf16 v[96:111], v[60:63], v[156:159], 0
	ds_read_b64_tr_b16 v[80:81], v168 offset:36864
	ds_read_b64_tr_b16 v[82:83], v168 offset:37376
	v_add_f32_e32 v48, v86, v48
	v_add_f32_e32 v48, v87, v48
	v_add_f32_e32 v48, v88, v48
	v_add_f32_e32 v128, v89, v48
	s_waitcnt lgkmcnt(10)
	v_mfma_f32_32x32x16_bf16 v[48:63], v[112:115], v[156:159], 0
	v_cvt_pk_bf16_f32 v142, v84, v85
	v_cvt_pk_bf16_f32 v143, v86, v87
	ds_read_b64_tr_b16 v[84:85], v168 offset:33792
	ds_read_b64_tr_b16 v[86:87], v168 offset:34304
	v_add_f32_e32 v112, v90, v128
	v_add_f32_e32 v112, v91, v112
	v_add_f32_e32 v112, v92, v112
	v_add_f32_e32 v112, v93, v112
	v_cvt_pk_bf16_f32 v136, v88, v89
	v_cvt_pk_bf16_f32 v137, v90, v91
	s_waitcnt lgkmcnt(11)
	v_mfma_f32_32x32x16_bf16 v[96:111], v[116:119], v[152:155], v[96:111]
	ds_read_b64_tr_b16 v[88:89], v168 offset:37888
	ds_read_b64_tr_b16 v[90:91], v168 offset:38400
	s_waitcnt lgkmcnt(12)
	v_mfma_f32_32x32x16_bf16 v[48:63], v[120:123], v[152:155], v[48:63]
	v_add_f32_e32 v112, v94, v112
	v_add_f32_e32 v112, v95, v112
	v_add_f32_e32 v112, v64, v112
	v_add_f32_e32 v112, v65, v112
	v_cvt_pk_bf16_f32 v138, v92, v93
	v_cvt_pk_bf16_f32 v139, v94, v95
	ds_read_b64_tr_b16 v[92:93], v168 offset:34816
	ds_read_b64_tr_b16 v[94:95], v168 offset:35328
	v_add_f32_e32 v112, v66, v112
	v_add_f32_e32 v112, v67, v112
	v_add_f32_e32 v112, v68, v112
	v_add_f32_e32 v112, v69, v112
	v_cvt_pk_bf16_f32 v132, v64, v65
	v_cvt_pk_bf16_f32 v133, v66, v67
	s_waitcnt lgkmcnt(13)
	v_mfma_f32_32x32x16_bf16 v[96:111], v[124:127], v[148:151], v[96:111]
	ds_read_b64_tr_b16 v[64:65], v168 offset:38912
	ds_read_b64_tr_b16 v[66:67], v168 offset:39424
	s_waitcnt lgkmcnt(14)
	v_mfma_f32_32x32x16_bf16 v[48:63], v[160:163], v[148:151], v[48:63]
	v_add_f32_e32 v112, v70, v112
	v_add_f32_e32 v112, v71, v112
	v_add_f32_e32 v112, v72, v112
	v_add_f32_e32 v112, v73, v112
	v_cvt_pk_bf16_f32 v134, v68, v69
	v_cvt_pk_bf16_f32 v135, v70, v71
	ds_read_b64_tr_b16 v[68:69], v168 offset:35840
	ds_read_b64_tr_b16 v[70:71], v168 offset:36352
	v_add_f32_e32 v112, v74, v112
	v_add_f32_e32 v112, v75, v112
	v_add_f32_e32 v112, v76, v112
	v_add_f32_e32 v112, v77, v112
	v_cvt_pk_bf16_f32 v128, v72, v73
	v_cvt_pk_bf16_f32 v129, v74, v75
	s_waitcnt lgkmcnt(14)
	v_mfma_f32_32x32x16_bf16 v[96:111], v[164:167], v[144:147], v[96:111]
	ds_read_b64_tr_b16 v[72:73], v168 offset:39936
	ds_read_b64_tr_b16 v[74:75], v168 offset:40448
	v_mfma_f32_32x32x16_bf16 v[48:63], v[184:187], v[144:147], v[48:63]
	v_add_f32_e32 v112, v78, v112
	v_add_f32_e32 v112, v79, v112
	v_add_f32_e32 v112, 0, v112
	v_cvt_pk_bf16_f32 v130, v76, v77
	v_cvt_pk_bf16_f32 v131, v78, v79
	v_lshl_add_u64 v[76:77], v[170:171], 0, s[44:45]
	s_mov_b32 s17, m0
	s_mov_b32 m0, s16
	s_nop 0
	global_load_lds_dwordx4 v[76:77], off
	s_mov_b32 m0, s17
	v_add_f32_e32 v120, v172, v112
	s_waitcnt lgkmcnt(14)
	v_mfma_f32_32x32x16_bf16 v[16:31], v[140:143], v[188:191], v[16:31]
	v_exp_f32_e32 v96, v96
	v_exp_f32_e32 v97, v97
	v_exp_f32_e32 v98, v98
	v_exp_f32_e32 v99, v99
	s_waitcnt lgkmcnt(12)
	v_mfma_f32_32x32x16_bf16 v[32:47], v[140:143], v[80:83], v[32:47]
	v_exp_f32_e32 v100, v100
	v_exp_f32_e32 v101, v101
	v_exp_f32_e32 v102, v102
	v_exp_f32_e32 v103, v103
	ds_read_b128 v[76:79], v234
	ds_read_b128 v[80:83], v234 offset:4096
	s_waitcnt lgkmcnt(12)
	v_mfma_f32_32x32x16_bf16 v[16:31], v[136:139], v[84:87], v[16:31]
	v_exp_f32_e32 v104, v104
	v_exp_f32_e32 v105, v105
	v_exp_f32_e32 v106, v106
	v_exp_f32_e32 v107, v107
	ds_read_b128 v[122:125], v235
	ds_read_b128 v[160:163], v235 offset:4096
	s_waitcnt lgkmcnt(12)
	v_mfma_f32_32x32x16_bf16 v[32:47], v[136:139], v[88:91], v[32:47]
	v_exp_f32_e32 v108, v108
	v_exp_f32_e32 v109, v109
	v_exp_f32_e32 v110, v110
	v_exp_f32_e32 v111, v111
	ds_read_b128 v[164:167], v236
	ds_read_b128 v[170:173], v236 offset:4096
	s_waitcnt lgkmcnt(12)
	v_mfma_f32_32x32x16_bf16 v[16:31], v[132:135], v[92:95], v[16:31]
	v_exp_f32_e32 v48, v48
	v_exp_f32_e32 v49, v49
	v_exp_f32_e32 v50, v50
	v_exp_f32_e32 v51, v51
	ds_read_b128 v[184:187], v237
	ds_read_b128 v[188:191], v237 offset:4096
	s_waitcnt lgkmcnt(12)
	v_mfma_f32_32x32x16_bf16 v[32:47], v[132:135], v[64:67], v[32:47]
	v_exp_f32_e32 v52, v52
	v_exp_f32_e32 v53, v53
	v_exp_f32_e32 v54, v54
	v_exp_f32_e32 v55, v55
	s_waitcnt lgkmcnt(10)
	v_mfma_f32_32x32x16_bf16 v[16:31], v[128:131], v[68:71], v[16:31]
	v_exp_f32_e32 v56, v56
	v_exp_f32_e32 v57, v57
	v_exp_f32_e32 v58, v58
	v_exp_f32_e32 v59, v59
	s_waitcnt lgkmcnt(8)
	v_mfma_f32_32x32x16_bf16 v[32:47], v[128:131], v[72:75], v[32:47]
	v_exp_f32_e32 v60, v60
	v_exp_f32_e32 v61, v61
	v_exp_f32_e32 v62, v62
	v_exp_f32_e32 v63, v63
	s_waitcnt vmcnt(0) lgkmcnt(0)
	s_barrier
;   #define RESC() do{ if(!NOMAX&&resc){ asm volatile("s_waitcnt lgkmcnt(0)":::"memory"); \
;       _Pragma("unroll") for(int d_=0;d_<2*VM;++d_) _Pragma("unroll") for(int r=0;r<16;++r)o[d_][r]*=wsf[crow(r,hi)]; } }while(0)
; template<int THRL,int VM,bool NOMAX> __device__ __forceinline__ void attn_unit(const bf16*Qb,const bf16*__restrict__ Kh,const bf16*__restrict__ Vh,bf16*Ob,const int NT,const int sp,float*wscr,char*shm){
;     ...
;   STEP(pB0,pB1,pA0,pA1,NT-1,false,false,false); RESC();
	ds_read_b64_tr_b16 v[112:113], v168 offset:40960
	ds_read_b64_tr_b16 v[114:115], v168 offset:41472
	v_add_f32_e32 v64, v96, v97
	v_add_f32_e32 v64, v98, v64
	v_add_f32_e32 v64, v99, v64
	v_add_f32_e32 v64, v100, v64
	v_add_f32_e32 v84, v101, v64
	v_cvt_pk_bf16_f32 v140, v96, v97
	v_cvt_pk_bf16_f32 v141, v98, v99
	s_waitcnt lgkmcnt(9)
	v_mfma_f32_32x32x16_bf16 v[64:79], v[76:79], v[156:159], 0
	ds_read_b64_tr_b16 v[96:97], v168 offset:45056
	ds_read_b64_tr_b16 v[98:99], v168 offset:45568
	v_add_f32_e32 v84, v102, v84
	v_add_f32_e32 v84, v103, v84
	v_add_f32_e32 v84, v104, v84
	v_add_f32_e32 v121, v105, v84
	v_cvt_pk_bf16_f32 v142, v100, v101
	v_cvt_pk_bf16_f32 v143, v102, v103
	s_waitcnt lgkmcnt(10)
	v_mfma_f32_32x32x16_bf16 v[80:95], v[80:83], v[156:159], 0
	ds_read_b64_tr_b16 v[116:117], v168 offset:41984
	ds_read_b64_tr_b16 v[118:119], v168 offset:42496
	v_add_f32_e32 v100, v106, v121
	v_add_f32_e32 v100, v107, v100
	v_add_f32_e32 v100, v108, v100
	v_add_f32_e32 v121, v109, v100
	v_cvt_pk_bf16_f32 v136, v104, v105
	v_cvt_pk_bf16_f32 v137, v106, v107
	s_waitcnt lgkmcnt(11)
	v_mfma_f32_32x32x16_bf16 v[64:79], v[122:125], v[152:155], v[64:79]
	ds_read_b64_tr_b16 v[100:101], v168 offset:46080
	ds_read_b64_tr_b16 v[102:103], v168 offset:46592
	v_add_f32_e32 v104, v110, v121
	v_add_f32_e32 v104, v111, v104
	v_add_f32_e32 v104, v48, v104
	v_add_f32_e32 v121, v49, v104
	v_cvt_pk_bf16_f32 v138, v108, v109
	v_cvt_pk_bf16_f32 v139, v110, v111
	s_waitcnt lgkmcnt(12)
	v_mfma_f32_32x32x16_bf16 v[80:95], v[160:163], v[152:155], v[80:95]
	ds_read_b64_tr_b16 v[104:105], v168 offset:43008
	ds_read_b64_tr_b16 v[106:107], v168 offset:43520
	v_add_f32_e32 v108, v50, v121
	v_add_f32_e32 v108, v51, v108
	v_add_f32_e32 v108, v52, v108
	v_add_f32_e32 v108, v53, v108
	v_cvt_pk_bf16_f32 v132, v48, v49
	v_cvt_pk_bf16_f32 v133, v50, v51
	s_waitcnt lgkmcnt(13)
	v_mfma_f32_32x32x16_bf16 v[64:79], v[164:167], v[148:151], v[64:79]
	ds_read_b64_tr_b16 v[48:49], v168 offset:47104
	ds_read_b64_tr_b16 v[50:51], v168 offset:47616
	v_add_f32_e32 v108, v54, v108
	v_add_f32_e32 v108, v55, v108
	v_add_f32_e32 v108, v56, v108
	v_add_f32_e32 v121, v57, v108
	v_cvt_pk_bf16_f32 v134, v52, v53
	v_cvt_pk_bf16_f32 v135, v54, v55
	s_waitcnt lgkmcnt(14)
	v_mfma_f32_32x32x16_bf16 v[80:95], v[170:173], v[148:151], v[80:95]
	ds_read_b64_tr_b16 v[108:109], v168 offset:44032
	ds_read_b64_tr_b16 v[110:111], v168 offset:44544
	v_add_f32_e32 v52, v58, v121
	v_add_f32_e32 v52, v59, v52
	v_add_f32_e32 v52, v60, v52
	v_add_f32_e32 v121, v61, v52
	v_cvt_pk_bf16_f32 v128, v56, v57
	v_cvt_pk_bf16_f32 v129, v58, v59
	s_waitcnt lgkmcnt(14)
	v_mfma_f32_32x32x16_bf16 v[64:79], v[184:187], v[144:147], v[64:79]
	ds_read_b64_tr_b16 v[52:53], v168 offset:48128
	ds_read_b64_tr_b16 v[54:55], v168 offset:48640
	v_add_f32_e32 v56, v62, v121
	v_add_f32_e32 v56, v63, v56
	v_add_f32_e32 v56, 0, v56
	v_cvt_pk_bf16_f32 v130, v60, v61
	v_cvt_pk_bf16_f32 v131, v62, v63
	v_mfma_f32_32x32x16_bf16 v[80:95], v[188:191], v[144:147], v[80:95]
	s_nop 3
	v_exp_f32_e32 v64, v64
	v_exp_f32_e32 v65, v65
	v_exp_f32_e32 v66, v66
	v_exp_f32_e32 v67, v67
	s_nop 0
	v_exp_f32_e32 v68, v68
	v_exp_f32_e32 v69, v69
	v_exp_f32_e32 v70, v70
	v_exp_f32_e32 v71, v71
	s_nop 0
	v_exp_f32_e32 v72, v72
	v_exp_f32_e32 v73, v73
	v_exp_f32_e32 v74, v74
	v_exp_f32_e32 v75, v75
	s_nop 0
	v_exp_f32_e32 v76, v76
	v_exp_f32_e32 v77, v77
	v_exp_f32_e32 v78, v78
	v_exp_f32_e32 v79, v79
	v_exp_f32_e32 v80, v80
	v_exp_f32_e32 v81, v81
	v_exp_f32_e32 v82, v82
	v_exp_f32_e32 v83, v83
	s_nop 0
	v_exp_f32_e32 v84, v84
	v_exp_f32_e32 v85, v85
	v_exp_f32_e32 v86, v86
	v_exp_f32_e32 v87, v87
	s_nop 0
	v_exp_f32_e32 v88, v88
	v_exp_f32_e32 v89, v89
	v_exp_f32_e32 v90, v90
	v_exp_f32_e32 v91, v91
	s_nop 0
	v_exp_f32_e32 v92, v92
	v_exp_f32_e32 v93, v93
	v_exp_f32_e32 v94, v94
	v_exp_f32_e32 v95, v95
	s_waitcnt lgkmcnt(14)
; #define SBAR() __builtin_amdgcn_sched_barrier(0)
;   #define PKW(P,B) cvtpk_s(P[B],P[B+1])
; __device__ __forceinline__ void pv(f32x16*o,int vb,bf16x8 pa0,bf16x8 pa1,bf16x8 pa2,bf16x8 pa3){
;   #pragma unroll
;   for(int d0=0;d0<2;++d0){s16x4 lo[4],hi[4];
;     #pragma unroll
;     for(int ks=0;ks<4;++ks){
;       asm volatile("ds_read_b64_tr_b16 %0,%1 offset:%c2":"=&v"(lo[ks]):"v"(vb),"i"(d0*4096+ks*1024):"memory");
;       asm volatile("ds_read_b64_tr_b16 %0,%1 offset:%c2":"=&v"(hi[ks]):"v"(vb),"i"(d0*4096+ks*1024+512):"memory");}
;     asm volatile("s_waitcnt lgkmcnt(0)":::"memory");SBAR();
;     ...
;     o[d0]=__builtin_amdgcn_mfma_f32_32x32x16_bf16(pa0,PK(0),o[d0],0,0,0);
;     o[d0]=__builtin_amdgcn_mfma_f32_32x32x16_bf16(pa1,PK(1),o[d0],0,0,0);
;     o[d0]=__builtin_amdgcn_mfma_f32_32x32x16_bf16(pa2,PK(2),o[d0],0,0,0);
;     o[d0]=__builtin_amdgcn_mfma_f32_32x32x16_bf16(pa3,PK(3),o[d0],0,0,0);
;     ...
;   }
; }
; template<int THRL,int VM,bool NOMAX> __device__ __forceinline__ void attn_unit(const bf16*Qb,const bf16*__restrict__ Kh,const bf16*__restrict__ Vh,bf16*Ob,const int NT,const int sp,float*wscr,char*shm){
;     ...
;   { float sacc=pB0[0]+pB0[1]; _Pragma("unroll") for(int r=2;r<16;++r)sacc+=pB0[r]; _Pragma("unroll") for(int r=0;r<16;++r)sacc+=pB1[r]; l_reg+=sacc;
;     pw0=(u32x4){PKW(pB0,0),PKW(pB0,2),PKW(pB0,4),PKW(pB0,6)};pw1=(u32x4){PKW(pB0,8),PKW(pB0,10),PKW(pB0,12),PKW(pB0,14)};pw2=(u32x4){PKW(pB1,0),PKW(pB1,2),PKW(pB1,4),PKW(pB1,6)};pw3=(u32x4){PKW(pB1,8),PKW(pB1,10),PKW(pB1,12),PKW(pB1,14)};
;     SBAR(); pv(o,vb0+VM*sl_cur,PAF(0),PAF(1),PAF(2),PAF(3)); if constexpr(VM==2) pv(o+2,vb0+VM*sl_cur+8192,PAF(0),PAF(1),PAF(2),PAF(3)); }
;     ...
;   {auto rr=__builtin_amdgcn_permlane32_swap(__float_as_uint(l_reg),__float_as_uint(l_reg),false,false);l_reg=__uint_as_float(rr[0])+__uint_as_float(rr[1]);}
;   if(hi==0)wsf[32+r32]=l_reg;asm volatile("s_waitcnt lgkmcnt(0)":::"memory");
	v_mfma_f32_32x32x16_bf16 v[16:31], v[140:143], v[112:115], v[16:31]
	v_add_f32_e32 v57, v64, v65
	v_add_f32_e32 v57, v66, v57
	v_add_f32_e32 v57, v67, v57
	v_add_f32_e32 v57, v68, v57
	v_add_f32_e32 v57, v69, v57
	v_add_f32_e32 v57, v70, v57
	v_add_f32_e32 v57, v71, v57
	s_waitcnt lgkmcnt(12)
	v_mfma_f32_32x32x16_bf16 v[32:47], v[140:143], v[96:99], v[32:47]
	v_add_f32_e32 v57, v72, v57
	v_add_f32_e32 v57, v73, v57
	v_add_f32_e32 v57, v74, v57
	v_add_f32_e32 v57, v75, v57
	v_add_f32_e32 v57, v76, v57
	v_add_f32_e32 v57, v77, v57
	v_add_f32_e32 v57, v78, v57
	s_waitcnt lgkmcnt(10)
	v_mfma_f32_32x32x16_bf16 v[16:31], v[136:139], v[116:119], v[16:31]
	v_add_f32_e32 v57, v79, v57
	v_add_f32_e32 v57, v80, v57
	v_add_f32_e32 v57, v81, v57
	v_add_f32_e32 v57, v82, v57
	v_add_f32_e32 v57, v83, v57
	v_add_f32_e32 v57, v84, v57
	v_add_f32_e32 v57, v85, v57
	s_waitcnt lgkmcnt(8)
	v_mfma_f32_32x32x16_bf16 v[32:47], v[136:139], v[100:103], v[32:47]
	v_add_f32_e32 v57, v86, v57
	v_add_f32_e32 v57, v87, v57
	v_add_f32_e32 v57, v88, v57
	v_add_f32_e32 v57, v89, v57
	v_add_f32_e32 v57, v90, v57
	v_add_f32_e32 v57, v91, v57
	v_add_f32_e32 v57, v92, v57
	s_waitcnt lgkmcnt(6)
	v_mfma_f32_32x32x16_bf16 v[16:31], v[132:135], v[104:107], v[16:31]
	v_add_f32_e32 v57, v93, v57
	v_add_f32_e32 v57, v94, v57
	v_add_f32_e32 v57, v95, v57
	v_add_f32_e32 v56, v120, v56
	v_add_f32_e32 v56, v56, v57
	v_cvt_pk_bf16_f32 v58, v64, v65
	v_cvt_pk_bf16_f32 v59, v66, v67
	s_waitcnt lgkmcnt(4)
	v_mfma_f32_32x32x16_bf16 v[32:47], v[132:135], v[48:51], v[32:47]
	v_cvt_pk_bf16_f32 v48, v80, v81
	v_cvt_pk_bf16_f32 v60, v68, v69
	v_cvt_pk_bf16_f32 v61, v70, v71
	v_cvt_pk_bf16_f32 v62, v72, v73
	v_cvt_pk_bf16_f32 v63, v74, v75
	v_cvt_pk_bf16_f32 v64, v76, v77
	v_cvt_pk_bf16_f32 v65, v78, v79
	s_waitcnt lgkmcnt(2)
	v_mfma_f32_32x32x16_bf16 v[16:31], v[128:131], v[108:111], v[16:31]
	v_cvt_pk_bf16_f32 v49, v82, v83
	v_cvt_pk_bf16_f32 v50, v84, v85
	v_cvt_pk_bf16_f32 v51, v86, v87
	v_cvt_pk_bf16_f32 v66, v88, v89
	v_cvt_pk_bf16_f32 v67, v90, v91
	v_cvt_pk_bf16_f32 v68, v92, v93
	v_cvt_pk_bf16_f32 v69, v94, v95
	s_waitcnt lgkmcnt(0)
	v_mfma_f32_32x32x16_bf16 v[32:47], v[128:131], v[52:55], v[32:47]
	ds_read_b64_tr_b16 v[52:53],v174 offset:0
	ds_read_b64_tr_b16 v[54:55],v174 offset:512
	ds_read_b64_tr_b16 v[70:71],v174 offset:1024
	ds_read_b64_tr_b16 v[72:73],v174 offset:1536
	ds_read_b64_tr_b16 v[74:75],v174 offset:2048
	ds_read_b64_tr_b16 v[76:77],v174 offset:2560
	ds_read_b64_tr_b16 v[78:79],v174 offset:3072
	ds_read_b64_tr_b16 v[80:81],v174 offset:3584
	s_waitcnt lgkmcnt(0)
	s_nop 0
	v_mfma_f32_32x32x16_bf16 v[16:31], v[58:61], v[52:55], v[16:31]
	ds_read_b64_tr_b16 v[52:53],v174 offset:4096
	ds_read_b64_tr_b16 v[54:55],v174 offset:4608
	v_mfma_f32_32x32x16_bf16 v[16:31], v[62:65], v[70:73], v[16:31]
	ds_read_b64_tr_b16 v[70:71],v174 offset:5120
	ds_read_b64_tr_b16 v[72:73],v174 offset:5632
	v_mfma_f32_32x32x16_bf16 v[16:31], v[48:51], v[74:77], v[16:31]
	ds_read_b64_tr_b16 v[74:75],v174 offset:6144
	ds_read_b64_tr_b16 v[76:77],v174 offset:6656
	ds_read_b64_tr_b16 v[82:83],v174 offset:7168
	ds_read_b64_tr_b16 v[84:85],v174 offset:7680
	s_waitcnt lgkmcnt(0)
	v_mfma_f32_32x32x16_bf16 v[16:31], v[66:69], v[78:81], v[16:31]
	v_mfma_f32_32x32x16_bf16 v[32:47], v[58:61], v[52:55], v[32:47]
	v_cmp_gt_u32_e32 vcc, 32, v178
	v_mfma_f32_32x32x16_bf16 v[32:47], v[62:65], v[70:73], v[32:47]
	v_mfma_f32_32x32x16_bf16 v[32:47], v[48:51], v[74:77], v[32:47]
	v_mov_b32_e32 v48, v56
	s_nop 1
	v_permlane32_swap_b32_e32 v56, v48
	v_mfma_f32_32x32x16_bf16 v[32:47], v[66:69], v[82:85], v[32:47]
	s_and_saveexec_b64 s[16:17], vcc
	s_cbranch_execz .LBB0_887
	v_add_f32_e32 v48, v56, v48
	v_lshl_add_u32 v49, v180, 2, s19
	ds_write_b32 v49, v48 offset:49280
	s_branch .LBB0_887
